# GEMM K-loops: next iteration's first two A-fragment ds_reads issued right behind the barrier into spare registers (overlap with the trailing MFMAs)
# speedup vs baseline: 1.0054x; 1.0054x over previous
; #define TIDX opaque_tid()
; template <class Epi>
; DEVI void gemm_tile256b(const bf16_t* __restrict__ A, int lda, const bf16_t* __restrict__ Bt, int K,
;                         int m0, int n0, char* smem, Epi epi) {
;   const int tid = TIDX, lane = tid & 63, wave = tid >> 6;
;   const int wm = wave >> 1, wn = wave & 1, l15 = lane & 15, quad = lane >> 4;
;   f32x4 acc[8][4];
; #pragma unroll
;   for (int i = 0; i < 8; ++i)
; #pragma unroll
;     for (int j = 0; j < 4; ++j) acc[i][j] = f32x4{0.f, 0.f, 0.f, 0.f};
;   const int lrow = tid >> 3, lkc = tid & 7;
;   const bf16_t* ag = A + (size_t)(m0 + lrow) * lda + lkc * 8;
;   const int kb32 = K >> 5;
;   const bf16_t* bp = Bt + ((size_t)((n0 + wn * 64) >> 4) * kb32) * 512 + lane * 8;
;   u32x4 ra[8];
;   bf16x8 b0[4], b1[4];
;   const int lds_w = lrow * 128 + ((lkc ^ (lrow & 7)) << 4);
;   const int nk = K >> 6;
;   const int sw = (quad ^ (l15 & 7)) << 4;
;   const int a_rd = (wm * 128 + l15) * 128 + sw;
; #pragma unroll
;   for (int i = 0; i < 8; ++i) ra[i] = *(const u32x4*)(ag + (size_t)(i * 32) * lda);
; #pragma unroll
;   for (int i = 0; i < 4; ++i) b0[i] = *(const bf16x8*)(bp + ((size_t)i * kb32) * 512);
; #pragma unroll
;   for (int i = 0; i < 8; ++i) *(u32x4*)(smem + lds_w + i * 4096) = ra[i];
;   __syncthreads();
;   for (int kt = 0; kt < nk; ++kt) {
.LBB0_49:
	v_mov_b32_e32 v168, v206
	s_lshl_b32 s0, s24, 8
	v_readlane_b32 s24, v247, 26
	v_ashrrev_i32_e32 v8, 3, v168
	v_add_u32_e32 v2, s0, v8
	v_ashrrev_i32_e32 v3, 31, v2
	v_lshlrev_b64 v[50:51], 11, v[2:3]
	v_readlane_b32 s25, v247, 27
	v_lshlrev_b32_e32 v0, 4, v168
	v_and_b32_e32 v0, 0x70, v0
	v_lshl_add_u64 v[2:3], s[24:25], 0, v[50:51]
	v_lshl_add_u64 v[2:3], v[2:3], 0, v[0:1]
	v_add_co_u32_e32 v4, vcc, s54, v2
	global_load_dwordx4 v[18:21], v[2:3], off
	s_nop 0
	v_addc_co_u32_e32 v5, vcc, 0, v3, vcc
	v_add_co_u32_e32 v6, vcc, s53, v2
	s_lshl_b32 s13, s18, 7
	s_nop 0
	v_addc_co_u32_e32 v7, vcc, 0, v3, vcc
	global_load_dwordx4 v[22:25], v[4:5], off
	global_load_dwordx4 v[26:29], v[6:7], off
	v_add_co_u32_e32 v4, vcc, s52, v2
	v_and_or_b32 v170, v168, 64, s13
	s_nop 0
	v_addc_co_u32_e32 v5, vcc, 0, v3, vcc
	v_add_co_u32_e32 v6, vcc, s56, v2
	v_and_b32_e32 v0, 63, v168
	s_nop 0
	v_addc_co_u32_e32 v7, vcc, 0, v3, vcc
	global_load_dwordx4 v[30:33], v[4:5], off
	global_load_dwordx4 v[34:37], v[6:7], off
	v_add_co_u32_e32 v4, vcc, s57, v2
	v_lshlrev_b32_e32 v0, 4, v0
	s_nop 0
	v_addc_co_u32_e32 v5, vcc, 0, v3, vcc
	v_add_co_u32_e32 v6, vcc, s3, v2
	s_mov_b32 s1, 0x8000
	s_nop 0
	v_addc_co_u32_e32 v7, vcc, 0, v3, vcc
	v_add_co_u32_e32 v2, vcc, s19, v2
	global_load_dwordx4 v[38:41], v[4:5], off
	global_load_dwordx4 v[42:45], v[6:7], off
	v_addc_co_u32_e32 v3, vcc, 0, v3, vcc
	global_load_dwordx4 v[46:49], v[2:3], off
	v_lshlrev_b32_e32 v3, 7, v168
	v_ashrrev_i32_e32 v2, 4, v170
	v_and_b32_e32 v57, 0xffffc780, v3
	v_ashrrev_i32_e32 v3, 31, v2
	v_lshlrev_b64 v[52:53], 15, v[2:3]
	v_lshl_add_u64 v[2:3], s[10:11], 0, v[52:53]
	v_xor_b32_e32 v5, v8, v168
	v_lshl_add_u64 v[162:163], v[2:3], 0, v[0:1]
	v_lshlrev_b32_e32 v5, 4, v5
	v_add_co_u32_e32 v2, vcc, s1, v162
	v_lshlrev_b32_e32 v4, 7, v8
	v_and_b32_e32 v5, 0x70, v5
	v_addc_co_u32_e32 v3, vcc, 0, v163, vcc
	v_add3_u32 v173, 32, v5, v4
	v_add_co_u32_e32 v4, vcc, s54, v162
	v_bfe_u32 v169, v168, 4, 2
	s_nop 0
	v_addc_co_u32_e32 v5, vcc, 0, v163, vcc
	s_mov_b32 s13, 0x18000
	v_bitop3_b32 v6, v169, v168, 7 bitop3:0x78
	v_add_co_u32_e32 v54, vcc, s13, v162
	v_lshlrev_b32_e32 v58, 4, v6
	global_load_dwordx4 v[10:13], v[162:163], off
	v_addc_co_u32_e32 v55, vcc, 0, v163, vcc
	global_load_dwordx4 v[14:17], v[2:3], off
	global_load_dwordx4 v[6:9], v[4:5], off
	s_nop 0
	global_load_dwordx4 v[2:5], v[54:55], off
	v_and_b32_e32 v56, 7, v168
	v_or_b32_e32 v52, v52, v0
	v_lshl_or_b32 v50, v56, 4, v50
	v_mov_b32_e32 v126, 0
	v_or_b32_e32 v172, v58, v57
	v_bitop3_b32 v171, v58, 64, v57 bitop3:0x36
	v_lshl_add_u64 v[164:165], s[84:85], 0, v[52:53]
	v_lshl_add_u64 v[166:167], s[84:85], 0, v[50:51]
	v_mov_b32_e32 v127, v126
	v_mov_b32_e32 v128, v126
	v_mov_b32_e32 v129, v126
	v_mov_b32_e32 v130, v126
	v_mov_b32_e32 v131, v126
	v_mov_b32_e32 v132, v126
	v_mov_b32_e32 v133, v126
	v_mov_b32_e32 v134, v126
	v_mov_b32_e32 v135, v126
	s_waitcnt vmcnt(11)
	ds_write_b128 v173, v[18:21]
	s_waitcnt vmcnt(10)
	ds_write_b128 v173, v[22:25] offset:4096
	s_waitcnt vmcnt(9)
	ds_write_b128 v173, v[26:29] offset:8192
	s_waitcnt vmcnt(8)
	ds_write_b128 v173, v[30:33] offset:12288
	s_waitcnt vmcnt(7)
	ds_write_b128 v173, v[34:37] offset:16384
	s_waitcnt vmcnt(6)
	ds_write_b128 v173, v[38:41] offset:20480
	s_waitcnt vmcnt(5)
	ds_write_b128 v173, v[42:45] offset:24576
	s_waitcnt vmcnt(4)
	ds_write_b128 v173, v[46:49] offset:28672
	v_mov_b32_e32 v136, v126
	v_mov_b32_e32 v137, v126
	v_mov_b32_e32 v138, v126
	v_mov_b32_e32 v139, v126
	v_mov_b32_e32 v140, v126
	v_mov_b32_e32 v141, v126
	v_mov_b32_e32 v142, v126
	v_mov_b32_e32 v143, v126
	v_mov_b32_e32 v144, v126
	v_mov_b32_e32 v145, v126
	v_mov_b32_e32 v86, v126
	v_mov_b32_e32 v87, v126
	v_mov_b32_e32 v88, v126
	v_mov_b32_e32 v89, v126
	v_mov_b32_e32 v90, v126
	v_mov_b32_e32 v91, v126
	v_mov_b32_e32 v92, v126
	v_mov_b32_e32 v93, v126
	v_mov_b32_e32 v78, v126
	v_mov_b32_e32 v79, v126
	v_mov_b32_e32 v80, v126
	v_mov_b32_e32 v81, v126
	v_mov_b32_e32 v110, v126
	v_mov_b32_e32 v111, v126
	v_mov_b32_e32 v112, v126
	v_mov_b32_e32 v113, v126
	v_mov_b32_e32 v94, v126
	v_mov_b32_e32 v95, v126
	v_mov_b32_e32 v96, v126
	v_mov_b32_e32 v97, v126
	v_mov_b32_e32 v46, v126
	v_mov_b32_e32 v47, v126
	v_mov_b32_e32 v48, v126
	v_mov_b32_e32 v49, v126
	v_mov_b32_e32 v58, v126
	v_mov_b32_e32 v59, v126
	v_mov_b32_e32 v60, v126
	v_mov_b32_e32 v61, v126
	v_mov_b32_e32 v50, v126
	v_mov_b32_e32 v51, v126
	v_mov_b32_e32 v52, v126
	v_mov_b32_e32 v53, v126
	v_mov_b32_e32 v22, v126
	v_mov_b32_e32 v23, v126
	v_mov_b32_e32 v24, v126
	v_mov_b32_e32 v25, v126
	v_mov_b32_e32 v26, v126
	v_mov_b32_e32 v27, v126
	v_mov_b32_e32 v28, v126
	v_mov_b32_e32 v29, v126
	v_mov_b32_e32 v18, v126
	v_mov_b32_e32 v19, v126
	v_mov_b32_e32 v20, v126
	v_mov_b32_e32 v21, v126
	v_mov_b32_e32 v38, v126
	v_mov_b32_e32 v39, v126
	v_mov_b32_e32 v40, v126
	v_mov_b32_e32 v41, v126
	v_mov_b32_e32 v34, v126
	v_mov_b32_e32 v35, v126
	v_mov_b32_e32 v36, v126
	v_mov_b32_e32 v37, v126
	v_mov_b32_e32 v30, v126
	v_mov_b32_e32 v31, v126
	v_mov_b32_e32 v32, v126
	v_mov_b32_e32 v33, v126
	v_mov_b32_e32 v42, v126
	v_mov_b32_e32 v43, v126
	v_mov_b32_e32 v44, v126
	v_mov_b32_e32 v45, v126
	v_mov_b32_e32 v54, v126
	v_mov_b32_e32 v55, v126
	v_mov_b32_e32 v56, v126
	v_mov_b32_e32 v57, v126
	v_mov_b32_e32 v62, v126
	v_mov_b32_e32 v63, v126
	v_mov_b32_e32 v64, v126
	v_mov_b32_e32 v65, v126
	v_mov_b32_e32 v66, v126
	v_mov_b32_e32 v67, v126
	v_mov_b32_e32 v68, v126
	v_mov_b32_e32 v69, v126
	v_mov_b32_e32 v70, v126
	v_mov_b32_e32 v71, v126
	v_mov_b32_e32 v72, v126
	v_mov_b32_e32 v73, v126
	v_mov_b32_e32 v74, v126
	v_mov_b32_e32 v75, v126
	v_mov_b32_e32 v76, v126
	v_mov_b32_e32 v77, v126
	v_mov_b32_e32 v82, v126
	v_mov_b32_e32 v83, v126
	v_mov_b32_e32 v84, v126
	v_mov_b32_e32 v85, v126
	v_mov_b32_e32 v98, v126
	v_mov_b32_e32 v99, v126
	v_mov_b32_e32 v100, v126
	v_mov_b32_e32 v101, v126
	v_mov_b32_e32 v102, v126
	v_mov_b32_e32 v103, v126
	v_mov_b32_e32 v104, v126
	v_mov_b32_e32 v105, v126
	v_mov_b32_e32 v106, v126
	v_mov_b32_e32 v107, v126
	v_mov_b32_e32 v108, v126
	v_mov_b32_e32 v109, v126
	v_mov_b32_e32 v114, v126
	v_mov_b32_e32 v115, v126
	v_mov_b32_e32 v116, v126
	v_mov_b32_e32 v117, v126
	v_mov_b32_e32 v118, v126
	v_mov_b32_e32 v119, v126
	v_mov_b32_e32 v120, v126
	v_mov_b32_e32 v121, v126
	v_mov_b32_e32 v122, v126
	v_mov_b32_e32 v123, v126
	v_mov_b32_e32 v124, v126
	v_mov_b32_e32 v125, v126
	s_mov_b32 s18, 0x9c53000
	s_mov_b32 s24, 0x9c83000
	s_mov_b32 s25, 0x9cb3000
	s_mov_b32 s34, 0x2880000
	s_mov_b32 s35, 0x2888000
	s_mov_b32 s38, 0x2890000
	s_mov_b32 s39, 0x2898000
	s_waitcnt lgkmcnt(0)
	s_barrier
	s_add_i32 s98, s1, 0xffff8000
	s_and_b32 s98, s98, 0x8000
	s_add_i32 s98, s98, 32
	v_add_u32_e32 v226, s98, v172
	ds_read_b128 v[196:199], v226
	ds_read_b128 v[200:203], v226 offset:2048
; #define MFMA16(a, b, c) __builtin_amdgcn_mfma_f32_16x16x32_bf16((a), (b), (c), 0, 0, 0)
; template <class Epi>
; DEVI void gemm_tile256b(const bf16_t* __restrict__ A, int lda, const bf16_t* __restrict__ Bt, int K,
;                         int m0, int n0, char* smem, Epi epi) {
;     ...
;   for (int kt = 0; kt < nk; ++kt) {
;     const char* base = smem + (kt & 1) * 32768;
;     const bool more = kt + 1 < nk;
;     if (more) {
; #pragma unroll
;       for (int i = 0; i < 8; ++i) ra[i] = *(const u32x4*)(ag + (size_t)(i * 32) * lda + (kt + 1) * 64);
;     }
; #pragma unroll
;     for (int i = 0; i < 4; ++i) b1[i] = *(const bf16x8*)(bp + ((size_t)i * kb32 + kt * 2 + 1) * 512);
;     {
;       bf16x8 af[8];
; #pragma unroll
;       for (int i = 0; i < 8; ++i) af[i] = *(const bf16x8*)(base + a_rd + i * 2048);
; #pragma unroll
;       for (int mi = 0; mi < 8; ++mi)
; #pragma unroll
;         for (int ni = 0; ni < 4; ++ni) acc[mi][ni] = MFMA16(b0[ni], af[mi], acc[mi][ni]);
;     }
;     if (more) {
; #pragma unroll
;       for (int i = 0; i < 4; ++i) b0[i] = *(const bf16x8*)(bp + ((size_t)i * kb32 + kt * 2 + 2) * 512);
;     }
;     {
;       bf16x8 af[8];
; #pragma unroll
;       for (int i = 0; i < 8; ++i) af[i] = *(const bf16x8*)(base + ((a_rd + i * 2048) ^ 64));
; #pragma unroll
;       for (int mi = 0; mi < 8; ++mi)
; #pragma unroll
;         for (int ni = 0; ni < 4; ++ni) acc[mi][ni] = MFMA16(b1[ni], af[mi], acc[mi][ni]);
;     }
;     if (more) {
;       char* nb = smem + ((kt + 1) & 1) * 32768 + lds_w;
; #pragma unroll
;       for (int i = 0; i < 8; ++i) *(u32x4*)(nb + i * 4096) = ra[i];
;     }
.LBB0_50:
	s_add_i32 s13, s1, 0xffff8000
	s_and_b32 s13, s13, 0x8000
	s_add_i32 s13, s13, 32
	v_add_u32_e32 v0, s13, v172
	v_lshl_add_u64 v[154:155], v[164:165], 0, s[28:29]
	v_add_co_u32_e32 v156, vcc, s34, v154
	s_waitcnt vmcnt(3) lgkmcnt(1)
	v_mfma_f32_16x16x32_bf16 v[122:125], v[10:13], v[196:199], v[122:125]
	v_addc_co_u32_e32 v157, vcc, 0, v155, vcc
	v_add_co_u32_e32 v158, vcc, s35, v154
	s_waitcnt vmcnt(2)
	v_mfma_f32_16x16x32_bf16 v[118:121], v[14:17], v[196:199], v[118:121]
	v_addc_co_u32_e32 v159, vcc, 0, v155, vcc
	v_add_co_u32_e32 v160, vcc, s38, v154
	s_waitcnt vmcnt(1)
	v_mfma_f32_16x16x32_bf16 v[114:117], v[6:9], v[196:199], v[114:117]
	v_addc_co_u32_e32 v161, vcc, 0, v155, vcc
	v_add_co_u32_e32 v182, vcc, s39, v154
	s_waitcnt vmcnt(0)
	v_mfma_f32_16x16x32_bf16 v[106:109], v[2:5], v[196:199], v[106:109]
	v_addc_co_u32_e32 v183, vcc, 0, v155, vcc
	v_lshl_add_u64 v[164:165], v[164:165], 0, s[64:65]
	s_waitcnt lgkmcnt(0)
	v_mfma_f32_16x16x32_bf16 v[102:105], v[10:13], v[200:203], v[102:105]
	v_mfma_f32_16x16x32_bf16 v[98:101], v[14:17], v[200:203], v[98:101]
	v_mfma_f32_16x16x32_bf16 v[82:85], v[6:9], v[200:203], v[82:85]
	v_mfma_f32_16x16x32_bf16 v[74:77], v[2:5], v[200:203], v[74:77]
	ds_read_b128 v[146:149], v0 offset:4096
	ds_read_b128 v[150:153], v0 offset:6144
	s_waitcnt lgkmcnt(1)
	v_mfma_f32_16x16x32_bf16 v[70:73], v[10:13], v[146:149], v[70:73]
	v_mfma_f32_16x16x32_bf16 v[66:69], v[14:17], v[146:149], v[66:69]
	v_mfma_f32_16x16x32_bf16 v[62:65], v[6:9], v[146:149], v[62:65]
	v_mfma_f32_16x16x32_bf16 v[54:57], v[2:5], v[146:149], v[54:57]
	s_waitcnt lgkmcnt(0)
	v_mfma_f32_16x16x32_bf16 v[42:45], v[10:13], v[150:153], v[42:45]
	v_mfma_f32_16x16x32_bf16 v[30:33], v[14:17], v[150:153], v[30:33]
	v_mfma_f32_16x16x32_bf16 v[34:37], v[6:9], v[150:153], v[34:37]
	v_mfma_f32_16x16x32_bf16 v[38:41], v[2:5], v[150:153], v[38:41]
	ds_read_b128 v[146:149], v0 offset:8192
	ds_read_b128 v[150:153], v0 offset:10240
	s_waitcnt lgkmcnt(1)
	v_mfma_f32_16x16x32_bf16 v[18:21], v[10:13], v[146:149], v[18:21]
	v_mfma_f32_16x16x32_bf16 v[26:29], v[14:17], v[146:149], v[26:29]
	v_mfma_f32_16x16x32_bf16 v[22:25], v[6:9], v[146:149], v[22:25]
	v_mfma_f32_16x16x32_bf16 v[50:53], v[2:5], v[146:149], v[50:53]
	s_waitcnt lgkmcnt(0)
	v_mfma_f32_16x16x32_bf16 v[58:61], v[10:13], v[150:153], v[58:61]
	v_mfma_f32_16x16x32_bf16 v[46:49], v[14:17], v[150:153], v[46:49]
	v_mfma_f32_16x16x32_bf16 v[94:97], v[6:9], v[150:153], v[94:97]
	v_mfma_f32_16x16x32_bf16 v[110:113], v[2:5], v[150:153], v[110:113]
	ds_read_b128 v[146:149], v0 offset:12288
	ds_read_b128 v[150:153], v0 offset:14336
	v_add_u32_e32 v0, s13, v171
	s_waitcnt lgkmcnt(1)
	v_mfma_f32_16x16x32_bf16 v[78:81], v[10:13], v[146:149], v[78:81]
	v_mfma_f32_16x16x32_bf16 v[90:93], v[14:17], v[146:149], v[90:93]
	v_mfma_f32_16x16x32_bf16 v[86:89], v[6:9], v[146:149], v[86:89]
	v_mfma_f32_16x16x32_bf16 v[142:145], v[2:5], v[146:149], v[142:145]
	global_load_dwordx4 v[146:149], v[156:157], off offset:1024
	ds_read_b128 v[174:177], v0
	ds_read_b128 v[178:181], v0 offset:2048
	s_waitcnt lgkmcnt(2)
	v_mfma_f32_16x16x32_bf16 v[138:141], v[10:13], v[150:153], v[138:141]
	global_load_dwordx4 v[10:13], v[156:157], off offset:2048
	v_mfma_f32_16x16x32_bf16 v[134:137], v[14:17], v[150:153], v[134:137]
	v_mfma_f32_16x16x32_bf16 v[130:133], v[6:9], v[150:153], v[130:133]
	v_mfma_f32_16x16x32_bf16 v[126:129], v[2:5], v[150:153], v[126:129]
	global_load_dwordx4 v[150:153], v[158:159], off offset:1024
	global_load_dwordx4 v[14:17], v[158:159], off offset:2048
	global_load_dwordx4 v[154:157], v[160:161], off offset:1024
	global_load_dwordx4 v[6:9], v[160:161], off offset:2048
	s_nop 0
	global_load_dwordx4 v[158:161], v[182:183], off offset:1024
	global_load_dwordx4 v[2:5], v[182:183], off offset:2048
	v_lshrrev_b32_e32 v195, 6, v206
	v_lshl_add_u64 v[190:191], v[166:167], 0, s[28:29]
	v_lshrrev_b32_e32 v194, 3, v206
	v_readfirstlane_b32 s99, v195
	v_and_b32_e32 v194, 7, v194
	s_and_b32 s98, s1, 0x8000
	v_lshlrev_b32_e32 v194, 4, v194
	s_lshl_b32 s99, s99, 10
	v_xor_b32_e32 v190, v194, v190
	s_add_u32 s98, s98, s99
	s_add_u32 s98, s98, 32
	s_mov_b32 s101, 0
	s_add_u32 s100, s18, 0x80
	v_lshl_add_u64 v[192:193], v[190:191], 0, s[100:101]
	s_mov_b32 m0, s98
	s_nop 0
	global_load_lds_dwordx4 v[192:193], off
	s_mov_b32 s100, 0x9c63080
	v_lshl_add_u64 v[192:193], v[190:191], 0, s[100:101]
	s_add_u32 m0, s98, 0x1000
	s_nop 0
	global_load_lds_dwordx4 v[192:193], off
	s_mov_b32 s100, 0x9c73080
	v_lshl_add_u64 v[192:193], v[190:191], 0, s[100:101]
	s_add_u32 m0, s98, 0x2000
	s_nop 0
	global_load_lds_dwordx4 v[192:193], off
	s_add_u32 s100, s24, 0x80
	v_lshl_add_u64 v[192:193], v[190:191], 0, s[100:101]
	s_add_u32 m0, s98, 0x3000
	s_nop 0
	global_load_lds_dwordx4 v[192:193], off
	s_mov_b32 s100, 0x9c93080
	v_lshl_add_u64 v[192:193], v[190:191], 0, s[100:101]
	s_add_u32 m0, s98, 0x4000
	s_nop 0
	global_load_lds_dwordx4 v[192:193], off
	s_mov_b32 s100, 0x9ca3080
	v_lshl_add_u64 v[192:193], v[190:191], 0, s[100:101]
	s_add_u32 m0, s98, 0x5000
	s_nop 0
	global_load_lds_dwordx4 v[192:193], off
	s_add_u32 s100, s25, 0x80
	v_lshl_add_u64 v[192:193], v[190:191], 0, s[100:101]
	s_add_u32 m0, s98, 0x6000
	s_nop 0
	global_load_lds_dwordx4 v[192:193], off
	s_mov_b32 s100, 0x9cc3080
	v_lshl_add_u64 v[192:193], v[190:191], 0, s[100:101]
	s_add_u32 m0, s98, 0x7000
	s_nop 0
	global_load_lds_dwordx4 v[192:193], off
	s_waitcnt vmcnt(15) lgkmcnt(1)
	v_mfma_f32_16x16x32_bf16 v[122:125], v[146:149], v[174:177], v[122:125]
	s_nop 0
	s_waitcnt vmcnt(13)
	v_mfma_f32_16x16x32_bf16 v[118:121], v[150:153], v[174:177], v[118:121]
	s_waitcnt vmcnt(11)
; #define MFMA16(a, b, c) __builtin_amdgcn_mfma_f32_16x16x32_bf16((a), (b), (c), 0, 0, 0)
; template <class Epi>
; DEVI void gemm_tile256b(const bf16_t* __restrict__ A, int lda, const bf16_t* __restrict__ Bt, int K,
;                         int m0, int n0, char* smem, Epi epi) {
;     ...
;     if (more) {
; #pragma unroll
;       for (int i = 0; i < 4; ++i) b0[i] = *(const bf16x8*)(bp + ((size_t)i * kb32 + kt * 2 + 2) * 512);
;     }
;     {
;       bf16x8 af[8];
; #pragma unroll
;       for (int i = 0; i < 8; ++i) af[i] = *(const bf16x8*)(base + ((a_rd + i * 2048) ^ 64));
; #pragma unroll
;       for (int mi = 0; mi < 8; ++mi)
; #pragma unroll
;         for (int ni = 0; ni < 4; ++ni) acc[mi][ni] = MFMA16(b1[ni], af[mi], acc[mi][ni]);
;     }
;     if (more) {
;       char* nb = smem + ((kt + 1) & 1) * 32768 + lds_w;
; #pragma unroll
;       for (int i = 0; i < 8; ++i) *(u32x4*)(nb + i * 4096) = ra[i];
;     }
;     __syncthreads();
;   }
	v_mfma_f32_16x16x32_bf16 v[114:117], v[154:157], v[174:177], v[114:117]
	s_waitcnt vmcnt(9)
	v_mfma_f32_16x16x32_bf16 v[106:109], v[158:161], v[174:177], v[106:109]
	s_waitcnt lgkmcnt(0)
	v_mfma_f32_16x16x32_bf16 v[102:105], v[146:149], v[178:181], v[102:105]
	v_mfma_f32_16x16x32_bf16 v[98:101], v[150:153], v[178:181], v[98:101]
	s_nop 0
	v_mfma_f32_16x16x32_bf16 v[82:85], v[154:157], v[178:181], v[82:85]
	s_nop 0
	v_mfma_f32_16x16x32_bf16 v[74:77], v[158:161], v[178:181], v[74:77]
	ds_read_b128 v[174:177], v0 offset:4096
	ds_read_b128 v[178:181], v0 offset:6144
	s_waitcnt lgkmcnt(1)
	v_mfma_f32_16x16x32_bf16 v[70:73], v[146:149], v[174:177], v[70:73]
	s_and_b32 s13, s1, 0x8000
	v_mfma_f32_16x16x32_bf16 v[66:69], v[150:153], v[174:177], v[66:69]
	s_add_i32 s1, s1, 0x8000
	v_lshl_add_u64 v[166:167], v[166:167], 0, s[60:61]
	s_cmp_eq_u32 s1, 0x80000
	v_mfma_f32_16x16x32_bf16 v[62:65], v[154:157], v[174:177], v[62:65]
	v_mfma_f32_16x16x32_bf16 v[54:57], v[158:161], v[174:177], v[54:57]
	s_waitcnt lgkmcnt(0)
	v_mfma_f32_16x16x32_bf16 v[42:45], v[146:149], v[178:181], v[42:45]
	v_mfma_f32_16x16x32_bf16 v[30:33], v[150:153], v[178:181], v[30:33]
	v_mfma_f32_16x16x32_bf16 v[34:37], v[154:157], v[178:181], v[34:37]
	v_mfma_f32_16x16x32_bf16 v[38:41], v[158:161], v[178:181], v[38:41]
	ds_read_b128 v[174:177], v0 offset:8192
	ds_read_b128 v[178:181], v0 offset:10240
	s_waitcnt lgkmcnt(1)
	v_mfma_f32_16x16x32_bf16 v[18:21], v[146:149], v[174:177], v[18:21]
	v_mfma_f32_16x16x32_bf16 v[26:29], v[150:153], v[174:177], v[26:29]
	v_mfma_f32_16x16x32_bf16 v[22:25], v[154:157], v[174:177], v[22:25]
	v_mfma_f32_16x16x32_bf16 v[50:53], v[158:161], v[174:177], v[50:53]
	s_waitcnt lgkmcnt(0)
	v_mfma_f32_16x16x32_bf16 v[58:61], v[146:149], v[178:181], v[58:61]
	v_mfma_f32_16x16x32_bf16 v[46:49], v[150:153], v[178:181], v[46:49]
	v_mfma_f32_16x16x32_bf16 v[94:97], v[154:157], v[178:181], v[94:97]
	v_mfma_f32_16x16x32_bf16 v[110:113], v[158:161], v[178:181], v[110:113]
	ds_read_b128 v[178:181], v0 offset:12288
	ds_read_b128 v[182:185], v0 offset:14336
	s_nop 0
	s_nop 0
	s_nop 0
	s_nop 0
	s_nop 0
	s_waitcnt lgkmcnt(1)
	v_mfma_f32_16x16x32_bf16 v[78:81], v[146:149], v[178:181], v[78:81]
	v_mfma_f32_16x16x32_bf16 v[90:93], v[150:153], v[178:181], v[90:93]
	v_mfma_f32_16x16x32_bf16 v[86:89], v[154:157], v[178:181], v[86:89]
	s_waitcnt vmcnt(0) lgkmcnt(0)
	s_barrier
	s_add_i32 s98, s1, 0xffff8000
	s_and_b32 s98, s98, 0x8000
	s_add_i32 s98, s98, 32
	v_add_u32_e32 v226, s98, v172
	ds_read_b128 v[196:199], v226
	ds_read_b128 v[200:203], v226 offset:2048
	v_mfma_f32_16x16x32_bf16 v[142:145], v[158:161], v[178:181], v[142:145]
	v_mfma_f32_16x16x32_bf16 v[138:141], v[146:149], v[182:185], v[138:141]
	v_mfma_f32_16x16x32_bf16 v[134:137], v[150:153], v[182:185], v[134:137]
	v_mfma_f32_16x16x32_bf16 v[130:133], v[154:157], v[182:185], v[130:133]
	v_mfma_f32_16x16x32_bf16 v[126:129], v[158:161], v[182:185], v[126:129]
	s_cmp_eq_u32 s1, 0x80000
	s_cbranch_scc0 .LBB0_50
	v_add_u32_e32 v0, 32, v172
	ds_read_b128 v[146:149], v0 offset:32768
	ds_read_b128 v[150:153], v0 offset:34816
	s_waitcnt lgkmcnt(1)
	v_mfma_f32_16x16x32_bf16 v[122:125], v[10:13], v[146:149], v[122:125]
	v_mfma_f32_16x16x32_bf16 v[118:121], v[14:17], v[146:149], v[118:121]
	v_mfma_f32_16x16x32_bf16 v[114:117], v[6:9], v[146:149], v[114:117]
	v_mfma_f32_16x16x32_bf16 v[106:109], v[2:5], v[146:149], v[106:109]
	s_waitcnt lgkmcnt(0)
	v_mfma_f32_16x16x32_bf16 v[102:105], v[10:13], v[150:153], v[102:105]
	v_mfma_f32_16x16x32_bf16 v[98:101], v[14:17], v[150:153], v[98:101]
	v_mfma_f32_16x16x32_bf16 v[82:85], v[6:9], v[150:153], v[82:85]
	v_mfma_f32_16x16x32_bf16 v[74:77], v[2:5], v[150:153], v[74:77]
	ds_read_b128 v[146:149], v0 offset:36864
	ds_read_b128 v[150:153], v0 offset:38912
	s_waitcnt lgkmcnt(1)
	v_mfma_f32_16x16x32_bf16 v[70:73], v[10:13], v[146:149], v[70:73]
	v_mfma_f32_16x16x32_bf16 v[66:69], v[14:17], v[146:149], v[66:69]
	v_mfma_f32_16x16x32_bf16 v[62:65], v[6:9], v[146:149], v[62:65]
	v_mfma_f32_16x16x32_bf16 v[54:57], v[2:5], v[146:149], v[54:57]
	s_waitcnt lgkmcnt(0)
	v_mfma_f32_16x16x32_bf16 v[42:45], v[10:13], v[150:153], v[42:45]
	v_mfma_f32_16x16x32_bf16 v[30:33], v[14:17], v[150:153], v[30:33]
	v_mfma_f32_16x16x32_bf16 v[34:37], v[6:9], v[150:153], v[34:37]
	v_mfma_f32_16x16x32_bf16 v[38:41], v[2:5], v[150:153], v[38:41]
	ds_read_b128 v[146:149], v0 offset:40960
	ds_read_b128 v[150:153], v0 offset:43008
	s_waitcnt lgkmcnt(1)
	v_mfma_f32_16x16x32_bf16 v[18:21], v[10:13], v[146:149], v[18:21]
	v_mfma_f32_16x16x32_bf16 v[26:29], v[14:17], v[146:149], v[26:29]
	v_mfma_f32_16x16x32_bf16 v[22:25], v[6:9], v[146:149], v[22:25]
	v_mfma_f32_16x16x32_bf16 v[50:53], v[2:5], v[146:149], v[50:53]
	s_waitcnt lgkmcnt(0)
	v_mfma_f32_16x16x32_bf16 v[146:149], v[10:13], v[150:153], v[58:61]
	v_mfma_f32_16x16x32_bf16 v[154:157], v[14:17], v[150:153], v[46:49]
	s_nop 2
	ds_read_b128 v[46:49], v0 offset:45056
	ds_read_b128 v[58:61], v0 offset:47104
	v_add_u32_e32 v0, 32, v171
	s_waitcnt lgkmcnt(1)
	v_mfma_f32_16x16x32_bf16 v[164:167], v[10:13], v[46:49], v[78:81]
	s_nop 2
	v_add_co_u32_e32 v78, vcc, 0x7000, v162
	v_mfma_f32_16x16x32_bf16 v[172:175], v[14:17], v[46:49], v[90:93]
	s_nop 0
	v_addc_co_u32_e32 v79, vcc, 0, v163, vcc
	v_mfma_f32_16x16x32_bf16 v[176:179], v[6:9], v[46:49], v[86:89]
	v_mfma_f32_16x16x32_bf16 v[142:145], v[2:5], v[46:49], v[142:145]
	v_add_co_u32_e32 v46, vcc, 0xf000, v162
	s_nop 1
	v_addc_co_u32_e32 v47, vcc, 0, v163, vcc
	s_waitcnt lgkmcnt(0)
; #define MFMA16(a, b, c) __builtin_amdgcn_mfma_f32_16x16x32_bf16((a), (b), (c), 0, 0, 0)
; template <class Epi>
; DEVI void gemm_tile256b(const bf16_t* __restrict__ A, int lda, const bf16_t* __restrict__ Bt, int K,
;                         int m0, int n0, char* smem, Epi epi) {
;     ...
;     {
;       bf16x8 af[8];
; #pragma unroll
;       for (int i = 0; i < 8; ++i) af[i] = *(const bf16x8*)(base + ((a_rd + i * 2048) ^ 64));
; #pragma unroll
;       for (int mi = 0; mi < 8; ++mi)
; #pragma unroll
;         for (int ni = 0; ni < 4; ++ni) acc[mi][ni] = MFMA16(b1[ni], af[mi], acc[mi][ni]);
;     }
;     if (more) {
;       char* nb = smem + ((kt + 1) & 1) * 32768 + lds_w;
; #pragma unroll
;       for (int i = 0; i < 8; ++i) *(u32x4*)(nb + i * 4096) = ra[i];
;     }
;     __syncthreads();
;   }
; #pragma unroll
;   for (int mi = 0; mi < 8; ++mi)
; #pragma unroll
;     for (int ni = 0; ni < 4; ++ni)
;       epi(m0 + wm * 128 + mi * 16 + l15, n0 + wn * 64 + ni * 16 + quad * 4, acc[mi][ni]);
;   DEVI void operator()(int m, int n, f32x4 v) const {
;     if (m >= L) return;
;     float* h = hfrow(p, m) + n;
;     const float* src = (first && m >= 16) ? p.in[0] + (size_t)(m - 16) * 1024 + n : h;
;     f32x4 o = *(const f32x4*)src;
;     o = o * ALPHA + v;
;     *(f32x4*)h = o;
;   }
	v_mfma_f32_16x16x32_bf16 v[10:13], v[10:13], v[58:61], v[138:141]
	global_load_dwordx4 v[180:183], v[46:47], off offset:3072
	s_nop 1
	global_load_dwordx4 v[138:141], v[78:79], off offset:3072
	v_add_co_u32_e32 v78, vcc, 0x17000, v162
	v_mfma_f32_16x16x32_bf16 v[158:161], v[6:9], v[150:153], v[94:97]
	s_nop 0
	v_addc_co_u32_e32 v79, vcc, 0, v163, vcc
	v_mfma_f32_16x16x32_bf16 v[150:153], v[2:5], v[150:153], v[110:113]
	v_mfma_f32_16x16x32_bf16 v[134:137], v[14:17], v[58:61], v[134:137]
	ds_read_b128 v[14:17], v0 offset:32768
	v_mfma_f32_16x16x32_bf16 v[6:9], v[6:9], v[58:61], v[130:133]
	v_mfma_f32_16x16x32_bf16 v[2:5], v[2:5], v[58:61], v[126:129]
	v_add_co_u32_e32 v58, vcc, 0x1f000, v162
	s_nop 0
	global_load_dwordx4 v[130:133], v[78:79], off offset:3072
	v_addc_co_u32_e32 v59, vcc, 0, v163, vcc
	global_load_dwordx4 v[190:193], v[58:59], off offset:3072
	ds_read_b128 v[46:49], v0 offset:34816
	s_waitcnt vmcnt(2) lgkmcnt(1)
	v_mfma_f32_16x16x32_bf16 v[126:129], v[138:141], v[14:17], v[122:125]
	v_mfma_f32_16x16x32_bf16 v[122:125], v[180:183], v[14:17], v[118:121]
	s_waitcnt vmcnt(1)
	v_mfma_f32_16x16x32_bf16 v[118:121], v[130:133], v[14:17], v[114:117]
	s_waitcnt vmcnt(0)
	v_mfma_f32_16x16x32_bf16 v[114:117], v[190:193], v[14:17], v[106:109]
	s_waitcnt lgkmcnt(0)
	v_mfma_f32_16x16x32_bf16 v[110:113], v[138:141], v[46:49], v[102:105]
	v_mfma_f32_16x16x32_bf16 v[106:109], v[180:183], v[46:49], v[98:101]
	v_mfma_f32_16x16x32_bf16 v[102:105], v[130:133], v[46:49], v[82:85]
	v_mfma_f32_16x16x32_bf16 v[98:101], v[190:193], v[46:49], v[74:77]
	ds_read_b128 v[14:17], v0 offset:36864
	ds_read_b128 v[46:49], v0 offset:38912
	s_waitcnt lgkmcnt(1)
	v_mfma_f32_16x16x32_bf16 v[94:97], v[138:141], v[14:17], v[70:73]
	v_mfma_f32_16x16x32_bf16 v[90:93], v[180:183], v[14:17], v[66:69]
	v_mfma_f32_16x16x32_bf16 v[86:89], v[130:133], v[14:17], v[62:65]
	v_mfma_f32_16x16x32_bf16 v[82:85], v[190:193], v[14:17], v[54:57]
	s_waitcnt lgkmcnt(0)
	v_mfma_f32_16x16x32_bf16 v[74:77], v[180:183], v[46:49], v[30:33]
	ds_read_b128 v[14:17], v0 offset:40960
	s_nop 1
	ds_read_b128 v[30:33], v0 offset:43008
	v_mfma_f32_16x16x32_bf16 v[78:81], v[138:141], v[46:49], v[42:45]
	v_mfma_f32_16x16x32_bf16 v[70:73], v[130:133], v[46:49], v[34:37]
	v_mfma_f32_16x16x32_bf16 v[66:69], v[190:193], v[46:49], v[38:41]
	s_waitcnt lgkmcnt(1)
	v_mfma_f32_16x16x32_bf16 v[62:65], v[138:141], v[14:17], v[18:21]
	v_mfma_f32_16x16x32_bf16 v[58:61], v[180:183], v[14:17], v[26:29]
	v_mfma_f32_16x16x32_bf16 v[54:57], v[130:133], v[14:17], v[22:25]
	v_mfma_f32_16x16x32_bf16 v[50:53], v[190:193], v[14:17], v[50:53]
	s_waitcnt lgkmcnt(0)
	v_mfma_f32_16x16x32_bf16 v[46:49], v[138:141], v[30:33], v[146:149]
	ds_read_b128 v[14:17], v0 offset:45056
	s_nop 1
	ds_read_b128 v[146:149], v0 offset:47104
	v_and_b32_e32 v0, 0xffffff80, v168
	s_waitcnt lgkmcnt(0)
	v_mfma_f32_16x16x32_bf16 v[42:45], v[180:183], v[30:33], v[154:157]
	s_barrier
	v_mfma_f32_16x16x32_bf16 v[38:41], v[130:133], v[30:33], v[158:161]
	v_mfma_f32_16x16x32_bf16 v[34:37], v[190:193], v[30:33], v[150:153]
	v_mfma_f32_16x16x32_bf16 v[30:33], v[138:141], v[14:17], v[164:167]
	v_mfma_f32_16x16x32_bf16 v[26:29], v[180:183], v[14:17], v[172:175]
	v_mfma_f32_16x16x32_bf16 v[22:25], v[130:133], v[14:17], v[176:179]
	v_mfma_f32_16x16x32_bf16 v[18:21], v[190:193], v[14:17], v[142:145]
	v_mfma_f32_16x16x32_bf16 v[14:17], v[138:141], v[146:149], v[10:13]
	v_mfma_f32_16x16x32_bf16 v[10:13], v[180:183], v[146:149], v[134:137]
	v_mfma_f32_16x16x32_bf16 v[6:9], v[130:133], v[146:149], v[6:9]
	s_nop 1
	v_add_u32_e32 v134, s0, v0
	v_and_or_b32 v132, v168, 15, v134
	v_lshl_or_b32 v130, v169, 2, v170
	v_mfma_f32_16x16x32_bf16 v[2:5], v[190:193], v[146:149], v[2:5]
	s_movk_i32 s0, 0x4010
	v_cmp_gt_i32_e32 vcc, s0, v132
	v_ashrrev_i32_e32 v131, 31, v130
	s_and_saveexec_b64 s[38:39], vcc
	s_cbranch_execz .LBB0_53
	v_lshlrev_b32_e32 v136, 10, v132
	v_add_u32_e32 v0, -16, v132
	v_ashrrev_i32_e32 v137, 31, v136
	v_lshlrev_b64 v[138:139], 12, v[0:1]
	v_lshl_add_u64 v[136:137], v[136:137], 2, s[16:17]
	v_lshl_add_u64 v[140:141], s[26:27], 0, v[138:139]
	v_cmp_gt_i32_e64 s[0:1], 16, v132
	v_readlane_b32 s68, v248, 63
	v_readlane_b32 s69, v247, 0
	v_cndmask_b32_e64 v137, v141, v137, s[0:1]
	v_cndmask_b32_e64 v136, v140, v136, s[0:1]
	v_lshlrev_b64 v[140:141], 2, v[130:131]
	v_cmp_lt_i32_e32 vcc, 15, v132
	v_lshl_add_u64 v[142:143], v[136:137], 0, v[140:141]
	v_lshl_add_u64 v[136:137], s[68:69], 0, v[138:139]
	v_lshl_add_u64 v[136:137], v[136:137], 0, v[140:141]
	s_and_b64 vcc, s[36:37], vcc
	v_cndmask_b32_e32 v141, v143, v137, vcc
	v_cndmask_b32_e32 v140, v142, v136, vcc
	global_load_dwordx4 v[136:139], v[140:141], off
	v_readlane_b32 s70, v247, 1
	v_readlane_b32 s71, v247, 2
	v_readlane_b32 s72, v247, 3
	v_readlane_b32 s73, v247, 4
	v_readlane_b32 s74, v247, 5
	v_readlane_b32 s75, v247, 6
	v_readlane_b32 s76, v247, 7
	v_readlane_b32 s77, v247, 8
	v_readlane_b32 s78, v247, 9
	v_readlane_b32 s79, v247, 10
	v_readlane_b32 s80, v247, 11
	v_readlane_b32 s81, v247, 12
	v_readlane_b32 s82, v247, 13
	v_readlane_b32 s83, v247, 14
	s_waitcnt vmcnt(0)
	v_pk_fma_f32 v[128:129], v[138:139], s[66:67], v[128:129] op_sel_hi:[1,0,1]
	v_pk_fma_f32 v[126:127], v[136:137], s[66:67], v[126:127] op_sel_hi:[1,0,1]
	global_store_dwordx4 v[142:143], v[126:129], off
	global_load_dwordx4 v[126:129], v[140:141], off offset:64
	s_waitcnt vmcnt(0)
	v_pk_fma_f32 v[124:125], v[128:129], s[66:67], v[124:125] op_sel_hi:[1,0,1]
	v_pk_fma_f32 v[122:123], v[126:127], s[66:67], v[122:123] op_sel_hi:[1,0,1]
	global_store_dwordx4 v[142:143], v[122:125], off offset:64
	global_load_dwordx4 v[122:125], v[140:141], off offset:128
	s_waitcnt vmcnt(0)
	v_pk_fma_f32 v[120:121], v[124:125], s[66:67], v[120:121] op_sel_hi:[1,0,1]
	v_pk_fma_f32 v[118:119], v[122:123], s[66:67], v[118:119] op_sel_hi:[1,0,1]
	global_store_dwordx4 v[142:143], v[118:121], off offset:128
	global_load_dwordx4 v[118:121], v[140:141], off offset:192
	s_waitcnt vmcnt(0)
	v_pk_fma_f32 v[116:117], v[120:121], s[66:67], v[116:117] op_sel_hi:[1,0,1]
	v_pk_fma_f32 v[114:115], v[118:119], s[66:67], v[114:115] op_sel_hi:[1,0,1]
	global_store_dwordx4 v[142:143], v[114:117], off offset:192

; #define TIDX opaque_tid()
; template <class Epi>
; DEVI void gemm_tile256b(const bf16_t* __restrict__ A, int lda, const bf16_t* __restrict__ Bt, int K,
;                         int m0, int n0, char* smem, Epi epi) {
;   const int tid = TIDX, lane = tid & 63, wave = tid >> 6;
;   const int wm = wave >> 1, wn = wave & 1, l15 = lane & 15, quad = lane >> 4;
;   f32x4 acc[8][4];
; #pragma unroll
;   for (int i = 0; i < 8; ++i)
; #pragma unroll
;     for (int j = 0; j < 4; ++j) acc[i][j] = f32x4{0.f, 0.f, 0.f, 0.f};
;   const int lrow = tid >> 3, lkc = tid & 7;
;   const bf16_t* ag = A + (size_t)(m0 + lrow) * lda + lkc * 8;
;   const int kb32 = K >> 5;
;   const bf16_t* bp = Bt + ((size_t)((n0 + wn * 64) >> 4) * kb32) * 512 + lane * 8;
;   u32x4 ra[8];
;   bf16x8 b0[4], b1[4];
;   const int lds_w = lrow * 128 + ((lkc ^ (lrow & 7)) << 4);
;   const int nk = K >> 6;
;   const int sw = (quad ^ (l15 & 7)) << 4;
;   const int a_rd = (wm * 128 + l15) * 128 + sw;
; #pragma unroll
;   for (int i = 0; i < 8; ++i) ra[i] = *(const u32x4*)(ag + (size_t)(i * 32) * lda);
; #pragma unroll
;   for (int i = 0; i < 4; ++i) b0[i] = *(const bf16x8*)(bp + ((size_t)i * kb32) * 512);
; #pragma unroll
;   for (int i = 0; i < 8; ++i) *(u32x4*)(smem + lds_w + i * 4096) = ra[i];
;   __syncthreads();
;   for (int kt = 0; kt < nk; ++kt) {
.LBB0_323:
	v_mov_b32_e32 v168, v206
	v_readlane_b32 s24, v247, 26
	s_lshl_b32 s0, s17, 8
	v_readlane_b32 s25, v247, 27
	v_ashrrev_i32_e32 v8, 3, v168
	v_add_u32_e32 v9, s0, v8
	v_mov_b64_e32 v[2:3], s[24:25]
	s_movk_i32 s17, 0x1800
	v_lshlrev_b32_e32 v0, 4, v168
	v_mad_i64_i32 v[2:3], s[24:25], v9, s17, v[2:3]
	v_and_b32_e32 v0, 0x70, v0
	v_lshl_add_u64 v[2:3], v[2:3], 0, v[0:1]
	v_add_co_u32_e32 v4, vcc, s52, v2
	s_mov_b32 s1, 0x90000
	s_nop 0
	v_addc_co_u32_e32 v5, vcc, 0, v3, vcc
	v_add_co_u32_e32 v6, vcc, s3, v2
	global_load_dwordx4 v[18:21], v[2:3], off
	s_nop 0
	v_addc_co_u32_e32 v7, vcc, 0, v3, vcc
	global_load_dwordx4 v[22:25], v[4:5], off
	global_load_dwordx4 v[26:29], v[6:7], off
	v_add_co_u32_e32 v4, vcc, s1, v2
	s_mov_b32 s1, 0xc0000
	s_nop 0
	v_addc_co_u32_e32 v5, vcc, 0, v3, vcc
	v_add_co_u32_e32 v6, vcc, s1, v2
	s_mov_b32 s1, 0xf0000
	s_nop 0
	v_addc_co_u32_e32 v7, vcc, 0, v3, vcc
	global_load_dwordx4 v[30:33], v[4:5], off
	global_load_dwordx4 v[34:37], v[6:7], off
	v_add_co_u32_e32 v4, vcc, s1, v2
	s_mov_b32 s1, 0x120000
	s_nop 0
	v_addc_co_u32_e32 v5, vcc, 0, v3, vcc
	v_add_co_u32_e32 v6, vcc, s1, v2
	s_mov_b32 s1, 0x150000
	s_nop 0
	v_addc_co_u32_e32 v7, vcc, 0, v3, vcc
	v_add_co_u32_e32 v2, vcc, s1, v2
	s_lshl_b32 s13, s16, 7
	s_nop 0
	v_addc_co_u32_e32 v3, vcc, 0, v3, vcc
	v_and_or_b32 v170, v168, 64, s13
	global_load_dwordx4 v[38:41], v[4:5], off
	global_load_dwordx4 v[42:45], v[6:7], off
	global_load_dwordx4 v[46:49], v[2:3], off
	v_lshlrev_b32_e32 v3, 7, v168
	v_ashrrev_i32_e32 v2, 4, v170
	v_and_b32_e32 v57, 0xffffc780, v3
	v_ashrrev_i32_e32 v3, 31, v2
	v_and_b32_e32 v0, 63, v168
	v_lshlrev_b64 v[52:53], 15, v[2:3]
	v_lshlrev_b32_e32 v0, 4, v0
	v_lshl_add_u64 v[2:3], s[6:7], 0, v[52:53]
	s_mov_b32 s1, 0x8000
	v_xor_b32_e32 v5, v8, v168
	v_lshl_add_u64 v[162:163], v[2:3], 0, v[0:1]
	v_lshlrev_b32_e32 v5, 4, v5
	v_add_co_u32_e32 v2, vcc, s1, v162
	v_lshlrev_b32_e32 v4, 7, v8
	v_and_b32_e32 v5, 0x70, v5
	v_addc_co_u32_e32 v3, vcc, 0, v163, vcc
	v_add3_u32 v173, 32, v5, v4
	v_add_co_u32_e32 v4, vcc, s54, v162
	v_bfe_u32 v169, v168, 4, 2
	s_nop 0
	v_addc_co_u32_e32 v5, vcc, 0, v163, vcc
	s_mov_b32 s13, 0x18000
	v_bitop3_b32 v6, v169, v168, 7 bitop3:0x78
	v_add_co_u32_e32 v54, vcc, s13, v162
	v_mad_i64_i32 v[50:51], s[16:17], v9, s17, 0
	v_lshlrev_b32_e32 v58, 4, v6
	global_load_dwordx4 v[10:13], v[162:163], off
	v_addc_co_u32_e32 v55, vcc, 0, v163, vcc
	global_load_dwordx4 v[14:17], v[2:3], off
	global_load_dwordx4 v[6:9], v[4:5], off
	s_nop 0
	global_load_dwordx4 v[2:5], v[54:55], off
	v_and_b32_e32 v56, 7, v168
	v_or_b32_e32 v52, v52, v0
	v_lshl_or_b32 v50, v56, 4, v50
	v_mov_b32_e32 v126, 0
	v_or_b32_e32 v172, v58, v57
	v_bitop3_b32 v171, v58, 64, v57 bitop3:0x36
	v_lshl_add_u64 v[164:165], s[84:85], 0, v[52:53]
	s_waitcnt vmcnt(11)
	ds_write_b128 v173, v[18:21]
	s_waitcnt vmcnt(10)
	ds_write_b128 v173, v[22:25] offset:4096
	s_waitcnt vmcnt(9)
	ds_write_b128 v173, v[26:29] offset:8192
	s_waitcnt vmcnt(8)
	ds_write_b128 v173, v[30:33] offset:12288
	s_waitcnt vmcnt(7)
	ds_write_b128 v173, v[34:37] offset:16384
	s_waitcnt vmcnt(6)
	ds_write_b128 v173, v[38:41] offset:20480
	s_waitcnt vmcnt(5)
	ds_write_b128 v173, v[42:45] offset:24576
	s_waitcnt vmcnt(4)
	ds_write_b128 v173, v[46:49] offset:28672
	v_lshl_add_u64 v[166:167], s[84:85], 0, v[50:51]
	v_mov_b32_e32 v127, v126
	v_mov_b32_e32 v128, v126
	v_mov_b32_e32 v129, v126
	v_mov_b32_e32 v130, v126
	v_mov_b32_e32 v131, v126
	v_mov_b32_e32 v132, v126
	v_mov_b32_e32 v133, v126
	v_mov_b32_e32 v134, v126
	v_mov_b32_e32 v135, v126
	v_mov_b32_e32 v136, v126
	v_mov_b32_e32 v137, v126
	v_mov_b32_e32 v138, v126
	v_mov_b32_e32 v139, v126
	v_mov_b32_e32 v140, v126
	v_mov_b32_e32 v141, v126
	v_mov_b32_e32 v142, v126
	v_mov_b32_e32 v143, v126
	v_mov_b32_e32 v144, v126
	v_mov_b32_e32 v145, v126
	v_mov_b32_e32 v86, v126
	v_mov_b32_e32 v87, v126
	v_mov_b32_e32 v88, v126
	v_mov_b32_e32 v89, v126
	v_mov_b32_e32 v90, v126
	v_mov_b32_e32 v91, v126
	v_mov_b32_e32 v92, v126
	v_mov_b32_e32 v93, v126
	v_mov_b32_e32 v78, v126
	v_mov_b32_e32 v79, v126
	v_mov_b32_e32 v80, v126
	v_mov_b32_e32 v81, v126
	v_mov_b32_e32 v110, v126
	v_mov_b32_e32 v111, v126
	v_mov_b32_e32 v112, v126
	v_mov_b32_e32 v113, v126
	v_mov_b32_e32 v94, v126
	v_mov_b32_e32 v95, v126
	v_mov_b32_e32 v96, v126
	v_mov_b32_e32 v97, v126
	v_mov_b32_e32 v58, v126
	v_mov_b32_e32 v59, v126
	v_mov_b32_e32 v60, v126
	v_mov_b32_e32 v61, v126
	v_mov_b32_e32 v50, v126
	v_mov_b32_e32 v51, v126
	v_mov_b32_e32 v52, v126
	v_mov_b32_e32 v53, v126
	v_mov_b32_e32 v46, v126
	v_mov_b32_e32 v47, v126
	v_mov_b32_e32 v48, v126
	v_mov_b32_e32 v49, v126
	v_mov_b32_e32 v34, v126
	v_mov_b32_e32 v35, v126
	v_mov_b32_e32 v36, v126
	v_mov_b32_e32 v37, v126
	v_mov_b32_e32 v18, v126
	v_mov_b32_e32 v19, v126
	v_mov_b32_e32 v20, v126
	v_mov_b32_e32 v21, v126
	v_mov_b32_e32 v22, v126
	v_mov_b32_e32 v23, v126
	v_mov_b32_e32 v24, v126
	v_mov_b32_e32 v25, v126
	v_mov_b32_e32 v26, v126
	v_mov_b32_e32 v27, v126
	v_mov_b32_e32 v28, v126
	v_mov_b32_e32 v29, v126
	v_mov_b32_e32 v38, v126
	v_mov_b32_e32 v39, v126
	v_mov_b32_e32 v40, v126
	v_mov_b32_e32 v41, v126
	v_mov_b32_e32 v30, v126
	v_mov_b32_e32 v31, v126
	v_mov_b32_e32 v32, v126
	v_mov_b32_e32 v33, v126
	v_mov_b32_e32 v42, v126
	v_mov_b32_e32 v43, v126
	v_mov_b32_e32 v44, v126
	v_mov_b32_e32 v45, v126
	v_mov_b32_e32 v54, v126
	v_mov_b32_e32 v55, v126
	v_mov_b32_e32 v56, v126
	v_mov_b32_e32 v57, v126
	v_mov_b32_e32 v62, v126
	v_mov_b32_e32 v63, v126
	v_mov_b32_e32 v64, v126
	v_mov_b32_e32 v65, v126
	v_mov_b32_e32 v66, v126
	v_mov_b32_e32 v67, v126
	v_mov_b32_e32 v68, v126
	v_mov_b32_e32 v69, v126
	v_mov_b32_e32 v70, v126
	v_mov_b32_e32 v71, v126
	v_mov_b32_e32 v72, v126
	v_mov_b32_e32 v73, v126
	v_mov_b32_e32 v74, v126
	v_mov_b32_e32 v75, v126
	v_mov_b32_e32 v76, v126
	v_mov_b32_e32 v77, v126
	v_mov_b32_e32 v82, v126
	v_mov_b32_e32 v83, v126
	v_mov_b32_e32 v84, v126
	v_mov_b32_e32 v85, v126
	v_mov_b32_e32 v98, v126
	v_mov_b32_e32 v99, v126
	v_mov_b32_e32 v100, v126
	v_mov_b32_e32 v101, v126
	v_mov_b32_e32 v102, v126
	v_mov_b32_e32 v103, v126
	v_mov_b32_e32 v104, v126
	v_mov_b32_e32 v105, v126
	v_mov_b32_e32 v106, v126
	v_mov_b32_e32 v107, v126
	v_mov_b32_e32 v108, v126
	v_mov_b32_e32 v109, v126
	v_mov_b32_e32 v114, v126
	v_mov_b32_e32 v115, v126
	v_mov_b32_e32 v116, v126
	v_mov_b32_e32 v117, v126
	v_mov_b32_e32 v118, v126
	v_mov_b32_e32 v119, v126
	v_mov_b32_e32 v120, v126
	v_mov_b32_e32 v121, v126
	v_mov_b32_e32 v122, v126
	v_mov_b32_e32 v123, v126
	v_mov_b32_e32 v124, v126
	v_mov_b32_e32 v125, v126
	s_mov_b32 s16, 0x9c53000
	s_mov_b32 s17, 0x9c83000
	s_mov_b32 s18, 0x9cb3000
	s_mov_b32 s24, 0x2880000
	s_mov_b32 s25, 0x2888000
	s_mov_b32 s34, 0x2890000
	s_mov_b32 s35, 0x2898000
	s_waitcnt lgkmcnt(0)
	s_barrier
	s_add_i32 s98, s1, 0xffff8000
	s_and_b32 s98, s98, 0x8000
	s_add_i32 s98, s98, 32
	v_add_u32_e32 v226, s98, v172
	ds_read_b128 v[196:199], v226
	ds_read_b128 v[200:203], v226 offset:2048
; #define MFMA16(a, b, c) __builtin_amdgcn_mfma_f32_16x16x32_bf16((a), (b), (c), 0, 0, 0)
; template <class Epi>
; DEVI void gemm_tile256b(const bf16_t* __restrict__ A, int lda, const bf16_t* __restrict__ Bt, int K,
;                         int m0, int n0, char* smem, Epi epi) {
;     ...
;   for (int kt = 0; kt < nk; ++kt) {
;     const char* base = smem + (kt & 1) * 32768;
;     const bool more = kt + 1 < nk;
;     if (more) {
; #pragma unroll
;       for (int i = 0; i < 8; ++i) ra[i] = *(const u32x4*)(ag + (size_t)(i * 32) * lda + (kt + 1) * 64);
;     }
; #pragma unroll
;     for (int i = 0; i < 4; ++i) b1[i] = *(const bf16x8*)(bp + ((size_t)i * kb32 + kt * 2 + 1) * 512);
;     {
;       bf16x8 af[8];
; #pragma unroll
;       for (int i = 0; i < 8; ++i) af[i] = *(const bf16x8*)(base + a_rd + i * 2048);
; #pragma unroll
;       for (int mi = 0; mi < 8; ++mi)
; #pragma unroll
;         for (int ni = 0; ni < 4; ++ni) acc[mi][ni] = MFMA16(b0[ni], af[mi], acc[mi][ni]);
;     }
;     if (more) {
; #pragma unroll
;       for (int i = 0; i < 4; ++i) b0[i] = *(const bf16x8*)(bp + ((size_t)i * kb32 + kt * 2 + 2) * 512);
;     }
;     {
;       bf16x8 af[8];
; #pragma unroll
;       for (int i = 0; i < 8; ++i) af[i] = *(const bf16x8*)(base + ((a_rd + i * 2048) ^ 64));
; #pragma unroll
;       for (int mi = 0; mi < 8; ++mi)
; #pragma unroll
;         for (int ni = 0; ni < 4; ++ni) acc[mi][ni] = MFMA16(b1[ni], af[mi], acc[mi][ni]);
;     }
;     if (more) {
;       char* nb = smem + ((kt + 1) & 1) * 32768 + lds_w;
; #pragma unroll
;       for (int i = 0; i < 8; ++i) *(u32x4*)(nb + i * 4096) = ra[i];
;     }
.LBB0_324:
	s_add_i32 s13, s1, 0xffff8000
	s_and_b32 s13, s13, 0x8000
	s_add_i32 s13, s13, 32
	v_add_u32_e32 v0, s13, v172
	v_lshl_add_u64 v[154:155], v[164:165], 0, s[28:29]
	v_add_co_u32_e32 v156, vcc, s24, v154
	s_waitcnt vmcnt(3) lgkmcnt(1)
	v_mfma_f32_16x16x32_bf16 v[122:125], v[10:13], v[196:199], v[122:125]
	v_addc_co_u32_e32 v157, vcc, 0, v155, vcc
	v_add_co_u32_e32 v158, vcc, s25, v154
	s_waitcnt vmcnt(2)
	v_mfma_f32_16x16x32_bf16 v[118:121], v[14:17], v[196:199], v[118:121]
	v_addc_co_u32_e32 v159, vcc, 0, v155, vcc
	v_add_co_u32_e32 v160, vcc, s34, v154
	s_waitcnt vmcnt(1)
	v_mfma_f32_16x16x32_bf16 v[114:117], v[6:9], v[196:199], v[114:117]
	v_addc_co_u32_e32 v161, vcc, 0, v155, vcc
	v_add_co_u32_e32 v182, vcc, s35, v154
	s_waitcnt vmcnt(0)
	v_mfma_f32_16x16x32_bf16 v[106:109], v[2:5], v[196:199], v[106:109]
	v_addc_co_u32_e32 v183, vcc, 0, v155, vcc
	v_lshl_add_u64 v[164:165], v[164:165], 0, s[64:65]
	s_waitcnt lgkmcnt(0)
	v_mfma_f32_16x16x32_bf16 v[102:105], v[10:13], v[200:203], v[102:105]
	v_mfma_f32_16x16x32_bf16 v[98:101], v[14:17], v[200:203], v[98:101]
	v_mfma_f32_16x16x32_bf16 v[82:85], v[6:9], v[200:203], v[82:85]
	v_mfma_f32_16x16x32_bf16 v[74:77], v[2:5], v[200:203], v[74:77]
	ds_read_b128 v[146:149], v0 offset:4096
	ds_read_b128 v[150:153], v0 offset:6144
	s_waitcnt lgkmcnt(1)
	v_mfma_f32_16x16x32_bf16 v[70:73], v[10:13], v[146:149], v[70:73]
	v_mfma_f32_16x16x32_bf16 v[66:69], v[14:17], v[146:149], v[66:69]
	v_mfma_f32_16x16x32_bf16 v[62:65], v[6:9], v[146:149], v[62:65]
	v_mfma_f32_16x16x32_bf16 v[54:57], v[2:5], v[146:149], v[54:57]
	s_waitcnt lgkmcnt(0)
	v_mfma_f32_16x16x32_bf16 v[42:45], v[10:13], v[150:153], v[42:45]
	v_mfma_f32_16x16x32_bf16 v[30:33], v[14:17], v[150:153], v[30:33]
	v_mfma_f32_16x16x32_bf16 v[38:41], v[6:9], v[150:153], v[38:41]
	v_mfma_f32_16x16x32_bf16 v[26:29], v[2:5], v[150:153], v[26:29]
	ds_read_b128 v[146:149], v0 offset:8192
	ds_read_b128 v[150:153], v0 offset:10240
	s_waitcnt lgkmcnt(1)
	v_mfma_f32_16x16x32_bf16 v[22:25], v[10:13], v[146:149], v[22:25]
	v_mfma_f32_16x16x32_bf16 v[18:21], v[14:17], v[146:149], v[18:21]
	v_mfma_f32_16x16x32_bf16 v[34:37], v[6:9], v[146:149], v[34:37]
	v_mfma_f32_16x16x32_bf16 v[46:49], v[2:5], v[146:149], v[46:49]
	s_waitcnt lgkmcnt(0)
	v_mfma_f32_16x16x32_bf16 v[50:53], v[10:13], v[150:153], v[50:53]
	v_mfma_f32_16x16x32_bf16 v[58:61], v[14:17], v[150:153], v[58:61]
	v_mfma_f32_16x16x32_bf16 v[94:97], v[6:9], v[150:153], v[94:97]
	v_mfma_f32_16x16x32_bf16 v[110:113], v[2:5], v[150:153], v[110:113]
	ds_read_b128 v[146:149], v0 offset:12288
	ds_read_b128 v[150:153], v0 offset:14336
	v_add_u32_e32 v0, s13, v171
	s_waitcnt lgkmcnt(1)
	v_mfma_f32_16x16x32_bf16 v[78:81], v[10:13], v[146:149], v[78:81]
	v_mfma_f32_16x16x32_bf16 v[90:93], v[14:17], v[146:149], v[90:93]
	v_mfma_f32_16x16x32_bf16 v[86:89], v[6:9], v[146:149], v[86:89]
	v_mfma_f32_16x16x32_bf16 v[142:145], v[2:5], v[146:149], v[142:145]
	global_load_dwordx4 v[146:149], v[156:157], off offset:1024
	ds_read_b128 v[174:177], v0
	ds_read_b128 v[178:181], v0 offset:2048
	s_waitcnt lgkmcnt(2)
	v_mfma_f32_16x16x32_bf16 v[138:141], v[10:13], v[150:153], v[138:141]
	global_load_dwordx4 v[10:13], v[156:157], off offset:2048
	v_mfma_f32_16x16x32_bf16 v[134:137], v[14:17], v[150:153], v[134:137]
	v_mfma_f32_16x16x32_bf16 v[130:133], v[6:9], v[150:153], v[130:133]
	v_mfma_f32_16x16x32_bf16 v[126:129], v[2:5], v[150:153], v[126:129]
	global_load_dwordx4 v[150:153], v[158:159], off offset:1024
	global_load_dwordx4 v[14:17], v[158:159], off offset:2048
	global_load_dwordx4 v[154:157], v[160:161], off offset:1024
	global_load_dwordx4 v[6:9], v[160:161], off offset:2048
	s_nop 0
	global_load_dwordx4 v[158:161], v[182:183], off offset:1024
	global_load_dwordx4 v[2:5], v[182:183], off offset:2048
	v_lshrrev_b32_e32 v195, 6, v206
	v_lshl_add_u64 v[190:191], v[166:167], 0, s[28:29]
	v_lshrrev_b32_e32 v194, 3, v206
	v_readfirstlane_b32 s99, v195
	v_and_b32_e32 v194, 7, v194
	s_and_b32 s98, s1, 0x8000
	v_lshlrev_b32_e32 v194, 4, v194
	s_lshl_b32 s99, s99, 10
	v_xor_b32_e32 v190, v194, v190
	s_add_u32 s98, s98, s99
	s_add_u32 s98, s98, 32
	s_mov_b32 s101, 0
	s_add_u32 s100, s16, 0x80
	v_lshl_add_u64 v[192:193], v[190:191], 0, s[100:101]
	s_mov_b32 m0, s98
	s_nop 0
	global_load_lds_dwordx4 v[192:193], off
	s_add_u32 s100, s17, 0x80
	v_lshl_add_u64 v[192:193], v[190:191], 0, s[100:101]
	s_add_u32 m0, s98, 0x1000
	s_nop 0
	global_load_lds_dwordx4 v[192:193], off
	s_add_u32 s100, s18, 0x80
	v_lshl_add_u64 v[192:193], v[190:191], 0, s[100:101]
	s_add_u32 m0, s98, 0x2000
	s_nop 0
	global_load_lds_dwordx4 v[192:193], off
	s_mov_b32 s100, 0x9ce3080
	v_lshl_add_u64 v[192:193], v[190:191], 0, s[100:101]
	s_add_u32 m0, s98, 0x3000
	s_nop 0
	global_load_lds_dwordx4 v[192:193], off
	s_mov_b32 s100, 0x9d13080
	v_lshl_add_u64 v[192:193], v[190:191], 0, s[100:101]
	s_add_u32 m0, s98, 0x4000
	s_nop 0
	global_load_lds_dwordx4 v[192:193], off
	s_mov_b32 s100, 0x9d43080
	v_lshl_add_u64 v[192:193], v[190:191], 0, s[100:101]
	s_add_u32 m0, s98, 0x5000
	s_nop 0
	global_load_lds_dwordx4 v[192:193], off
	s_mov_b32 s100, 0x9d73080
	v_lshl_add_u64 v[192:193], v[190:191], 0, s[100:101]
	s_add_u32 m0, s98, 0x6000
	s_nop 0
	global_load_lds_dwordx4 v[192:193], off
	s_mov_b32 s100, 0x9da3080
	v_lshl_add_u64 v[192:193], v[190:191], 0, s[100:101]
	s_add_u32 m0, s98, 0x7000
	s_nop 0
	global_load_lds_dwordx4 v[192:193], off
	s_waitcnt vmcnt(15) lgkmcnt(1)
	v_mfma_f32_16x16x32_bf16 v[122:125], v[146:149], v[174:177], v[122:125]
	s_waitcnt vmcnt(13)
	v_mfma_f32_16x16x32_bf16 v[118:121], v[150:153], v[174:177], v[118:121]
	s_waitcnt vmcnt(11)
; #define MFMA16(a, b, c) __builtin_amdgcn_mfma_f32_16x16x32_bf16((a), (b), (c), 0, 0, 0)
; template <class Epi>
; DEVI void gemm_tile256b(const bf16_t* __restrict__ A, int lda, const bf16_t* __restrict__ Bt, int K,
;                         int m0, int n0, char* smem, Epi epi) {
;     ...
;     if (more) {
; #pragma unroll
;       for (int i = 0; i < 4; ++i) b0[i] = *(const bf16x8*)(bp + ((size_t)i * kb32 + kt * 2 + 2) * 512);
;     }
;     {
;       bf16x8 af[8];
; #pragma unroll
;       for (int i = 0; i < 8; ++i) af[i] = *(const bf16x8*)(base + ((a_rd + i * 2048) ^ 64));
; #pragma unroll
;       for (int mi = 0; mi < 8; ++mi)
; #pragma unroll
;         for (int ni = 0; ni < 4; ++ni) acc[mi][ni] = MFMA16(b1[ni], af[mi], acc[mi][ni]);
;     }
;     if (more) {
;       char* nb = smem + ((kt + 1) & 1) * 32768 + lds_w;
; #pragma unroll
;       for (int i = 0; i < 8; ++i) *(u32x4*)(nb + i * 4096) = ra[i];
;     }
;     __syncthreads();
;   }
	v_mfma_f32_16x16x32_bf16 v[114:117], v[154:157], v[174:177], v[114:117]
	s_waitcnt vmcnt(9)
	v_mfma_f32_16x16x32_bf16 v[106:109], v[158:161], v[174:177], v[106:109]
	s_waitcnt lgkmcnt(0)
	v_mfma_f32_16x16x32_bf16 v[102:105], v[146:149], v[178:181], v[102:105]
	v_mfma_f32_16x16x32_bf16 v[98:101], v[150:153], v[178:181], v[98:101]
	v_mfma_f32_16x16x32_bf16 v[82:85], v[154:157], v[178:181], v[82:85]
	s_nop 0
	v_mfma_f32_16x16x32_bf16 v[74:77], v[158:161], v[178:181], v[74:77]
	ds_read_b128 v[174:177], v0 offset:4096
	ds_read_b128 v[178:181], v0 offset:6144
	s_waitcnt lgkmcnt(1)
	v_mfma_f32_16x16x32_bf16 v[70:73], v[146:149], v[174:177], v[70:73]
	v_mfma_f32_16x16x32_bf16 v[66:69], v[150:153], v[174:177], v[66:69]
	s_and_b32 s13, s1, 0x8000
	v_mfma_f32_16x16x32_bf16 v[62:65], v[154:157], v[174:177], v[62:65]
	s_add_i32 s1, s1, 0x8000
	v_mfma_f32_16x16x32_bf16 v[54:57], v[158:161], v[174:177], v[54:57]
	v_lshl_add_u64 v[166:167], v[166:167], 0, s[60:61]
	s_cmp_eq_u32 s1, 0x80000
	s_waitcnt lgkmcnt(0)
	v_mfma_f32_16x16x32_bf16 v[42:45], v[146:149], v[178:181], v[42:45]
	v_mfma_f32_16x16x32_bf16 v[30:33], v[150:153], v[178:181], v[30:33]
	v_mfma_f32_16x16x32_bf16 v[38:41], v[154:157], v[178:181], v[38:41]
	v_mfma_f32_16x16x32_bf16 v[26:29], v[158:161], v[178:181], v[26:29]
	ds_read_b128 v[174:177], v0 offset:8192
	ds_read_b128 v[178:181], v0 offset:10240
	s_waitcnt lgkmcnt(1)
	v_mfma_f32_16x16x32_bf16 v[22:25], v[146:149], v[174:177], v[22:25]
	v_mfma_f32_16x16x32_bf16 v[18:21], v[150:153], v[174:177], v[18:21]
	v_mfma_f32_16x16x32_bf16 v[34:37], v[154:157], v[174:177], v[34:37]
	v_mfma_f32_16x16x32_bf16 v[46:49], v[158:161], v[174:177], v[46:49]
	s_waitcnt lgkmcnt(0)
	v_mfma_f32_16x16x32_bf16 v[50:53], v[146:149], v[178:181], v[50:53]
	v_mfma_f32_16x16x32_bf16 v[58:61], v[150:153], v[178:181], v[58:61]
	v_mfma_f32_16x16x32_bf16 v[94:97], v[154:157], v[178:181], v[94:97]
	v_mfma_f32_16x16x32_bf16 v[110:113], v[158:161], v[178:181], v[110:113]
	ds_read_b128 v[178:181], v0 offset:12288
	ds_read_b128 v[182:185], v0 offset:14336
	s_nop 0
	s_nop 0
	s_nop 0
	s_nop 0
	s_nop 0
	s_waitcnt lgkmcnt(1)
	v_mfma_f32_16x16x32_bf16 v[78:81], v[146:149], v[178:181], v[78:81]
	v_mfma_f32_16x16x32_bf16 v[90:93], v[150:153], v[178:181], v[90:93]
	v_mfma_f32_16x16x32_bf16 v[86:89], v[154:157], v[178:181], v[86:89]
	s_waitcnt vmcnt(0) lgkmcnt(0)
	s_barrier
	s_add_i32 s98, s1, 0xffff8000
	s_and_b32 s98, s98, 0x8000
	s_add_i32 s98, s98, 32
	v_add_u32_e32 v226, s98, v172
	ds_read_b128 v[196:199], v226
	ds_read_b128 v[200:203], v226 offset:2048
	v_mfma_f32_16x16x32_bf16 v[142:145], v[158:161], v[178:181], v[142:145]
	v_mfma_f32_16x16x32_bf16 v[138:141], v[146:149], v[182:185], v[138:141]
	v_mfma_f32_16x16x32_bf16 v[134:137], v[150:153], v[182:185], v[134:137]
	v_mfma_f32_16x16x32_bf16 v[130:133], v[154:157], v[182:185], v[130:133]
	v_mfma_f32_16x16x32_bf16 v[126:129], v[158:161], v[182:185], v[126:129]
	s_cmp_eq_u32 s1, 0x80000
	s_cbranch_scc0 .LBB0_324
	v_add_u32_e32 v0, 32, v172
	ds_read_b128 v[146:149], v0 offset:32768
	ds_read_b128 v[150:153], v0 offset:34816
	s_waitcnt lgkmcnt(1)
	v_mfma_f32_16x16x32_bf16 v[122:125], v[10:13], v[146:149], v[122:125]
	v_mfma_f32_16x16x32_bf16 v[118:121], v[14:17], v[146:149], v[118:121]
	v_mfma_f32_16x16x32_bf16 v[114:117], v[6:9], v[146:149], v[114:117]
	v_mfma_f32_16x16x32_bf16 v[106:109], v[2:5], v[146:149], v[106:109]
	s_waitcnt lgkmcnt(0)
	v_mfma_f32_16x16x32_bf16 v[102:105], v[10:13], v[150:153], v[102:105]
	v_mfma_f32_16x16x32_bf16 v[98:101], v[14:17], v[150:153], v[98:101]
	v_mfma_f32_16x16x32_bf16 v[82:85], v[6:9], v[150:153], v[82:85]
	v_mfma_f32_16x16x32_bf16 v[74:77], v[2:5], v[150:153], v[74:77]
	ds_read_b128 v[146:149], v0 offset:36864
	ds_read_b128 v[150:153], v0 offset:38912
	s_waitcnt lgkmcnt(1)
	v_mfma_f32_16x16x32_bf16 v[70:73], v[10:13], v[146:149], v[70:73]
	v_mfma_f32_16x16x32_bf16 v[66:69], v[14:17], v[146:149], v[66:69]
	v_mfma_f32_16x16x32_bf16 v[62:65], v[6:9], v[146:149], v[62:65]
	v_mfma_f32_16x16x32_bf16 v[54:57], v[2:5], v[146:149], v[54:57]
	s_waitcnt lgkmcnt(0)
	v_mfma_f32_16x16x32_bf16 v[42:45], v[10:13], v[150:153], v[42:45]
	v_mfma_f32_16x16x32_bf16 v[30:33], v[14:17], v[150:153], v[30:33]
	v_mfma_f32_16x16x32_bf16 v[38:41], v[6:9], v[150:153], v[38:41]
	v_mfma_f32_16x16x32_bf16 v[26:29], v[2:5], v[150:153], v[26:29]
	ds_read_b128 v[146:149], v0 offset:40960
	ds_read_b128 v[150:153], v0 offset:43008
	s_waitcnt lgkmcnt(1)
	v_mfma_f32_16x16x32_bf16 v[22:25], v[10:13], v[146:149], v[22:25]
	v_mfma_f32_16x16x32_bf16 v[18:21], v[14:17], v[146:149], v[18:21]
	v_mfma_f32_16x16x32_bf16 v[34:37], v[6:9], v[146:149], v[34:37]
	v_mfma_f32_16x16x32_bf16 v[46:49], v[2:5], v[146:149], v[46:49]
	s_waitcnt lgkmcnt(0)
	v_mfma_f32_16x16x32_bf16 v[146:149], v[10:13], v[150:153], v[50:53]
	v_mfma_f32_16x16x32_bf16 v[154:157], v[14:17], v[150:153], v[58:61]
	s_nop 1
	ds_read_b128 v[50:53], v0 offset:45056
	ds_read_b128 v[58:61], v0 offset:47104
	v_add_u32_e32 v0, 32, v171
	s_waitcnt lgkmcnt(1)
	v_mfma_f32_16x16x32_bf16 v[164:167], v[10:13], v[50:53], v[78:81]
	s_nop 2
	v_add_co_u32_e32 v78, vcc, 0x7000, v162
	v_mfma_f32_16x16x32_bf16 v[172:175], v[14:17], v[50:53], v[90:93]
	s_nop 0
	v_addc_co_u32_e32 v79, vcc, 0, v163, vcc
	v_mfma_f32_16x16x32_bf16 v[176:179], v[6:9], v[50:53], v[86:89]
	v_mfma_f32_16x16x32_bf16 v[142:145], v[2:5], v[50:53], v[142:145]
	v_add_co_u32_e32 v50, vcc, 0xf000, v162
	s_nop 1
	v_addc_co_u32_e32 v51, vcc, 0, v163, vcc
	s_waitcnt lgkmcnt(0)
; #define MFMA16(a, b, c) __builtin_amdgcn_mfma_f32_16x16x32_bf16((a), (b), (c), 0, 0, 0)
; template <class Epi>
; DEVI void gemm_tile256b(const bf16_t* __restrict__ A, int lda, const bf16_t* __restrict__ Bt, int K,
;                         int m0, int n0, char* smem, Epi epi) {
;     ...
;     {
;       bf16x8 af[8];
; #pragma unroll
;       for (int i = 0; i < 8; ++i) af[i] = *(const bf16x8*)(base + ((a_rd + i * 2048) ^ 64));
; #pragma unroll
;       for (int mi = 0; mi < 8; ++mi)
; #pragma unroll
;         for (int ni = 0; ni < 4; ++ni) acc[mi][ni] = MFMA16(b1[ni], af[mi], acc[mi][ni]);
;     }
;     if (more) {
;       char* nb = smem + ((kt + 1) & 1) * 32768 + lds_w;
; #pragma unroll
;       for (int i = 0; i < 8; ++i) *(u32x4*)(nb + i * 4096) = ra[i];
;     }
;     __syncthreads();
;   }
; #pragma unroll
;   for (int mi = 0; mi < 8; ++mi)
; #pragma unroll
;     for (int ni = 0; ni < 4; ++ni)
;       epi(m0 + wm * 128 + mi * 16 + l15, n0 + wn * 64 + ni * 16 + quad * 4, acc[mi][ni]);
;   DEVI void operator()(int m, int n, f32x4 v) const {
;     if (m >= L) return;
;     float* h = hfrow(p, m) + n;
;     const float* src = (first && m >= 16) ? p.in[0] + (size_t)(m - 16) * 1024 + n : h;
;     f32x4 o = *(const f32x4*)src;
;     o = o * ALPHA + v;
;     *(f32x4*)h = o;
;   }
	v_mfma_f32_16x16x32_bf16 v[10:13], v[10:13], v[58:61], v[138:141]
	global_load_dwordx4 v[180:183], v[50:51], off offset:3072
	s_nop 1
	global_load_dwordx4 v[138:141], v[78:79], off offset:3072
	v_add_co_u32_e32 v78, vcc, 0x17000, v162
	v_mfma_f32_16x16x32_bf16 v[158:161], v[6:9], v[150:153], v[94:97]
	s_nop 0
	v_addc_co_u32_e32 v79, vcc, 0, v163, vcc
	v_mfma_f32_16x16x32_bf16 v[150:153], v[2:5], v[150:153], v[110:113]
	v_mfma_f32_16x16x32_bf16 v[134:137], v[14:17], v[58:61], v[134:137]
	ds_read_b128 v[14:17], v0 offset:32768
	v_mfma_f32_16x16x32_bf16 v[6:9], v[6:9], v[58:61], v[130:133]
	v_mfma_f32_16x16x32_bf16 v[2:5], v[2:5], v[58:61], v[126:129]
	v_add_co_u32_e32 v58, vcc, 0x1f000, v162
	s_nop 0
	global_load_dwordx4 v[130:133], v[78:79], off offset:3072
	v_addc_co_u32_e32 v59, vcc, 0, v163, vcc
	global_load_dwordx4 v[190:193], v[58:59], off offset:3072
	ds_read_b128 v[50:53], v0 offset:34816
	s_waitcnt vmcnt(2) lgkmcnt(1)
	v_mfma_f32_16x16x32_bf16 v[126:129], v[138:141], v[14:17], v[122:125]
	v_mfma_f32_16x16x32_bf16 v[122:125], v[180:183], v[14:17], v[118:121]
	s_waitcnt vmcnt(1)
	v_mfma_f32_16x16x32_bf16 v[118:121], v[130:133], v[14:17], v[114:117]
	s_waitcnt vmcnt(0)
	v_mfma_f32_16x16x32_bf16 v[114:117], v[190:193], v[14:17], v[106:109]
	s_waitcnt lgkmcnt(0)
	v_mfma_f32_16x16x32_bf16 v[110:113], v[138:141], v[50:53], v[102:105]
	v_mfma_f32_16x16x32_bf16 v[106:109], v[180:183], v[50:53], v[98:101]
	v_mfma_f32_16x16x32_bf16 v[102:105], v[130:133], v[50:53], v[82:85]
	v_mfma_f32_16x16x32_bf16 v[98:101], v[190:193], v[50:53], v[74:77]
	ds_read_b128 v[14:17], v0 offset:36864
	ds_read_b128 v[50:53], v0 offset:38912
	s_waitcnt lgkmcnt(1)
	v_mfma_f32_16x16x32_bf16 v[94:97], v[138:141], v[14:17], v[70:73]
	v_mfma_f32_16x16x32_bf16 v[90:93], v[180:183], v[14:17], v[66:69]
	v_mfma_f32_16x16x32_bf16 v[86:89], v[130:133], v[14:17], v[62:65]
	v_mfma_f32_16x16x32_bf16 v[82:85], v[190:193], v[14:17], v[54:57]
	s_waitcnt lgkmcnt(0)
	v_mfma_f32_16x16x32_bf16 v[66:69], v[190:193], v[50:53], v[26:29]
	ds_read_b128 v[14:17], v0 offset:40960
	s_nop 1
	ds_read_b128 v[26:29], v0 offset:43008
	v_mfma_f32_16x16x32_bf16 v[78:81], v[138:141], v[50:53], v[42:45]
	v_mfma_f32_16x16x32_bf16 v[74:77], v[180:183], v[50:53], v[30:33]
	v_mfma_f32_16x16x32_bf16 v[70:73], v[130:133], v[50:53], v[38:41]
	s_waitcnt lgkmcnt(1)
	v_mfma_f32_16x16x32_bf16 v[62:65], v[138:141], v[14:17], v[22:25]
	v_mfma_f32_16x16x32_bf16 v[58:61], v[180:183], v[14:17], v[18:21]
	v_mfma_f32_16x16x32_bf16 v[54:57], v[130:133], v[14:17], v[34:37]
	v_mfma_f32_16x16x32_bf16 v[50:53], v[190:193], v[14:17], v[46:49]
	s_waitcnt lgkmcnt(0)
	v_mfma_f32_16x16x32_bf16 v[46:49], v[138:141], v[26:29], v[146:149]
	ds_read_b128 v[14:17], v0 offset:45056
	s_nop 1
	ds_read_b128 v[146:149], v0 offset:47104
	v_and_b32_e32 v0, 0xffffff80, v168
	v_add_u32_e32 v0, s0, v0
	v_mfma_f32_16x16x32_bf16 v[42:45], v[180:183], v[26:29], v[154:157]
	s_movk_i32 s0, 0x4010
	s_waitcnt lgkmcnt(0)
	s_barrier
	v_mfma_f32_16x16x32_bf16 v[38:41], v[130:133], v[26:29], v[158:161]
	v_mfma_f32_16x16x32_bf16 v[34:37], v[190:193], v[26:29], v[150:153]
	v_mfma_f32_16x16x32_bf16 v[30:33], v[138:141], v[14:17], v[164:167]
	v_mfma_f32_16x16x32_bf16 v[26:29], v[180:183], v[14:17], v[172:175]
	v_mfma_f32_16x16x32_bf16 v[22:25], v[130:133], v[14:17], v[176:179]
	v_mfma_f32_16x16x32_bf16 v[18:21], v[190:193], v[14:17], v[142:145]
	v_mfma_f32_16x16x32_bf16 v[14:17], v[138:141], v[146:149], v[10:13]
	v_mfma_f32_16x16x32_bf16 v[10:13], v[180:183], v[146:149], v[134:137]
	v_mfma_f32_16x16x32_bf16 v[6:9], v[130:133], v[146:149], v[6:9]
	v_and_or_b32 v132, v168, 15, v0
	v_lshl_or_b32 v130, v169, 2, v170
	v_cmp_gt_i32_e32 vcc, s0, v132
	v_mfma_f32_16x16x32_bf16 v[2:5], v[190:193], v[146:149], v[2:5]
	v_ashrrev_i32_e32 v131, 31, v130
	s_and_saveexec_b64 s[0:1], vcc
	s_cbranch_execz .LBB0_327
	v_lshlrev_b32_e32 v134, 10, v132
	v_add_u32_e32 v136, -16, v132
	v_mov_b32_e32 v137, v1
	v_ashrrev_i32_e32 v135, 31, v134
	v_lshlrev_b64 v[136:137], 12, v[136:137]
	v_lshl_add_u64 v[134:135], v[134:135], 2, s[10:11]
	v_lshl_add_u64 v[136:137], s[26:27], 0, v[136:137]
	v_cmp_gt_i32_e32 vcc, 16, v132
	s_nop 1
	v_cndmask_b32_e32 v135, v137, v135, vcc
	v_cndmask_b32_e32 v134, v136, v134, vcc
	v_lshl_add_u64 v[138:139], v[130:131], 2, v[134:135]
	global_load_dwordx4 v[134:137], v[138:139], off
	s_waitcnt vmcnt(0)
	v_pk_fma_f32 v[128:129], v[136:137], s[66:67], v[128:129] op_sel_hi:[1,0,1]
	v_pk_fma_f32 v[126:127], v[134:135], s[66:67], v[126:127] op_sel_hi:[1,0,1]
	global_store_dwordx4 v[138:139], v[126:129], off
	global_load_dwordx4 v[126:129], v[138:139], off offset:64
	s_waitcnt vmcnt(0)
	v_pk_fma_f32 v[124:125], v[128:129], s[66:67], v[124:125] op_sel_hi:[1,0,1]
	v_pk_fma_f32 v[122:123], v[126:127], s[66:67], v[122:123] op_sel_hi:[1,0,1]
	global_store_dwordx4 v[138:139], v[122:125], off offset:64
	global_load_dwordx4 v[122:125], v[138:139], off offset:128
	s_waitcnt vmcnt(0)
	v_pk_fma_f32 v[120:121], v[124:125], s[66:67], v[120:121] op_sel_hi:[1,0,1]
	v_pk_fma_f32 v[118:119], v[122:123], s[66:67], v[118:119] op_sel_hi:[1,0,1]
	global_store_dwordx4 v[138:139], v[118:121], off offset:128
	global_load_dwordx4 v[118:121], v[138:139], off offset:192
	s_waitcnt vmcnt(0)
	v_pk_fma_f32 v[116:117], v[120:121], s[66:67], v[116:117] op_sel_hi:[1,0,1]
	v_pk_fma_f32 v[114:115], v[118:119], s[66:67], v[114:115] op_sel_hi:[1,0,1]
	global_store_dwordx4 v[138:139], v[114:117], off offset:192

; #define TIDX opaque_tid()
; template <class Epi>
; DEVI void gemm_tile256b(const bf16_t* __restrict__ A, int lda, const bf16_t* __restrict__ Bt, int K,
;                         int m0, int n0, char* smem, Epi epi) {
;   const int tid = TIDX, lane = tid & 63, wave = tid >> 6;
;   const int wm = wave >> 1, wn = wave & 1, l15 = lane & 15, quad = lane >> 4;
;   f32x4 acc[8][4];
; #pragma unroll
;   for (int i = 0; i < 8; ++i)
; #pragma unroll
;     for (int j = 0; j < 4; ++j) acc[i][j] = f32x4{0.f, 0.f, 0.f, 0.f};
;   const int lrow = tid >> 3, lkc = tid & 7;
;   const bf16_t* ag = A + (size_t)(m0 + lrow) * lda + lkc * 8;
;   const int kb32 = K >> 5;
;   const bf16_t* bp = Bt + ((size_t)((n0 + wn * 64) >> 4) * kb32) * 512 + lane * 8;
;   u32x4 ra[8];
;   bf16x8 b0[4], b1[4];
;   const int lds_w = lrow * 128 + ((lkc ^ (lrow & 7)) << 4);
;   const int nk = K >> 6;
;   const int sw = (quad ^ (l15 & 7)) << 4;
;   const int a_rd = (wm * 128 + l15) * 128 + sw;
; #pragma unroll
;   for (int i = 0; i < 8; ++i) ra[i] = *(const u32x4*)(ag + (size_t)(i * 32) * lda);
; #pragma unroll
;   for (int i = 0; i < 4; ++i) b0[i] = *(const bf16x8*)(bp + ((size_t)i * kb32) * 512);
; #pragma unroll
;   for (int i = 0; i < 8; ++i) *(u32x4*)(smem + lds_w + i * 4096) = ra[i];
;   __syncthreads();
;   for (int kt = 0; kt < nk; ++kt) {
.LBB0_361:
	s_andn2_b64 vcc, exec, s[0:1]
	s_cbranch_vccnz .LBB0_356
	s_ashr_i32 s0, s13, 31
	s_lshr_b32 s0, s0, 29
	s_add_i32 s0, s13, s0
	s_ashr_i32 s1, s0, 3
	v_mov_b32_e32 v0, v206
	s_lshl_b32 s0, s1, 8
	s_lshl_b32 s1, s1, 10
	v_ashrrev_i32_e32 v7, 3, v0
	v_add_u32_e32 v2, s0, v7
	s_lshl_b32 s13, s13, 7
	v_ashrrev_i32_e32 v3, 31, v2
	s_sub_i32 s1, s13, s1
	v_lshlrev_b64 v[50:51], 11, v[2:3]
	v_lshlrev_b32_e32 v4, 4, v0
	v_lshl_add_u64 v[2:3], s[14:15], 0, v[50:51]
	v_and_b32_e32 v4, 0x70, v4
	v_mov_b32_e32 v5, v1
	v_and_or_b32 v169, v0, 64, s1
	v_lshl_add_u64 v[2:3], v[2:3], 0, v[4:5]
	v_ashrrev_i32_e32 v4, 4, v169
	v_ashrrev_i32_e32 v5, 31, v4
	v_lshlrev_b64 v[52:53], 15, v[4:5]
	v_xor_b32_e32 v4, v7, v0
	v_bfe_u32 v168, v0, 4, 2
	v_lshlrev_b32_e32 v4, 4, v4
	v_and_b32_e32 v56, 0x70, v4
	v_bitop3_b32 v4, v168, v0, 7 bitop3:0x78
	v_lshlrev_b32_e32 v58, 4, v4
	v_lshlrev_b32_e32 v4, 7, v0
	v_and_b32_e32 v59, 0xffffc780, v4
	v_add_co_u32_e32 v4, vcc, s54, v2
	global_load_dwordx4 v[18:21], v[2:3], off
	s_nop 0
	v_addc_co_u32_e32 v5, vcc, 0, v3, vcc
	global_load_dwordx4 v[22:25], v[4:5], off
	v_add_co_u32_e32 v4, vcc, s53, v2
	v_and_b32_e32 v6, 63, v0
	s_nop 0
	v_addc_co_u32_e32 v5, vcc, 0, v3, vcc
	global_load_dwordx4 v[26:29], v[4:5], off
	v_add_co_u32_e32 v4, vcc, s52, v2
	v_lshlrev_b32_e32 v54, 4, v6
	s_nop 0
	v_addc_co_u32_e32 v5, vcc, 0, v3, vcc
	global_load_dwordx4 v[30:33], v[4:5], off
	v_add_co_u32_e32 v4, vcc, s56, v2
	v_mov_b32_e32 v55, v1
	s_nop 0
	v_addc_co_u32_e32 v5, vcc, 0, v3, vcc
	global_load_dwordx4 v[34:37], v[4:5], off
	v_add_co_u32_e32 v4, vcc, s57, v2
	s_mov_b32 s1, 0x8000
	s_nop 0
	v_addc_co_u32_e32 v5, vcc, 0, v3, vcc
	global_load_dwordx4 v[38:41], v[4:5], off
	v_add_co_u32_e32 v4, vcc, s3, v2
	s_mov_b32 s13, 0x18000
	s_nop 0
	v_addc_co_u32_e32 v5, vcc, 0, v3, vcc
	v_add_co_u32_e32 v2, vcc, s19, v2
	global_load_dwordx4 v[42:45], v[4:5], off
	s_nop 0
	v_addc_co_u32_e32 v3, vcc, 0, v3, vcc
	global_load_dwordx4 v[46:49], v[2:3], off
	v_lshl_add_u64 v[2:3], s[6:7], 0, v[52:53]
	v_lshl_add_u64 v[162:163], v[2:3], 0, v[54:55]
	v_add_co_u32_e32 v2, vcc, s1, v162
	global_load_dwordx4 v[10:13], v[162:163], off
	s_nop 0
	v_addc_co_u32_e32 v3, vcc, 0, v163, vcc
	global_load_dwordx4 v[14:17], v[2:3], off
	v_add_co_u32_e32 v2, vcc, s54, v162
	v_lshlrev_b32_e32 v55, 7, v7
	s_nop 0
	v_addc_co_u32_e32 v3, vcc, 0, v163, vcc
	v_add_co_u32_e32 v6, vcc, s13, v162
	global_load_dwordx4 v[2:5], v[2:3], off
	s_nop 0
	v_addc_co_u32_e32 v7, vcc, 0, v163, vcc
	global_load_dwordx4 v[6:9], v[6:7], off
	v_and_b32_e32 v57, 7, v0
	v_add3_u32 v171, 32, v56, v55
	v_or_b32_e32 v52, v52, v54
	v_lshl_or_b32 v50, v57, 4, v50
	v_mov_b32_e32 v78, 0
	v_or_b32_e32 v172, v58, v59
	v_bitop3_b32 v170, v58, 64, v59 bitop3:0x36
	v_lshl_add_u64 v[164:165], s[84:85], 0, v[52:53]
	v_lshl_add_u64 v[166:167], s[84:85], 0, v[50:51]
	v_mov_b32_e32 v79, v78
	v_mov_b32_e32 v80, v78
	s_waitcnt vmcnt(11)
	ds_write_b128 v171, v[18:21]
	s_waitcnt vmcnt(10)
	ds_write_b128 v171, v[22:25] offset:4096
	s_waitcnt vmcnt(9)
	ds_write_b128 v171, v[26:29] offset:8192
	s_waitcnt vmcnt(8)
	ds_write_b128 v171, v[30:33] offset:12288
	s_waitcnt vmcnt(7)
	ds_write_b128 v171, v[34:37] offset:16384
	s_waitcnt vmcnt(6)
	ds_write_b128 v171, v[38:41] offset:20480
	s_waitcnt vmcnt(5)
	ds_write_b128 v171, v[42:45] offset:24576
	s_waitcnt vmcnt(4)
	ds_write_b128 v171, v[46:49] offset:28672
	v_mov_b32_e32 v81, v78
	v_mov_b32_e32 v90, v78
	v_mov_b32_e32 v91, v78
	v_mov_b32_e32 v92, v78
	v_mov_b32_e32 v93, v78
	v_mov_b32_e32 v118, v78
	v_mov_b32_e32 v119, v78
	v_mov_b32_e32 v120, v78
	v_mov_b32_e32 v121, v78
	v_mov_b32_e32 v138, v78
	v_mov_b32_e32 v139, v78
	v_mov_b32_e32 v140, v78
	v_mov_b32_e32 v141, v78
	v_mov_b32_e32 v142, v78
	v_mov_b32_e32 v143, v78
	v_mov_b32_e32 v144, v78
	v_mov_b32_e32 v145, v78
	v_mov_b32_e32 v30, v78
	v_mov_b32_e32 v31, v78
	v_mov_b32_e32 v32, v78
	v_mov_b32_e32 v33, v78
	v_mov_b32_e32 v38, v78
	v_mov_b32_e32 v39, v78
	v_mov_b32_e32 v40, v78
	v_mov_b32_e32 v41, v78
	v_mov_b32_e32 v34, v78
	v_mov_b32_e32 v35, v78
	v_mov_b32_e32 v36, v78
	v_mov_b32_e32 v37, v78
	v_mov_b32_e32 v42, v78
	v_mov_b32_e32 v43, v78
	v_mov_b32_e32 v44, v78
	v_mov_b32_e32 v45, v78
	v_mov_b32_e32 v18, v78
	v_mov_b32_e32 v19, v78
	v_mov_b32_e32 v20, v78
	v_mov_b32_e32 v21, v78
	v_mov_b32_e32 v22, v78
	v_mov_b32_e32 v23, v78
	v_mov_b32_e32 v24, v78
	v_mov_b32_e32 v25, v78
	v_mov_b32_e32 v26, v78
	v_mov_b32_e32 v27, v78
	v_mov_b32_e32 v28, v78
	v_mov_b32_e32 v29, v78
	v_mov_b32_e32 v54, v78
	v_mov_b32_e32 v55, v78
	v_mov_b32_e32 v56, v78
	v_mov_b32_e32 v57, v78
	v_mov_b32_e32 v58, v78
	v_mov_b32_e32 v59, v78
	v_mov_b32_e32 v60, v78
	v_mov_b32_e32 v61, v78
	v_mov_b32_e32 v50, v78
	v_mov_b32_e32 v51, v78
	v_mov_b32_e32 v52, v78
	v_mov_b32_e32 v53, v78
	v_mov_b32_e32 v46, v78
	v_mov_b32_e32 v47, v78
	v_mov_b32_e32 v48, v78
	v_mov_b32_e32 v49, v78
	v_mov_b32_e32 v66, v78
	v_mov_b32_e32 v67, v78
	v_mov_b32_e32 v68, v78
	v_mov_b32_e32 v69, v78
	v_mov_b32_e32 v62, v78
	v_mov_b32_e32 v63, v78
	v_mov_b32_e32 v64, v78
	v_mov_b32_e32 v65, v78
	v_mov_b32_e32 v70, v78
	v_mov_b32_e32 v71, v78
	v_mov_b32_e32 v72, v78
	v_mov_b32_e32 v73, v78
	v_mov_b32_e32 v74, v78
	v_mov_b32_e32 v75, v78
	v_mov_b32_e32 v76, v78
	v_mov_b32_e32 v77, v78
	v_mov_b32_e32 v82, v78
	v_mov_b32_e32 v83, v78
	v_mov_b32_e32 v84, v78
	v_mov_b32_e32 v85, v78
	v_mov_b32_e32 v86, v78
	v_mov_b32_e32 v87, v78
	v_mov_b32_e32 v88, v78
	v_mov_b32_e32 v89, v78
	v_mov_b32_e32 v94, v78
	v_mov_b32_e32 v95, v78
	v_mov_b32_e32 v96, v78
	v_mov_b32_e32 v97, v78
	v_mov_b32_e32 v98, v78
	v_mov_b32_e32 v99, v78
	v_mov_b32_e32 v100, v78
	v_mov_b32_e32 v101, v78
	v_mov_b32_e32 v102, v78
	v_mov_b32_e32 v103, v78
	v_mov_b32_e32 v104, v78
	v_mov_b32_e32 v105, v78
	v_mov_b32_e32 v106, v78
	v_mov_b32_e32 v107, v78
	v_mov_b32_e32 v108, v78
	v_mov_b32_e32 v109, v78
	v_mov_b32_e32 v110, v78
	v_mov_b32_e32 v111, v78
	v_mov_b32_e32 v112, v78
	v_mov_b32_e32 v113, v78
	v_mov_b32_e32 v114, v78
	v_mov_b32_e32 v115, v78
	v_mov_b32_e32 v116, v78
	v_mov_b32_e32 v117, v78
	v_mov_b32_e32 v122, v78
	v_mov_b32_e32 v123, v78
	v_mov_b32_e32 v124, v78
	v_mov_b32_e32 v125, v78
	v_mov_b32_e32 v126, v78
	v_mov_b32_e32 v127, v78
	v_mov_b32_e32 v128, v78
	v_mov_b32_e32 v129, v78
	v_mov_b32_e32 v130, v78
	v_mov_b32_e32 v131, v78
	v_mov_b32_e32 v132, v78
	v_mov_b32_e32 v133, v78
	v_mov_b32_e32 v134, v78
	v_mov_b32_e32 v135, v78
	v_mov_b32_e32 v136, v78
	v_mov_b32_e32 v137, v78
	s_waitcnt lgkmcnt(0)
	s_barrier
	s_add_i32 s98, s1, 0xffff8000
	s_and_b32 s98, s98, 0x8000
	s_add_i32 s98, s98, 32
	v_add_u32_e32 v226, s98, v172
	ds_read_b128 v[196:199], v226
	ds_read_b128 v[200:203], v226 offset:2048
; #define MFMA16(a, b, c) __builtin_amdgcn_mfma_f32_16x16x32_bf16((a), (b), (c), 0, 0, 0)
; template <class Epi>
; DEVI void gemm_tile256b(const bf16_t* __restrict__ A, int lda, const bf16_t* __restrict__ Bt, int K,
;                         int m0, int n0, char* smem, Epi epi) {
;     ...
;   for (int kt = 0; kt < nk; ++kt) {
;     const char* base = smem + (kt & 1) * 32768;
;     const bool more = kt + 1 < nk;
;     if (more) {
; #pragma unroll
;       for (int i = 0; i < 8; ++i) ra[i] = *(const u32x4*)(ag + (size_t)(i * 32) * lda + (kt + 1) * 64);
;     }
; #pragma unroll
;     for (int i = 0; i < 4; ++i) b1[i] = *(const bf16x8*)(bp + ((size_t)i * kb32 + kt * 2 + 1) * 512);
;     {
;       bf16x8 af[8];
; #pragma unroll
;       for (int i = 0; i < 8; ++i) af[i] = *(const bf16x8*)(base + a_rd + i * 2048);
; #pragma unroll
;       for (int mi = 0; mi < 8; ++mi)
; #pragma unroll
;         for (int ni = 0; ni < 4; ++ni) acc[mi][ni] = MFMA16(b0[ni], af[mi], acc[mi][ni]);
;     }
;     if (more) {
; #pragma unroll
;       for (int i = 0; i < 4; ++i) b0[i] = *(const bf16x8*)(bp + ((size_t)i * kb32 + kt * 2 + 2) * 512);
;     }
;     {
;       bf16x8 af[8];
; #pragma unroll
;       for (int i = 0; i < 8; ++i) af[i] = *(const bf16x8*)(base + ((a_rd + i * 2048) ^ 64));
; #pragma unroll
;       for (int mi = 0; mi < 8; ++mi)
; #pragma unroll
;         for (int ni = 0; ni < 4; ++ni) acc[mi][ni] = MFMA16(b1[ni], af[mi], acc[mi][ni]);
;     }
;     if (more) {
;       char* nb = smem + ((kt + 1) & 1) * 32768 + lds_w;
; #pragma unroll
;       for (int i = 0; i < 8; ++i) *(u32x4*)(nb + i * 4096) = ra[i];
;     }
.LBB0_363:
	s_add_i32 s13, s1, 0xffff8000
	s_and_b32 s13, s13, 0x8000
	s_add_i32 s13, s13, 32
	v_add_u32_e32 v154, s13, v172
	s_mov_b32 s16, 0x2680000
	v_add_u32_e32 v173, s13, v170
	s_waitcnt vmcnt(3) lgkmcnt(1)
	v_mfma_f32_16x16x32_bf16 v[134:137], v[10:13], v[196:199], v[134:137]
	s_and_b32 s13, s1, 0x8000
	s_add_i32 s1, s1, 0x8000
	v_lshl_add_u64 v[166:167], v[166:167], 0, s[60:61]
	s_waitcnt vmcnt(2)
	v_mfma_f32_16x16x32_bf16 v[130:133], v[14:17], v[196:199], v[130:133]
	s_cmp_eq_u32 s1, 0x80000
	s_waitcnt vmcnt(1)
	v_mfma_f32_16x16x32_bf16 v[126:129], v[2:5], v[196:199], v[126:129]
	s_waitcnt vmcnt(0)
	v_mfma_f32_16x16x32_bf16 v[122:125], v[6:9], v[196:199], v[122:125]
	s_waitcnt lgkmcnt(0)
	v_mfma_f32_16x16x32_bf16 v[114:117], v[10:13], v[200:203], v[114:117]
	v_mfma_f32_16x16x32_bf16 v[110:113], v[14:17], v[200:203], v[110:113]
	v_mfma_f32_16x16x32_bf16 v[106:109], v[2:5], v[200:203], v[106:109]
	v_mfma_f32_16x16x32_bf16 v[102:105], v[6:9], v[200:203], v[102:105]
	ds_read_b128 v[146:149], v154 offset:4096
	ds_read_b128 v[150:153], v154 offset:6144
	s_waitcnt lgkmcnt(1)
	v_mfma_f32_16x16x32_bf16 v[98:101], v[10:13], v[146:149], v[98:101]
	v_mfma_f32_16x16x32_bf16 v[94:97], v[14:17], v[146:149], v[94:97]
	v_mfma_f32_16x16x32_bf16 v[86:89], v[2:5], v[146:149], v[86:89]
	v_mfma_f32_16x16x32_bf16 v[82:85], v[6:9], v[146:149], v[82:85]
	s_waitcnt lgkmcnt(0)
	v_mfma_f32_16x16x32_bf16 v[74:77], v[10:13], v[150:153], v[74:77]
	v_mfma_f32_16x16x32_bf16 v[70:73], v[14:17], v[150:153], v[70:73]
	v_mfma_f32_16x16x32_bf16 v[62:65], v[2:5], v[150:153], v[62:65]
	v_mfma_f32_16x16x32_bf16 v[66:69], v[6:9], v[150:153], v[66:69]
	ds_read_b128 v[146:149], v154 offset:8192
	ds_read_b128 v[150:153], v154 offset:10240
	s_waitcnt lgkmcnt(1)
	v_mfma_f32_16x16x32_bf16 v[46:49], v[10:13], v[146:149], v[46:49]
	v_mfma_f32_16x16x32_bf16 v[50:53], v[14:17], v[146:149], v[50:53]
	v_mfma_f32_16x16x32_bf16 v[58:61], v[2:5], v[146:149], v[58:61]
	v_mfma_f32_16x16x32_bf16 v[54:57], v[6:9], v[146:149], v[54:57]
	s_waitcnt lgkmcnt(0)
	v_mfma_f32_16x16x32_bf16 v[26:29], v[10:13], v[150:153], v[26:29]
	v_mfma_f32_16x16x32_bf16 v[22:25], v[14:17], v[150:153], v[22:25]
	v_mfma_f32_16x16x32_bf16 v[18:21], v[2:5], v[150:153], v[18:21]
	v_mfma_f32_16x16x32_bf16 v[42:45], v[6:9], v[150:153], v[42:45]
	ds_read_b128 v[146:149], v154 offset:12288
	ds_read_b128 v[150:153], v154 offset:14336
	v_lshl_add_u64 v[154:155], v[164:165], 0, s[28:29]
	v_add_co_u32_e32 v156, vcc, s16, v154
	s_mov_b32 s16, 0x2688000
	s_nop 0
	v_addc_co_u32_e32 v157, vcc, 0, v155, vcc
	v_add_co_u32_e32 v158, vcc, s16, v154
	s_waitcnt lgkmcnt(1)
	v_mfma_f32_16x16x32_bf16 v[34:37], v[10:13], v[146:149], v[34:37]
	v_addc_co_u32_e32 v159, vcc, 0, v155, vcc
	s_mov_b32 s16, 0x2690000
	v_mfma_f32_16x16x32_bf16 v[38:41], v[14:17], v[146:149], v[38:41]
	v_add_co_u32_e32 v160, vcc, s16, v154
	s_mov_b32 s16, 0x2698000
	v_mfma_f32_16x16x32_bf16 v[30:33], v[2:5], v[146:149], v[30:33]
	v_addc_co_u32_e32 v161, vcc, 0, v155, vcc
	v_add_co_u32_e32 v182, vcc, s16, v154
	v_mfma_f32_16x16x32_bf16 v[142:145], v[6:9], v[146:149], v[142:145]
	global_load_dwordx4 v[146:149], v[156:157], off offset:1024
	v_addc_co_u32_e32 v183, vcc, 0, v155, vcc
	s_waitcnt lgkmcnt(0)
	v_mfma_f32_16x16x32_bf16 v[138:141], v[10:13], v[150:153], v[138:141]
	ds_read_b128 v[174:177], v173
	ds_read_b128 v[178:181], v173 offset:2048
	global_load_dwordx4 v[10:13], v[156:157], off offset:2048
	v_mfma_f32_16x16x32_bf16 v[118:121], v[14:17], v[150:153], v[118:121]
	s_nop 0
	v_mfma_f32_16x16x32_bf16 v[90:93], v[2:5], v[150:153], v[90:93]
	s_nop 0
	v_mfma_f32_16x16x32_bf16 v[78:81], v[6:9], v[150:153], v[78:81]
	global_load_dwordx4 v[150:153], v[158:159], off offset:1024
	global_load_dwordx4 v[14:17], v[158:159], off offset:2048
	global_load_dwordx4 v[154:157], v[160:161], off offset:1024
	global_load_dwordx4 v[2:5], v[160:161], off offset:2048
	s_nop 0
	global_load_dwordx4 v[158:161], v[182:183], off offset:1024
	global_load_dwordx4 v[6:9], v[182:183], off offset:2048
	v_lshrrev_b32_e32 v195, 6, v206
	v_lshl_add_u64 v[190:191], v[166:167], 0, s[28:29]
	v_lshrrev_b32_e32 v194, 3, v206
	v_readfirstlane_b32 s99, v195
	v_and_b32_e32 v194, 7, v194
	s_and_b32 s98, s1, 0x8000
	s_xor_b32 s98, s98, 0x8000
	v_lshlrev_b32_e32 v194, 4, v194
	s_lshl_b32 s99, s99, 10
	v_xor_b32_e32 v190, v194, v190
	s_add_u32 s98, s98, s99
	s_add_u32 s98, s98, 32
	s_mov_b32 s101, 0
	s_mov_b32 s100, 0x0
	v_lshl_add_u64 v[192:193], v[190:191], 0, s[100:101]
	s_mov_b32 m0, s98
	s_nop 0
	global_load_lds_dwordx4 v[192:193], off
	s_add_u32 s100, s54, 0x0
	v_lshl_add_u64 v[192:193], v[190:191], 0, s[100:101]
	s_add_u32 m0, s98, 0x1000
	s_nop 0
	global_load_lds_dwordx4 v[192:193], off
	s_add_u32 s100, s53, 0x0
	v_lshl_add_u64 v[192:193], v[190:191], 0, s[100:101]
	s_add_u32 m0, s98, 0x2000
	s_nop 0
	global_load_lds_dwordx4 v[192:193], off
	s_add_u32 s100, s52, 0x0
	v_lshl_add_u64 v[192:193], v[190:191], 0, s[100:101]
	s_add_u32 m0, s98, 0x3000
	s_nop 0
	global_load_lds_dwordx4 v[192:193], off
	s_add_u32 s100, s56, 0x0
	v_lshl_add_u64 v[192:193], v[190:191], 0, s[100:101]
	s_add_u32 m0, s98, 0x4000
	s_nop 0
	global_load_lds_dwordx4 v[192:193], off
	s_add_u32 s100, s57, 0x0
	v_lshl_add_u64 v[192:193], v[190:191], 0, s[100:101]
	s_add_u32 m0, s98, 0x5000
	s_nop 0
	global_load_lds_dwordx4 v[192:193], off
	s_add_u32 s100, s3, 0x0
	v_lshl_add_u64 v[192:193], v[190:191], 0, s[100:101]
	s_add_u32 m0, s98, 0x6000
	s_nop 0
	global_load_lds_dwordx4 v[192:193], off
	s_add_u32 s100, s19, 0x0
	v_lshl_add_u64 v[192:193], v[190:191], 0, s[100:101]
	s_add_u32 m0, s98, 0x7000
	s_nop 0
	global_load_lds_dwordx4 v[192:193], off
	s_waitcnt vmcnt(15) lgkmcnt(1)
; #define MFMA16(a, b, c) __builtin_amdgcn_mfma_f32_16x16x32_bf16((a), (b), (c), 0, 0, 0)
; template <class Epi>
; DEVI void gemm_tile256b(const bf16_t* __restrict__ A, int lda, const bf16_t* __restrict__ Bt, int K,
;                         int m0, int n0, char* smem, Epi epi) {
;     ...
;     if (more) {
; #pragma unroll
;       for (int i = 0; i < 4; ++i) b0[i] = *(const bf16x8*)(bp + ((size_t)i * kb32 + kt * 2 + 2) * 512);
;     }
;     {
;       bf16x8 af[8];
; #pragma unroll
;       for (int i = 0; i < 8; ++i) af[i] = *(const bf16x8*)(base + ((a_rd + i * 2048) ^ 64));
; #pragma unroll
;       for (int mi = 0; mi < 8; ++mi)
; #pragma unroll
;         for (int ni = 0; ni < 4; ++ni) acc[mi][ni] = MFMA16(b1[ni], af[mi], acc[mi][ni]);
;     }
;     if (more) {
;       char* nb = smem + ((kt + 1) & 1) * 32768 + lds_w;
; #pragma unroll
;       for (int i = 0; i < 8; ++i) *(u32x4*)(nb + i * 4096) = ra[i];
;     }
;     __syncthreads();
;   }
	v_mfma_f32_16x16x32_bf16 v[134:137], v[146:149], v[174:177], v[134:137]
	s_waitcnt vmcnt(13)
	v_mfma_f32_16x16x32_bf16 v[130:133], v[150:153], v[174:177], v[130:133]
	s_waitcnt vmcnt(11)
	v_mfma_f32_16x16x32_bf16 v[126:129], v[154:157], v[174:177], v[126:129]
	s_waitcnt vmcnt(9)
	v_mfma_f32_16x16x32_bf16 v[122:125], v[158:161], v[174:177], v[122:125]
	s_waitcnt lgkmcnt(0)
	v_mfma_f32_16x16x32_bf16 v[114:117], v[146:149], v[178:181], v[114:117]
	v_lshl_add_u64 v[164:165], v[164:165], 0, s[64:65]
	v_mfma_f32_16x16x32_bf16 v[110:113], v[150:153], v[178:181], v[110:113]
	v_mfma_f32_16x16x32_bf16 v[106:109], v[154:157], v[178:181], v[106:109]
	v_mfma_f32_16x16x32_bf16 v[102:105], v[158:161], v[178:181], v[102:105]
	ds_read_b128 v[174:177], v173 offset:4096
	ds_read_b128 v[178:181], v173 offset:6144
	s_waitcnt lgkmcnt(1)
	v_mfma_f32_16x16x32_bf16 v[98:101], v[146:149], v[174:177], v[98:101]
	v_mfma_f32_16x16x32_bf16 v[94:97], v[150:153], v[174:177], v[94:97]
	v_mfma_f32_16x16x32_bf16 v[86:89], v[154:157], v[174:177], v[86:89]
	v_mfma_f32_16x16x32_bf16 v[82:85], v[158:161], v[174:177], v[82:85]
	s_waitcnt lgkmcnt(0)
	v_mfma_f32_16x16x32_bf16 v[74:77], v[146:149], v[178:181], v[74:77]
	v_mfma_f32_16x16x32_bf16 v[70:73], v[150:153], v[178:181], v[70:73]
	v_mfma_f32_16x16x32_bf16 v[62:65], v[154:157], v[178:181], v[62:65]
	v_mfma_f32_16x16x32_bf16 v[66:69], v[158:161], v[178:181], v[66:69]
	ds_read_b128 v[178:181], v173 offset:8192
	ds_read_b128 v[182:185], v173 offset:10240
	s_waitcnt lgkmcnt(1)
	v_mfma_f32_16x16x32_bf16 v[46:49], v[146:149], v[178:181], v[46:49]
	v_mfma_f32_16x16x32_bf16 v[50:53], v[150:153], v[178:181], v[50:53]
	v_mfma_f32_16x16x32_bf16 v[58:61], v[154:157], v[178:181], v[58:61]
	v_mfma_f32_16x16x32_bf16 v[54:57], v[158:161], v[178:181], v[54:57]
	s_waitcnt lgkmcnt(0)
	v_mfma_f32_16x16x32_bf16 v[26:29], v[146:149], v[182:185], v[26:29]
	v_mfma_f32_16x16x32_bf16 v[22:25], v[150:153], v[182:185], v[22:25]
	v_mfma_f32_16x16x32_bf16 v[18:21], v[154:157], v[182:185], v[18:21]
	v_mfma_f32_16x16x32_bf16 v[42:45], v[158:161], v[182:185], v[42:45]
	ds_read_b128 v[178:181], v173 offset:12288
	ds_read_b128 v[182:185], v173 offset:14336
	s_nop 0
	s_nop 0
	s_nop 0
	s_nop 0
	s_nop 0
	s_waitcnt lgkmcnt(1)
	v_mfma_f32_16x16x32_bf16 v[34:37], v[146:149], v[178:181], v[34:37]
	v_mfma_f32_16x16x32_bf16 v[38:41], v[150:153], v[178:181], v[38:41]
	v_mfma_f32_16x16x32_bf16 v[30:33], v[154:157], v[178:181], v[30:33]
	s_waitcnt vmcnt(0) lgkmcnt(0)
	s_barrier
	s_add_i32 s98, s1, 0xffff8000
	s_and_b32 s98, s98, 0x8000
	s_add_i32 s98, s98, 32
	v_add_u32_e32 v226, s98, v172
	ds_read_b128 v[196:199], v226
	ds_read_b128 v[200:203], v226 offset:2048
	v_mfma_f32_16x16x32_bf16 v[142:145], v[158:161], v[178:181], v[142:145]
	v_mfma_f32_16x16x32_bf16 v[138:141], v[146:149], v[182:185], v[138:141]
	v_mfma_f32_16x16x32_bf16 v[118:121], v[150:153], v[182:185], v[118:121]
	v_mfma_f32_16x16x32_bf16 v[90:93], v[154:157], v[182:185], v[90:93]
	v_mfma_f32_16x16x32_bf16 v[78:81], v[158:161], v[182:185], v[78:81]
	s_cmp_eq_u32 s1, 0x80000
	s_cbranch_scc0 .LBB0_363
	v_add_u32_e32 v171, 32, v172
	ds_read_b128 v[146:149], v171 offset:32768
	s_movk_i32 s1, 0x7000
	v_add_u32_e32 v170, 32, v170
	s_waitcnt lgkmcnt(0)
	v_mfma_f32_16x16x32_bf16 v[134:137], v[10:13], v[146:149], v[134:137]
	v_mfma_f32_16x16x32_bf16 v[130:133], v[14:17], v[146:149], v[130:133]
	v_mfma_f32_16x16x32_bf16 v[126:129], v[2:5], v[146:149], v[126:129]
	v_mfma_f32_16x16x32_bf16 v[122:125], v[6:9], v[146:149], v[122:125]
	ds_read_b128 v[146:149], v171 offset:34816
	s_waitcnt lgkmcnt(0)
	v_mfma_f32_16x16x32_bf16 v[114:117], v[10:13], v[146:149], v[114:117]
	v_mfma_f32_16x16x32_bf16 v[150:153], v[14:17], v[146:149], v[110:113]
	v_mfma_f32_16x16x32_bf16 v[154:157], v[2:5], v[146:149], v[106:109]
	v_mfma_f32_16x16x32_bf16 v[146:149], v[6:9], v[146:149], v[102:105]
	s_nop 2
	ds_read_b128 v[102:105], v171 offset:36864
	s_waitcnt lgkmcnt(0)
	v_mfma_f32_16x16x32_bf16 v[164:167], v[14:17], v[102:105], v[94:97]
	s_nop 2
	ds_read_b128 v[94:97], v171 offset:38912
	s_waitcnt lgkmcnt(0)
	v_mfma_f32_16x16x32_bf16 v[74:77], v[10:13], v[94:97], v[74:77]
	v_mfma_f32_16x16x32_bf16 v[70:73], v[14:17], v[94:97], v[70:73]
	v_mfma_f32_16x16x32_bf16 v[62:65], v[2:5], v[94:97], v[62:65]
	v_mfma_f32_16x16x32_bf16 v[66:69], v[6:9], v[94:97], v[66:69]
	ds_read_b128 v[94:97], v171 offset:40960
	s_waitcnt lgkmcnt(0)
	v_mfma_f32_16x16x32_bf16 v[176:179], v[6:9], v[94:97], v[54:57]
	s_nop 2
	ds_read_b128 v[54:57], v171 offset:43008
	s_waitcnt lgkmcnt(0)
	v_mfma_f32_16x16x32_bf16 v[180:183], v[6:9], v[54:57], v[42:45]
	s_nop 2
	ds_read_b128 v[42:45], v171 offset:45056
	s_waitcnt lgkmcnt(0)
	v_mfma_f32_16x16x32_bf16 v[198:201], v[2:5], v[42:45], v[30:33]
	s_nop 2
	ds_read_b128 v[30:33], v171 offset:47104
	v_mfma_f32_16x16x32_bf16 v[158:161], v[10:13], v[102:105], v[98:101]
	v_mfma_f32_16x16x32_bf16 v[46:49], v[10:13], v[94:97], v[46:49]
	v_mfma_f32_16x16x32_bf16 v[50:53], v[14:17], v[94:97], v[50:53]
	v_mfma_f32_16x16x32_bf16 v[26:29], v[10:13], v[54:57], v[26:29]
	v_mfma_f32_16x16x32_bf16 v[22:25], v[14:17], v[54:57], v[22:25]
	v_mfma_f32_16x16x32_bf16 v[190:193], v[10:13], v[42:45], v[34:37]
	v_mfma_f32_16x16x32_bf16 v[194:197], v[14:17], v[42:45], v[38:41]
	s_waitcnt lgkmcnt(0)
; #define MFMA16(a, b, c) __builtin_amdgcn_mfma_f32_16x16x32_bf16((a), (b), (c), 0, 0, 0)
; template <class Epi>
; DEVI void gemm_tile256b(const bf16_t* __restrict__ A, int lda, const bf16_t* __restrict__ Bt, int K,
;                         int m0, int n0, char* smem, Epi epi) {
;     ...
;     {
;       bf16x8 af[8];
; #pragma unroll
;       for (int i = 0; i < 8; ++i) af[i] = *(const bf16x8*)(base + ((a_rd + i * 2048) ^ 64));
; #pragma unroll
;       for (int mi = 0; mi < 8; ++mi)
; #pragma unroll
;         for (int ni = 0; ni < 4; ++ni) acc[mi][ni] = MFMA16(b1[ni], af[mi], acc[mi][ni]);
;     }
;     if (more) {
;       char* nb = smem + ((kt + 1) & 1) * 32768 + lds_w;
; #pragma unroll
;       for (int i = 0; i < 8; ++i) *(u32x4*)(nb + i * 4096) = ra[i];
;     }
;     __syncthreads();
;   }
; #pragma unroll
;   for (int mi = 0; mi < 8; ++mi)
; #pragma unroll
;     for (int ni = 0; ni < 4; ++ni)
;       epi(m0 + wm * 128 + mi * 16 + l15, n0 + wn * 64 + ni * 16 + quad * 4, acc[mi][ni]);
;   DEVI void operator()(int m, int n, f32x4 v) const {
;     if (m >= L) return;
;     *(u32x2*)(z + (size_t)m * 1024 + n) = u32x2{pack2(v[0], v[1]), pack2(v[2], v[3])};
;   }
	v_mfma_f32_16x16x32_bf16 v[10:13], v[10:13], v[30:33], v[138:141]
	v_mfma_f32_16x16x32_bf16 v[138:141], v[14:17], v[30:33], v[118:121]
	v_add_co_u32_e32 v14, vcc, s1, v162
	s_mov_b32 s1, 0xf000
	s_nop 0
	v_addc_co_u32_e32 v15, vcc, 0, v163, vcc
	global_load_dwordx4 v[14:17], v[14:15], off offset:3072
	v_mfma_f32_16x16x32_bf16 v[82:85], v[6:9], v[102:105], v[82:85]
	v_add_co_u32_e32 v34, vcc, s1, v162
	s_mov_b32 s1, 0x17000
	v_mfma_f32_16x16x32_bf16 v[142:145], v[6:9], v[42:45], v[142:145]
	v_addc_co_u32_e32 v35, vcc, 0, v163, vcc
	global_load_dwordx4 v[202:205], v[34:35], off offset:3072
	v_mfma_f32_16x16x32_bf16 v[226:229], v[6:9], v[30:33], v[78:81]
	ds_read_b128 v[6:9], v170 offset:32768
	v_mfma_f32_16x16x32_bf16 v[86:89], v[2:5], v[102:105], v[86:89]
	v_mfma_f32_16x16x32_bf16 v[172:175], v[2:5], v[94:97], v[58:61]
	v_mfma_f32_16x16x32_bf16 v[18:21], v[2:5], v[54:57], v[18:21]
	v_mfma_f32_16x16x32_bf16 v[2:5], v[2:5], v[30:33], v[90:93]
	v_add_co_u32_e32 v30, vcc, s1, v162
	s_mov_b32 s1, 0x1f000
	s_nop 0
	v_addc_co_u32_e32 v31, vcc, 0, v163, vcc
	s_waitcnt vmcnt(1) lgkmcnt(0)
	v_mfma_f32_16x16x32_bf16 v[110:113], v[14:17], v[6:9], v[134:137]
	s_nop 2
	global_load_dwordx4 v[134:137], v[30:31], off offset:3072
	v_add_co_u32_e32 v30, vcc, s1, v162
	s_waitcnt vmcnt(1)
	v_mfma_f32_16x16x32_bf16 v[106:109], v[202:205], v[6:9], v[130:133]
	v_addc_co_u32_e32 v31, vcc, 0, v163, vcc
	global_load_dwordx4 v[230:233], v[30:31], off offset:3072
	s_waitcnt vmcnt(1)
	v_mfma_f32_16x16x32_bf16 v[102:105], v[134:137], v[6:9], v[126:129]
	v_lshl_or_b32 v130, v168, 2, v169
	v_ashrrev_i32_e32 v131, 31, v130
	s_waitcnt vmcnt(0)
	v_mfma_f32_16x16x32_bf16 v[98:101], v[230:233], v[6:9], v[122:125]
	ds_read_b128 v[6:9], v170 offset:34816
	s_waitcnt lgkmcnt(0)
	v_mfma_f32_16x16x32_bf16 v[126:129], v[14:17], v[6:9], v[114:117]
	v_mfma_f32_16x16x32_bf16 v[122:125], v[202:205], v[6:9], v[150:153]
	v_mfma_f32_16x16x32_bf16 v[118:121], v[134:137], v[6:9], v[154:157]
	v_mfma_f32_16x16x32_bf16 v[114:117], v[230:233], v[6:9], v[146:149]
	ds_read_b128 v[6:9], v170 offset:36864
	s_waitcnt lgkmcnt(0)
	v_mfma_f32_16x16x32_bf16 v[94:97], v[14:17], v[6:9], v[158:161]
	v_mfma_f32_16x16x32_bf16 v[90:93], v[202:205], v[6:9], v[164:167]
	v_mfma_f32_16x16x32_bf16 v[86:89], v[134:137], v[6:9], v[86:89]
	v_mfma_f32_16x16x32_bf16 v[82:85], v[230:233], v[6:9], v[82:85]
	ds_read_b128 v[6:9], v170 offset:38912
	s_waitcnt lgkmcnt(0)
	v_mfma_f32_16x16x32_bf16 v[78:81], v[14:17], v[6:9], v[74:77]
	v_mfma_f32_16x16x32_bf16 v[74:77], v[202:205], v[6:9], v[70:73]
	v_mfma_f32_16x16x32_bf16 v[70:73], v[134:137], v[6:9], v[62:65]
	v_mfma_f32_16x16x32_bf16 v[66:69], v[230:233], v[6:9], v[66:69]
	ds_read_b128 v[6:9], v170 offset:40960
	s_waitcnt lgkmcnt(0)
	v_mfma_f32_16x16x32_bf16 v[62:65], v[14:17], v[6:9], v[46:49]
	v_mfma_f32_16x16x32_bf16 v[58:61], v[202:205], v[6:9], v[50:53]
	v_mfma_f32_16x16x32_bf16 v[54:57], v[134:137], v[6:9], v[172:175]
	v_mfma_f32_16x16x32_bf16 v[50:53], v[230:233], v[6:9], v[176:179]
	ds_read_b128 v[6:9], v170 offset:43008
	s_waitcnt lgkmcnt(0)
	v_mfma_f32_16x16x32_bf16 v[46:49], v[14:17], v[6:9], v[26:29]
	v_mfma_f32_16x16x32_bf16 v[42:45], v[202:205], v[6:9], v[22:25]
	v_mfma_f32_16x16x32_bf16 v[38:41], v[134:137], v[6:9], v[18:21]
	v_mfma_f32_16x16x32_bf16 v[34:37], v[230:233], v[6:9], v[180:183]
	ds_read_b128 v[6:9], v170 offset:45056
	s_waitcnt lgkmcnt(0)
	v_mfma_f32_16x16x32_bf16 v[18:21], v[230:233], v[6:9], v[142:145]
	s_nop 2
	ds_read_b128 v[142:145], v170 offset:47104
	s_waitcnt lgkmcnt(0)
	v_mfma_f32_16x16x32_bf16 v[30:33], v[14:17], v[6:9], v[190:193]
	s_barrier
	v_mfma_f32_16x16x32_bf16 v[14:17], v[14:17], v[142:145], v[10:13]
	s_nop 2
	v_and_b32_e32 v10, 0xffffff80, v0
	v_add_u32_e32 v10, s0, v10
	v_mfma_f32_16x16x32_bf16 v[26:29], v[202:205], v[6:9], v[194:197]
	v_and_or_b32 v132, v0, 15, v10
	s_movk_i32 s0, 0x4010
	v_cmp_gt_i32_e32 vcc, s0, v132
	v_mfma_f32_16x16x32_bf16 v[22:25], v[134:137], v[6:9], v[198:201]
	v_mfma_f32_16x16x32_bf16 v[6:9], v[202:205], v[142:145], v[138:141]
	v_mfma_f32_16x16x32_bf16 v[2:5], v[134:137], v[142:145], v[2:5]
	v_mfma_f32_16x16x32_bf16 v[10:13], v[230:233], v[142:145], v[226:229]
	s_and_saveexec_b64 s[0:1], vcc
	s_cbranch_execz .LBB0_366
	v_ashrrev_i32_e32 v133, 31, v132
	v_lshlrev_b64 v[134:135], 11, v[132:133]
	v_lshl_add_u64 v[134:135], s[10:11], 0, v[134:135]
	v_cvt_pk_bf16_f32 v110, v110, v111
	v_cvt_pk_bf16_f32 v111, v112, v113
	v_lshl_add_u64 v[112:113], v[130:131], 1, v[134:135]
	v_cvt_pk_bf16_f32 v106, v106, v107
	v_cvt_pk_bf16_f32 v107, v108, v109
	v_cvt_pk_bf16_f32 v102, v102, v103
	v_cvt_pk_bf16_f32 v103, v104, v105
	v_cvt_pk_bf16_f32 v98, v98, v99
	v_cvt_pk_bf16_f32 v99, v100, v101
	global_store_dwordx2 v[112:113], v[110:111], off
	global_store_dwordx2 v[112:113], v[106:107], off offset:32
	global_store_dwordx2 v[112:113], v[102:103], off offset:64
	global_store_dwordx2 v[112:113], v[98:99], off offset:96

; #define TIDX opaque_tid()
; template <class Epi>
; DEVI void gemm_tile256b(const bf16_t* __restrict__ A, int lda, const bf16_t* __restrict__ Bt, int K,
;                         int m0, int n0, char* smem, Epi epi) {
;   const int tid = TIDX, lane = tid & 63, wave = tid >> 6;
;   const int wm = wave >> 1, wn = wave & 1, l15 = lane & 15, quad = lane >> 4;
;   f32x4 acc[8][4];
; #pragma unroll
;   for (int i = 0; i < 8; ++i)
; #pragma unroll
;     for (int j = 0; j < 4; ++j) acc[i][j] = f32x4{0.f, 0.f, 0.f, 0.f};
;   const int lrow = tid >> 3, lkc = tid & 7;
;   const bf16_t* ag = A + (size_t)(m0 + lrow) * lda + lkc * 8;
;   const int kb32 = K >> 5;
;   const bf16_t* bp = Bt + ((size_t)((n0 + wn * 64) >> 4) * kb32) * 512 + lane * 8;
;   u32x4 ra[8];
;   bf16x8 b0[4], b1[4];
;   const int lds_w = lrow * 128 + ((lkc ^ (lrow & 7)) << 4);
;   const int nk = K >> 6;
;   const int sw = (quad ^ (l15 & 7)) << 4;
;   const int a_rd = (wm * 128 + l15) * 128 + sw;
; #pragma unroll
;   for (int i = 0; i < 8; ++i) ra[i] = *(const u32x4*)(ag + (size_t)(i * 32) * lda);
; #pragma unroll
;   for (int i = 0; i < 4; ++i) b0[i] = *(const bf16x8*)(bp + ((size_t)i * kb32) * 512);
; #pragma unroll
;   for (int i = 0; i < 8; ++i) *(u32x4*)(smem + lds_w + i * 4096) = ra[i];
;   __syncthreads();
;   for (int kt = 0; kt < nk; ++kt) {
.LBB0_420:
	v_mov_b32_e32 v170, v206
	s_lshl_b32 s0, s17, 8
	s_lshl_b32 s62, s16, 7
	v_ashrrev_i32_e32 v8, 3, v170
	v_add_u32_e32 v2, s0, v8
	v_ashrrev_i32_e32 v3, 31, v2
	v_lshlrev_b64 v[50:51], 11, v[2:3]
	v_lshlrev_b32_e32 v0, 4, v170
	v_lshl_add_u64 v[2:3], s[14:15], 0, v[50:51]
	v_and_b32_e32 v0, 0x70, v0
	v_lshl_add_u64 v[2:3], v[2:3], 0, v[0:1]
	v_add_co_u32_e32 v4, vcc, s54, v2
	global_load_dwordx4 v[18:21], v[2:3], off
	s_nop 0
	v_addc_co_u32_e32 v5, vcc, 0, v3, vcc
	v_add_co_u32_e32 v6, vcc, s53, v2
	v_and_or_b32 v168, v170, 64, s62
	s_nop 0
	v_addc_co_u32_e32 v7, vcc, 0, v3, vcc
	global_load_dwordx4 v[22:25], v[4:5], off
	global_load_dwordx4 v[26:29], v[6:7], off
	v_add_co_u32_e32 v4, vcc, s52, v2
	v_readlane_b32 s16, v247, 19
	s_nop 0
	v_addc_co_u32_e32 v5, vcc, 0, v3, vcc
	v_add_co_u32_e32 v6, vcc, s56, v2
	v_and_b32_e32 v0, 63, v170
	s_nop 0
	v_addc_co_u32_e32 v7, vcc, 0, v3, vcc
	global_load_dwordx4 v[30:33], v[4:5], off
	global_load_dwordx4 v[34:37], v[6:7], off
	v_add_co_u32_e32 v4, vcc, s57, v2
	v_readlane_b32 s17, v247, 20
	s_nop 0
	v_addc_co_u32_e32 v5, vcc, 0, v3, vcc
	v_add_co_u32_e32 v6, vcc, s3, v2
	v_lshlrev_b32_e32 v0, 4, v0
	s_nop 0
	v_addc_co_u32_e32 v7, vcc, 0, v3, vcc
	v_add_co_u32_e32 v2, vcc, s19, v2
	global_load_dwordx4 v[38:41], v[4:5], off
	global_load_dwordx4 v[42:45], v[6:7], off
	v_addc_co_u32_e32 v3, vcc, 0, v3, vcc
	global_load_dwordx4 v[46:49], v[2:3], off
	v_lshlrev_b32_e32 v3, 7, v170
	v_ashrrev_i32_e32 v2, 4, v168
	v_and_b32_e32 v57, 0xffffc780, v3
	v_ashrrev_i32_e32 v3, 31, v2
	v_lshlrev_b64 v[52:53], 15, v[2:3]
	v_lshl_add_u64 v[2:3], s[16:17], 0, v[52:53]
	s_mov_b32 s1, 0x8000
	v_xor_b32_e32 v4, v8, v170
	v_lshl_add_u64 v[162:163], v[2:3], 0, v[0:1]
	v_lshlrev_b32_e32 v4, 4, v4
	v_add_co_u32_e32 v2, vcc, s1, v162
	v_bfe_u32 v169, v170, 4, 2
	v_lshlrev_b32_e32 v6, 7, v8
	v_and_b32_e32 v4, 0x70, v4
	v_addc_co_u32_e32 v3, vcc, 0, v163, vcc
	v_bitop3_b32 v5, v169, v170, 7 bitop3:0x78
	v_add3_u32 v172, 32, v4, v6
	v_add_co_u32_e32 v4, vcc, s54, v162
	v_lshlrev_b32_e32 v58, 4, v5
	s_nop 0
	v_addc_co_u32_e32 v5, vcc, 0, v163, vcc
	s_mov_b32 s13, 0x18000
	v_add_co_u32_e32 v54, vcc, s13, v162
	global_load_dwordx4 v[10:13], v[162:163], off
	s_nop 0
	v_addc_co_u32_e32 v55, vcc, 0, v163, vcc
	global_load_dwordx4 v[14:17], v[2:3], off
	global_load_dwordx4 v[6:9], v[4:5], off
	s_nop 0
	global_load_dwordx4 v[2:5], v[54:55], off
	v_and_b32_e32 v56, 7, v170
	v_or_b32_e32 v52, v52, v0
	v_lshl_or_b32 v50, v56, 4, v50
	v_mov_b32_e32 v90, 0
	v_or_b32_e32 v173, v58, v57
	v_bitop3_b32 v171, v58, 64, v57 bitop3:0x36
	v_lshl_add_u64 v[164:165], s[84:85], 0, v[52:53]
	v_lshl_add_u64 v[166:167], s[84:85], 0, v[50:51]
	v_mov_b32_e32 v91, v90
	v_mov_b32_e32 v92, v90
	v_mov_b32_e32 v93, v90
	v_mov_b32_e32 v110, v90
	v_mov_b32_e32 v111, v90
	v_mov_b32_e32 v112, v90
	v_mov_b32_e32 v113, v90
	v_mov_b32_e32 v134, v90
	v_mov_b32_e32 v135, v90
	s_waitcnt vmcnt(11)
	ds_write_b128 v172, v[18:21]
	s_waitcnt vmcnt(10)
	ds_write_b128 v172, v[22:25] offset:4096
	s_waitcnt vmcnt(9)
	ds_write_b128 v172, v[26:29] offset:8192
	s_waitcnt vmcnt(8)
	ds_write_b128 v172, v[30:33] offset:12288
	s_waitcnt vmcnt(7)
	ds_write_b128 v172, v[34:37] offset:16384
	s_waitcnt vmcnt(6)
	ds_write_b128 v172, v[38:41] offset:20480
	s_waitcnt vmcnt(5)
	ds_write_b128 v172, v[42:45] offset:24576
	s_waitcnt vmcnt(4)
	ds_write_b128 v172, v[46:49] offset:28672
	v_mov_b32_e32 v136, v90
	v_mov_b32_e32 v137, v90
	v_mov_b32_e32 v138, v90
	v_mov_b32_e32 v139, v90
	v_mov_b32_e32 v140, v90
	v_mov_b32_e32 v141, v90
	v_mov_b32_e32 v142, v90
	v_mov_b32_e32 v143, v90
	v_mov_b32_e32 v144, v90
	v_mov_b32_e32 v145, v90
	v_mov_b32_e32 v34, v90
	v_mov_b32_e32 v35, v90
	v_mov_b32_e32 v36, v90
	v_mov_b32_e32 v37, v90
	v_mov_b32_e32 v38, v90
	v_mov_b32_e32 v39, v90
	v_mov_b32_e32 v40, v90
	v_mov_b32_e32 v41, v90
	v_mov_b32_e32 v30, v90
	v_mov_b32_e32 v31, v90
	v_mov_b32_e32 v32, v90
	v_mov_b32_e32 v33, v90
	v_mov_b32_e32 v42, v90
	v_mov_b32_e32 v43, v90
	v_mov_b32_e32 v44, v90
	v_mov_b32_e32 v45, v90
	v_mov_b32_e32 v18, v90
	v_mov_b32_e32 v19, v90
	v_mov_b32_e32 v20, v90
	v_mov_b32_e32 v21, v90
	v_mov_b32_e32 v22, v90
	v_mov_b32_e32 v23, v90
	v_mov_b32_e32 v24, v90
	v_mov_b32_e32 v25, v90
	v_mov_b32_e32 v26, v90
	v_mov_b32_e32 v27, v90
	v_mov_b32_e32 v28, v90
	v_mov_b32_e32 v29, v90
	v_mov_b32_e32 v54, v90
	v_mov_b32_e32 v55, v90
	v_mov_b32_e32 v56, v90
	v_mov_b32_e32 v57, v90
	v_mov_b32_e32 v58, v90
	v_mov_b32_e32 v59, v90
	v_mov_b32_e32 v60, v90
	v_mov_b32_e32 v61, v90
	v_mov_b32_e32 v50, v90
	v_mov_b32_e32 v51, v90
	v_mov_b32_e32 v52, v90
	v_mov_b32_e32 v53, v90
	v_mov_b32_e32 v46, v90
	v_mov_b32_e32 v47, v90
	v_mov_b32_e32 v48, v90
	v_mov_b32_e32 v49, v90
	v_mov_b32_e32 v66, v90
	v_mov_b32_e32 v67, v90
	v_mov_b32_e32 v68, v90
	v_mov_b32_e32 v69, v90
	v_mov_b32_e32 v62, v90
	v_mov_b32_e32 v63, v90
	v_mov_b32_e32 v64, v90
	v_mov_b32_e32 v65, v90
	v_mov_b32_e32 v70, v90
	v_mov_b32_e32 v71, v90
	v_mov_b32_e32 v72, v90
	v_mov_b32_e32 v73, v90
	v_mov_b32_e32 v74, v90
	v_mov_b32_e32 v75, v90
	v_mov_b32_e32 v76, v90
	v_mov_b32_e32 v77, v90
	v_mov_b32_e32 v78, v90
	v_mov_b32_e32 v79, v90
	v_mov_b32_e32 v80, v90
	v_mov_b32_e32 v81, v90
	v_mov_b32_e32 v82, v90
	v_mov_b32_e32 v83, v90
	v_mov_b32_e32 v84, v90
	v_mov_b32_e32 v85, v90
	v_mov_b32_e32 v86, v90
	v_mov_b32_e32 v87, v90
	v_mov_b32_e32 v88, v90
	v_mov_b32_e32 v89, v90
	v_mov_b32_e32 v94, v90
	v_mov_b32_e32 v95, v90
	v_mov_b32_e32 v96, v90
	v_mov_b32_e32 v97, v90
	v_mov_b32_e32 v98, v90
	v_mov_b32_e32 v99, v90
	v_mov_b32_e32 v100, v90
	v_mov_b32_e32 v101, v90
	v_mov_b32_e32 v102, v90
	v_mov_b32_e32 v103, v90
	v_mov_b32_e32 v104, v90
	v_mov_b32_e32 v105, v90
	v_mov_b32_e32 v106, v90
	v_mov_b32_e32 v107, v90
	v_mov_b32_e32 v108, v90
	v_mov_b32_e32 v109, v90
	v_mov_b32_e32 v114, v90
	v_mov_b32_e32 v115, v90
	v_mov_b32_e32 v116, v90
	v_mov_b32_e32 v117, v90
	v_mov_b32_e32 v118, v90
	v_mov_b32_e32 v119, v90
	v_mov_b32_e32 v120, v90
	v_mov_b32_e32 v121, v90
	v_mov_b32_e32 v122, v90
	v_mov_b32_e32 v123, v90
	v_mov_b32_e32 v124, v90
	v_mov_b32_e32 v125, v90
	v_mov_b32_e32 v126, v90
	v_mov_b32_e32 v127, v90
	v_mov_b32_e32 v128, v90
	v_mov_b32_e32 v129, v90
	v_mov_b32_e32 v130, v90
	v_mov_b32_e32 v131, v90
	v_mov_b32_e32 v132, v90
	v_mov_b32_e32 v133, v90
	s_mov_b32 s16, 0x2040000
	s_mov_b32 s17, 0x2048000
	s_mov_b32 s18, 0x2050000
	s_mov_b32 s24, 0x2058000
	s_waitcnt lgkmcnt(0)
	s_barrier
	s_add_i32 s98, s1, 0xffff8000
	s_and_b32 s98, s98, 0x8000
	s_add_i32 s98, s98, 32
	v_add_u32_e32 v226, s98, v173
	ds_read_b128 v[196:199], v226
	ds_read_b128 v[200:203], v226 offset:2048
; #define MFMA16(a, b, c) __builtin_amdgcn_mfma_f32_16x16x32_bf16((a), (b), (c), 0, 0, 0)
; template <class Epi>
; DEVI void gemm_tile256b(const bf16_t* __restrict__ A, int lda, const bf16_t* __restrict__ Bt, int K,
;                         int m0, int n0, char* smem, Epi epi) {
;     ...
;   for (int kt = 0; kt < nk; ++kt) {
;     const char* base = smem + (kt & 1) * 32768;
;     const bool more = kt + 1 < nk;
;     if (more) {
; #pragma unroll
;       for (int i = 0; i < 8; ++i) ra[i] = *(const u32x4*)(ag + (size_t)(i * 32) * lda + (kt + 1) * 64);
;     }
; #pragma unroll
;     for (int i = 0; i < 4; ++i) b1[i] = *(const bf16x8*)(bp + ((size_t)i * kb32 + kt * 2 + 1) * 512);
;     {
;       bf16x8 af[8];
; #pragma unroll
;       for (int i = 0; i < 8; ++i) af[i] = *(const bf16x8*)(base + a_rd + i * 2048);
; #pragma unroll
;       for (int mi = 0; mi < 8; ++mi)
; #pragma unroll
;         for (int ni = 0; ni < 4; ++ni) acc[mi][ni] = MFMA16(b0[ni], af[mi], acc[mi][ni]);
;     }
;     if (more) {
; #pragma unroll
;       for (int i = 0; i < 4; ++i) b0[i] = *(const bf16x8*)(bp + ((size_t)i * kb32 + kt * 2 + 2) * 512);
;     }
;     {
;       bf16x8 af[8];
; #pragma unroll
;       for (int i = 0; i < 8; ++i) af[i] = *(const bf16x8*)(base + ((a_rd + i * 2048) ^ 64));
; #pragma unroll
;       for (int mi = 0; mi < 8; ++mi)
; #pragma unroll
;         for (int ni = 0; ni < 4; ++ni) acc[mi][ni] = MFMA16(b1[ni], af[mi], acc[mi][ni]);
;     }
;     if (more) {
;       char* nb = smem + ((kt + 1) & 1) * 32768 + lds_w;
; #pragma unroll
;       for (int i = 0; i < 8; ++i) *(u32x4*)(nb + i * 4096) = ra[i];
;     }
;     __syncthreads();
;   }
.LBB0_421:
	s_add_i32 s13, s1, 0xffff8000
	s_and_b32 s13, s13, 0x8000
	s_add_i32 s13, s13, 32
	v_add_u32_e32 v0, s13, v173
	v_lshl_add_u64 v[154:155], v[164:165], 0, s[28:29]
	v_add_co_u32_e32 v156, vcc, s16, v154
	s_waitcnt vmcnt(3) lgkmcnt(1)
	v_mfma_f32_16x16x32_bf16 v[130:133], v[10:13], v[196:199], v[130:133]
	v_addc_co_u32_e32 v157, vcc, 0, v155, vcc
	v_add_co_u32_e32 v158, vcc, s17, v154
	s_waitcnt vmcnt(2)
	v_mfma_f32_16x16x32_bf16 v[126:129], v[14:17], v[196:199], v[126:129]
	v_addc_co_u32_e32 v159, vcc, 0, v155, vcc
	v_add_co_u32_e32 v160, vcc, s18, v154
	s_waitcnt vmcnt(1)
	v_mfma_f32_16x16x32_bf16 v[122:125], v[6:9], v[196:199], v[122:125]
	v_addc_co_u32_e32 v161, vcc, 0, v155, vcc
	v_add_co_u32_e32 v182, vcc, s24, v154
	s_waitcnt vmcnt(0)
	v_mfma_f32_16x16x32_bf16 v[118:121], v[2:5], v[196:199], v[118:121]
	v_addc_co_u32_e32 v183, vcc, 0, v155, vcc
	s_waitcnt lgkmcnt(0)
	v_mfma_f32_16x16x32_bf16 v[114:117], v[10:13], v[200:203], v[114:117]
	v_lshl_add_u64 v[164:165], v[164:165], 0, s[64:65]
	v_mfma_f32_16x16x32_bf16 v[106:109], v[14:17], v[200:203], v[106:109]
	v_mfma_f32_16x16x32_bf16 v[102:105], v[6:9], v[200:203], v[102:105]
	s_nop 0
	v_mfma_f32_16x16x32_bf16 v[98:101], v[2:5], v[200:203], v[98:101]
	ds_read_b128 v[146:149], v0 offset:4096
	ds_read_b128 v[150:153], v0 offset:6144
	s_waitcnt lgkmcnt(1)
	v_mfma_f32_16x16x32_bf16 v[94:97], v[10:13], v[146:149], v[94:97]
	v_lshl_add_u64 v[166:167], v[166:167], 0, s[60:61]
	v_mfma_f32_16x16x32_bf16 v[86:89], v[14:17], v[146:149], v[86:89]
	v_mfma_f32_16x16x32_bf16 v[82:85], v[6:9], v[146:149], v[82:85]
	s_nop 0
	v_mfma_f32_16x16x32_bf16 v[78:81], v[2:5], v[146:149], v[78:81]
	s_nop 0
	s_waitcnt lgkmcnt(0)
	v_mfma_f32_16x16x32_bf16 v[74:77], v[10:13], v[150:153], v[74:77]
	v_mfma_f32_16x16x32_bf16 v[70:73], v[14:17], v[150:153], v[70:73]
	v_mfma_f32_16x16x32_bf16 v[62:65], v[6:9], v[150:153], v[62:65]
	v_mfma_f32_16x16x32_bf16 v[66:69], v[2:5], v[150:153], v[66:69]
	ds_read_b128 v[146:149], v0 offset:8192
	ds_read_b128 v[150:153], v0 offset:10240
	s_waitcnt lgkmcnt(1)
	v_mfma_f32_16x16x32_bf16 v[46:49], v[10:13], v[146:149], v[46:49]
	v_mfma_f32_16x16x32_bf16 v[50:53], v[14:17], v[146:149], v[50:53]
	v_mfma_f32_16x16x32_bf16 v[58:61], v[6:9], v[146:149], v[58:61]
	v_mfma_f32_16x16x32_bf16 v[54:57], v[2:5], v[146:149], v[54:57]
	s_waitcnt lgkmcnt(0)
	v_mfma_f32_16x16x32_bf16 v[26:29], v[10:13], v[150:153], v[26:29]
	v_mfma_f32_16x16x32_bf16 v[22:25], v[14:17], v[150:153], v[22:25]
	v_mfma_f32_16x16x32_bf16 v[18:21], v[6:9], v[150:153], v[18:21]
	v_mfma_f32_16x16x32_bf16 v[42:45], v[2:5], v[150:153], v[42:45]
	ds_read_b128 v[146:149], v0 offset:12288
	ds_read_b128 v[150:153], v0 offset:14336
	v_add_u32_e32 v0, s13, v171
	s_and_b32 s13, s1, 0x8000
	s_waitcnt lgkmcnt(1)
	v_mfma_f32_16x16x32_bf16 v[30:33], v[10:13], v[146:149], v[30:33]
	s_add_i32 s1, s1, 0x8000
	s_cmp_eq_u32 s1, 0x80000
	v_mfma_f32_16x16x32_bf16 v[38:41], v[14:17], v[146:149], v[38:41]
	v_mfma_f32_16x16x32_bf16 v[34:37], v[6:9], v[146:149], v[34:37]
	v_mfma_f32_16x16x32_bf16 v[142:145], v[2:5], v[146:149], v[142:145]
	global_load_dwordx4 v[146:149], v[156:157], off offset:1024
	ds_read_b128 v[174:177], v0
	ds_read_b128 v[178:181], v0 offset:2048
	s_waitcnt lgkmcnt(2)
	v_mfma_f32_16x16x32_bf16 v[138:141], v[10:13], v[150:153], v[138:141]
	global_load_dwordx4 v[10:13], v[156:157], off offset:2048
	v_mfma_f32_16x16x32_bf16 v[134:137], v[14:17], v[150:153], v[134:137]
	v_mfma_f32_16x16x32_bf16 v[110:113], v[6:9], v[150:153], v[110:113]
	v_mfma_f32_16x16x32_bf16 v[90:93], v[2:5], v[150:153], v[90:93]
	global_load_dwordx4 v[150:153], v[158:159], off offset:1024
	global_load_dwordx4 v[14:17], v[158:159], off offset:2048
	global_load_dwordx4 v[154:157], v[160:161], off offset:1024
	global_load_dwordx4 v[6:9], v[160:161], off offset:2048
	s_nop 0
	global_load_dwordx4 v[158:161], v[182:183], off offset:1024
	global_load_dwordx4 v[2:5], v[182:183], off offset:2048
	v_lshrrev_b32_e32 v195, 6, v206
	v_lshl_add_u64 v[190:191], v[166:167], 0, s[28:29]
	v_lshrrev_b32_e32 v194, 3, v206
	v_readfirstlane_b32 s99, v195
	v_and_b32_e32 v194, 7, v194
	s_and_b32 s98, s1, 0x8000
	s_xor_b32 s98, s98, 0x8000
	v_lshlrev_b32_e32 v194, 4, v194
	s_lshl_b32 s99, s99, 10
	v_xor_b32_e32 v190, v194, v190
	s_add_u32 s98, s98, s99
	s_add_u32 s98, s98, 32
	s_mov_b32 s101, 0
	s_mov_b32 s100, 0x0
	v_lshl_add_u64 v[192:193], v[190:191], 0, s[100:101]
	s_mov_b32 m0, s98
	s_nop 0
	global_load_lds_dwordx4 v[192:193], off
	s_add_u32 s100, s54, 0x0
	v_lshl_add_u64 v[192:193], v[190:191], 0, s[100:101]
	s_add_u32 m0, s98, 0x1000
	s_nop 0
	global_load_lds_dwordx4 v[192:193], off
	s_add_u32 s100, s53, 0x0
	v_lshl_add_u64 v[192:193], v[190:191], 0, s[100:101]
	s_add_u32 m0, s98, 0x2000
	s_nop 0
	global_load_lds_dwordx4 v[192:193], off
	s_add_u32 s100, s52, 0x0
	v_lshl_add_u64 v[192:193], v[190:191], 0, s[100:101]
	s_add_u32 m0, s98, 0x3000
	s_nop 0
	global_load_lds_dwordx4 v[192:193], off
	s_add_u32 s100, s56, 0x0
	v_lshl_add_u64 v[192:193], v[190:191], 0, s[100:101]
	s_add_u32 m0, s98, 0x4000
	s_nop 0
	global_load_lds_dwordx4 v[192:193], off
	s_add_u32 s100, s57, 0x0
	v_lshl_add_u64 v[192:193], v[190:191], 0, s[100:101]
	s_add_u32 m0, s98, 0x5000
	s_nop 0
	global_load_lds_dwordx4 v[192:193], off
	s_add_u32 s100, s3, 0x0
	v_lshl_add_u64 v[192:193], v[190:191], 0, s[100:101]
	s_add_u32 m0, s98, 0x6000
	s_nop 0
	global_load_lds_dwordx4 v[192:193], off
	s_add_u32 s100, s19, 0x0
	v_lshl_add_u64 v[192:193], v[190:191], 0, s[100:101]
	s_add_u32 m0, s98, 0x7000
	s_nop 0
	global_load_lds_dwordx4 v[192:193], off
	s_waitcnt vmcnt(15) lgkmcnt(1)
; #define MFMA16(a, b, c) __builtin_amdgcn_mfma_f32_16x16x32_bf16((a), (b), (c), 0, 0, 0)
; template <class Epi>
; DEVI void gemm_tile256b(const bf16_t* __restrict__ A, int lda, const bf16_t* __restrict__ Bt, int K,
;                         int m0, int n0, char* smem, Epi epi) {
;     ...
;   for (int kt = 0; kt < nk; ++kt) {
;     const char* base = smem + (kt & 1) * 32768;
;     const bool more = kt + 1 < nk;
;     if (more) {
; #pragma unroll
;       for (int i = 0; i < 8; ++i) ra[i] = *(const u32x4*)(ag + (size_t)(i * 32) * lda + (kt + 1) * 64);
;     }
; #pragma unroll
;     for (int i = 0; i < 4; ++i) b1[i] = *(const bf16x8*)(bp + ((size_t)i * kb32 + kt * 2 + 1) * 512);
;     {
;       bf16x8 af[8];
; #pragma unroll
;       for (int i = 0; i < 8; ++i) af[i] = *(const bf16x8*)(base + a_rd + i * 2048);
; #pragma unroll
;       for (int mi = 0; mi < 8; ++mi)
; #pragma unroll
;         for (int ni = 0; ni < 4; ++ni) acc[mi][ni] = MFMA16(b0[ni], af[mi], acc[mi][ni]);
;     }
;     if (more) {
; #pragma unroll
;       for (int i = 0; i < 4; ++i) b0[i] = *(const bf16x8*)(bp + ((size_t)i * kb32 + kt * 2 + 2) * 512);
;     }
;     {
;       bf16x8 af[8];
; #pragma unroll
;       for (int i = 0; i < 8; ++i) af[i] = *(const bf16x8*)(base + ((a_rd + i * 2048) ^ 64));
; #pragma unroll
;       for (int mi = 0; mi < 8; ++mi)
; #pragma unroll
;         for (int ni = 0; ni < 4; ++ni) acc[mi][ni] = MFMA16(b1[ni], af[mi], acc[mi][ni]);
;     }
;     if (more) {
;       char* nb = smem + ((kt + 1) & 1) * 32768 + lds_w;
; #pragma unroll
;       for (int i = 0; i < 8; ++i) *(u32x4*)(nb + i * 4096) = ra[i];
;     }
;     __syncthreads();
;   }
	v_mfma_f32_16x16x32_bf16 v[130:133], v[146:149], v[174:177], v[130:133]
	s_waitcnt vmcnt(13)
	v_mfma_f32_16x16x32_bf16 v[126:129], v[150:153], v[174:177], v[126:129]
	s_waitcnt vmcnt(11)
	v_mfma_f32_16x16x32_bf16 v[122:125], v[154:157], v[174:177], v[122:125]
	s_waitcnt vmcnt(9)
	v_mfma_f32_16x16x32_bf16 v[118:121], v[158:161], v[174:177], v[118:121]
	s_waitcnt lgkmcnt(0)
	v_mfma_f32_16x16x32_bf16 v[114:117], v[146:149], v[178:181], v[114:117]
	v_mfma_f32_16x16x32_bf16 v[106:109], v[150:153], v[178:181], v[106:109]
	v_mfma_f32_16x16x32_bf16 v[102:105], v[154:157], v[178:181], v[102:105]
	v_mfma_f32_16x16x32_bf16 v[98:101], v[158:161], v[178:181], v[98:101]
	ds_read_b128 v[174:177], v0 offset:4096
	ds_read_b128 v[178:181], v0 offset:6144
	s_waitcnt lgkmcnt(1)
	v_mfma_f32_16x16x32_bf16 v[94:97], v[146:149], v[174:177], v[94:97]
	v_mfma_f32_16x16x32_bf16 v[86:89], v[150:153], v[174:177], v[86:89]
	v_mfma_f32_16x16x32_bf16 v[82:85], v[154:157], v[174:177], v[82:85]
	v_mfma_f32_16x16x32_bf16 v[78:81], v[158:161], v[174:177], v[78:81]
	s_waitcnt lgkmcnt(0)
	v_mfma_f32_16x16x32_bf16 v[74:77], v[146:149], v[178:181], v[74:77]
	v_mfma_f32_16x16x32_bf16 v[70:73], v[150:153], v[178:181], v[70:73]
	v_mfma_f32_16x16x32_bf16 v[62:65], v[154:157], v[178:181], v[62:65]
	v_mfma_f32_16x16x32_bf16 v[66:69], v[158:161], v[178:181], v[66:69]
	ds_read_b128 v[178:181], v0 offset:8192
	ds_read_b128 v[182:185], v0 offset:10240
	s_waitcnt lgkmcnt(1)
	v_mfma_f32_16x16x32_bf16 v[46:49], v[146:149], v[178:181], v[46:49]
	v_mfma_f32_16x16x32_bf16 v[50:53], v[150:153], v[178:181], v[50:53]
	v_mfma_f32_16x16x32_bf16 v[58:61], v[154:157], v[178:181], v[58:61]
	v_mfma_f32_16x16x32_bf16 v[54:57], v[158:161], v[178:181], v[54:57]
	s_waitcnt lgkmcnt(0)
	v_mfma_f32_16x16x32_bf16 v[26:29], v[146:149], v[182:185], v[26:29]
	v_mfma_f32_16x16x32_bf16 v[22:25], v[150:153], v[182:185], v[22:25]
	v_mfma_f32_16x16x32_bf16 v[18:21], v[154:157], v[182:185], v[18:21]
	v_mfma_f32_16x16x32_bf16 v[42:45], v[158:161], v[182:185], v[42:45]
	ds_read_b128 v[178:181], v0 offset:12288
	ds_read_b128 v[182:185], v0 offset:14336
	s_nop 0
	s_nop 0
	s_nop 0
	s_nop 0
	s_nop 0
	s_waitcnt lgkmcnt(1)
	v_mfma_f32_16x16x32_bf16 v[30:33], v[146:149], v[178:181], v[30:33]
	v_mfma_f32_16x16x32_bf16 v[38:41], v[150:153], v[178:181], v[38:41]
	v_mfma_f32_16x16x32_bf16 v[34:37], v[154:157], v[178:181], v[34:37]
	s_waitcnt vmcnt(0) lgkmcnt(0)
	s_barrier
	s_add_i32 s98, s1, 0xffff8000
	s_and_b32 s98, s98, 0x8000
	s_add_i32 s98, s98, 32
	v_add_u32_e32 v226, s98, v173
	ds_read_b128 v[196:199], v226
	ds_read_b128 v[200:203], v226 offset:2048
	v_mfma_f32_16x16x32_bf16 v[142:145], v[158:161], v[178:181], v[142:145]
	v_mfma_f32_16x16x32_bf16 v[138:141], v[146:149], v[182:185], v[138:141]
	v_mfma_f32_16x16x32_bf16 v[134:137], v[150:153], v[182:185], v[134:137]
	v_mfma_f32_16x16x32_bf16 v[110:113], v[154:157], v[182:185], v[110:113]
	v_mfma_f32_16x16x32_bf16 v[90:93], v[158:161], v[182:185], v[90:93]
	s_cmp_eq_u32 s1, 0x80000
	s_cbranch_scc0 .LBB0_421
	v_add_u32_e32 v0, 32, v173
	ds_read_b128 v[146:149], v0 offset:32768
	s_movk_i32 s1, 0x7000
	s_movk_i32 s13, 0x4000
	s_waitcnt lgkmcnt(0)
	v_mfma_f32_16x16x32_bf16 v[130:133], v[10:13], v[146:149], v[130:133]
	v_mfma_f32_16x16x32_bf16 v[150:153], v[14:17], v[146:149], v[126:129]
	v_mfma_f32_16x16x32_bf16 v[154:157], v[6:9], v[146:149], v[122:125]
	v_mfma_f32_16x16x32_bf16 v[146:149], v[2:5], v[146:149], v[118:121]
	s_nop 2
	ds_read_b128 v[118:121], v0 offset:34816
	s_waitcnt lgkmcnt(0)
	v_mfma_f32_16x16x32_bf16 v[158:161], v[10:13], v[118:121], v[114:117]
	s_nop 2
	ds_read_b128 v[114:117], v0 offset:36864
	s_waitcnt lgkmcnt(0)
	v_mfma_f32_16x16x32_bf16 v[94:97], v[10:13], v[114:117], v[94:97]
	v_mfma_f32_16x16x32_bf16 v[86:89], v[14:17], v[114:117], v[86:89]
	v_mfma_f32_16x16x32_bf16 v[82:85], v[6:9], v[114:117], v[82:85]
	v_mfma_f32_16x16x32_bf16 v[78:81], v[2:5], v[114:117], v[78:81]
	ds_read_b128 v[114:117], v0 offset:38912
	s_waitcnt lgkmcnt(0)
	v_mfma_f32_16x16x32_bf16 v[74:77], v[10:13], v[114:117], v[74:77]
	v_mfma_f32_16x16x32_bf16 v[70:73], v[14:17], v[114:117], v[70:73]
	v_mfma_f32_16x16x32_bf16 v[62:65], v[6:9], v[114:117], v[62:65]
	v_mfma_f32_16x16x32_bf16 v[66:69], v[2:5], v[114:117], v[66:69]
	ds_read_b128 v[114:117], v0 offset:40960
	s_waitcnt lgkmcnt(0)
	v_mfma_f32_16x16x32_bf16 v[172:175], v[2:5], v[114:117], v[54:57]
	s_nop 2
	ds_read_b128 v[54:57], v0 offset:43008
	s_waitcnt lgkmcnt(0)
	v_mfma_f32_16x16x32_bf16 v[176:179], v[2:5], v[54:57], v[42:45]
	s_nop 2
	ds_read_b128 v[42:45], v0 offset:45056
	s_waitcnt lgkmcnt(0)
	v_mfma_f32_16x16x32_bf16 v[190:193], v[6:9], v[42:45], v[34:37]
	s_nop 2
	ds_read_b128 v[34:37], v0 offset:47104
	v_add_u32_e32 v0, 32, v171
	v_mfma_f32_16x16x32_bf16 v[106:109], v[14:17], v[118:121], v[106:109]
	v_mfma_f32_16x16x32_bf16 v[50:53], v[14:17], v[114:117], v[50:53]
	v_mfma_f32_16x16x32_bf16 v[22:25], v[14:17], v[54:57], v[22:25]
	v_mfma_f32_16x16x32_bf16 v[180:183], v[14:17], v[42:45], v[38:41]
	s_waitcnt lgkmcnt(0)
; DEVI bf16_t f2bf(float a) { return (bf16_t)(pack2(a, 0.f) & 0xffff); }
; #define MFMA16(a, b, c) __builtin_amdgcn_mfma_f32_16x16x32_bf16((a), (b), (c), 0, 0, 0)
; template <class Epi>
; DEVI void gemm_tile256b(const bf16_t* __restrict__ A, int lda, const bf16_t* __restrict__ Bt, int K,
;                         int m0, int n0, char* smem, Epi epi) {
;     ...
;     {
;       bf16x8 af[8];
; #pragma unroll
;       for (int i = 0; i < 8; ++i) af[i] = *(const bf16x8*)(base + ((a_rd + i * 2048) ^ 64));
; #pragma unroll
;       for (int mi = 0; mi < 8; ++mi)
; #pragma unroll
;         for (int ni = 0; ni < 4; ++ni) acc[mi][ni] = MFMA16(b1[ni], af[mi], acc[mi][ni]);
;     }
;     if (more) {
;       char* nb = smem + ((kt + 1) & 1) * 32768 + lds_w;
; #pragma unroll
;       for (int i = 0; i < 8; ++i) *(u32x4*)(nb + i * 4096) = ra[i];
;     }
;     __syncthreads();
;   }
; #pragma unroll
;   for (int mi = 0; mi < 8; ++mi)
; #pragma unroll
;     for (int ni = 0; ni < 4; ++ni)
;       epi(m0 + wm * 128 + mi * 16 + l15, n0 + wn * 64 + ni * 16 + quad * 4, acc[mi][ni]);
;   DEVI void operator()(int m, int n, f32x4 v) const {
;     if (n < 1024) {
;       if (m >= L) return;
;       const bool isq = n < 512;
;       const int nn = n & 511;
;       const int h = nn >> 7, c = (nn >> 6) & 1, d = nn & 63;
;       const float s = isq ? (0.125f * LOG2E) : 1.0f;
;       bf16_t* dst = isq ? r0 + R0_Q + ((size_t)(h * 2 + c) * LR + m) * 64 + d
;                         : r0 + R0_K + (size_t)(h * 2 + c) * LR * 64 + wfm(m, d, 64);
;       *(u32x2*)dst = u32x2{pack2(v[0] * s, v[1] * s), pack2(v[2] * s, v[3] * s)};
;     } else if (n < 1536) {
;       const int nn = n - 1024;
;       bf16_t* dst = r0 + R0_VT + (size_t)nn * LR + m;
;       const bool ok = m < L;
; #pragma unroll
;       for (int i = 0; i < 4; ++i) {
;         dst[(size_t)i * LR] = ok ? f2bf(v[i]) : (bf16_t)0;
;         if (m >= 16384) {
;           dst[(size_t)i * LR + 16] = 0;
;           dst[(size_t)i * LR + 32] = 0;
;           dst[(size_t)i * LR + 48] = 0;
;         }
;       }
;     } else {
;       if (m >= L) return;
;       bf16_t* dst = r0 + R0_U + (size_t)m * 512 + (n - 1536);
;       *(u32x2*)dst = u32x2{pack2(v[0], v[1]), pack2(v[2], v[3])};
	v_mfma_f32_16x16x32_bf16 v[134:137], v[14:17], v[34:37], v[134:137]
	v_add_co_u32_e32 v14, vcc, s1, v162
	s_mov_b32 s1, 0xf000
	s_nop 0
	v_addc_co_u32_e32 v15, vcc, 0, v163, vcc
	v_add_co_u32_e32 v38, vcc, s1, v162
	v_mfma_f32_16x16x32_bf16 v[46:49], v[10:13], v[114:117], v[46:49]
	s_nop 0
	v_addc_co_u32_e32 v39, vcc, 0, v163, vcc
	global_load_dwordx4 v[14:17], v[14:15], off offset:3072
	v_mfma_f32_16x16x32_bf16 v[26:29], v[10:13], v[54:57], v[26:29]
	s_mov_b32 s1, 0x17000
	v_mfma_f32_16x16x32_bf16 v[30:33], v[10:13], v[42:45], v[30:33]
	v_mfma_f32_16x16x32_bf16 v[10:13], v[10:13], v[34:37], v[138:141]
	s_nop 2
	global_load_dwordx4 v[138:141], v[38:39], off offset:3072
	v_mfma_f32_16x16x32_bf16 v[102:105], v[6:9], v[118:121], v[102:105]
	v_add_co_u32_e32 v38, vcc, s1, v162
	s_mov_b32 s1, 0x1f000
	v_mfma_f32_16x16x32_bf16 v[98:101], v[2:5], v[118:121], v[98:101]
	v_addc_co_u32_e32 v39, vcc, 0, v163, vcc
	global_load_dwordx4 v[198:201], v[38:39], off offset:3072
	v_mfma_f32_16x16x32_bf16 v[164:167], v[6:9], v[114:117], v[58:61]
	v_add_co_u32_e32 v38, vcc, s1, v162
	v_mfma_f32_16x16x32_bf16 v[18:21], v[6:9], v[54:57], v[18:21]
	s_nop 0
	v_addc_co_u32_e32 v39, vcc, 0, v163, vcc
	v_mfma_f32_16x16x32_bf16 v[194:197], v[2:5], v[42:45], v[142:145]
	v_mfma_f32_16x16x32_bf16 v[6:9], v[6:9], v[34:37], v[110:113]
	s_nop 1
	v_and_b32_e32 v142, 15, v170
	v_lshlrev_b32_e32 v143, 2, v169
	v_mfma_f32_16x16x32_bf16 v[2:5], v[2:5], v[34:37], v[90:93]
	ds_read_b128 v[34:37], v0 offset:32768
	s_waitcnt vmcnt(1) lgkmcnt(0)
	v_mfma_f32_16x16x32_bf16 v[122:125], v[138:141], v[34:37], v[150:153]
	s_nop 2
	global_load_dwordx4 v[150:153], v[38:39], off offset:3072
	v_mfma_f32_16x16x32_bf16 v[126:129], v[14:17], v[34:37], v[130:133]
	s_waitcnt vmcnt(1)
	v_mfma_f32_16x16x32_bf16 v[118:121], v[198:201], v[34:37], v[154:157]
	s_nop 0
	v_or_b32_e32 v130, v143, v168
	s_waitcnt vmcnt(0)
	v_mfma_f32_16x16x32_bf16 v[114:117], v[150:153], v[34:37], v[146:149]
	ds_read_b128 v[34:37], v0 offset:34816
	s_nop 1
	ds_read_b128 v[144:147], v0 offset:47104
	s_waitcnt lgkmcnt(1)
	v_mfma_f32_16x16x32_bf16 v[110:113], v[14:17], v[34:37], v[158:161]
	v_mfma_f32_16x16x32_bf16 v[106:109], v[138:141], v[34:37], v[106:109]
	v_mfma_f32_16x16x32_bf16 v[102:105], v[198:201], v[34:37], v[102:105]
	v_mfma_f32_16x16x32_bf16 v[98:101], v[150:153], v[34:37], v[98:101]
	ds_read_b128 v[34:37], v0 offset:36864
	s_waitcnt lgkmcnt(0)
	v_mfma_f32_16x16x32_bf16 v[94:97], v[14:17], v[34:37], v[94:97]
	v_mfma_f32_16x16x32_bf16 v[90:93], v[138:141], v[34:37], v[86:89]
	v_mfma_f32_16x16x32_bf16 v[86:89], v[198:201], v[34:37], v[82:85]
	v_mfma_f32_16x16x32_bf16 v[82:85], v[150:153], v[34:37], v[78:81]
	ds_read_b128 v[34:37], v0 offset:38912
	s_waitcnt lgkmcnt(0)
	v_mfma_f32_16x16x32_bf16 v[78:81], v[14:17], v[34:37], v[74:77]
	v_mfma_f32_16x16x32_bf16 v[74:77], v[138:141], v[34:37], v[70:73]
	v_mfma_f32_16x16x32_bf16 v[70:73], v[198:201], v[34:37], v[62:65]
	v_mfma_f32_16x16x32_bf16 v[66:69], v[150:153], v[34:37], v[66:69]
	ds_read_b128 v[34:37], v0 offset:40960
	s_waitcnt lgkmcnt(0)
	v_mfma_f32_16x16x32_bf16 v[62:65], v[14:17], v[34:37], v[46:49]
	v_mfma_f32_16x16x32_bf16 v[58:61], v[138:141], v[34:37], v[50:53]
	v_mfma_f32_16x16x32_bf16 v[54:57], v[198:201], v[34:37], v[164:167]
	v_mfma_f32_16x16x32_bf16 v[50:53], v[150:153], v[34:37], v[172:175]
	ds_read_b128 v[34:37], v0 offset:43008
	s_waitcnt lgkmcnt(0)
	v_mfma_f32_16x16x32_bf16 v[38:41], v[198:201], v[34:37], v[18:21]
	s_nop 2
	ds_read_b128 v[18:21], v0 offset:45056
	v_and_b32_e32 v0, 0xffffff80, v170
	v_add_u32_e32 v0, s0, v0
	v_mfma_f32_16x16x32_bf16 v[46:49], v[14:17], v[34:37], v[26:29]
	v_or_b32_e32 v132, v0, v142
	v_ashrrev_i32_e32 v133, 31, v132
	s_movk_i32 s0, 0x4010
	v_mfma_f32_16x16x32_bf16 v[42:45], v[138:141], v[34:37], v[22:25]
	v_cmp_gt_i32_e64 s[46:47], s13, v132
	s_movk_i32 s13, 0x3ff
	v_cmp_gt_i32_e64 s[0:1], s0, v132
	v_mfma_f32_16x16x32_bf16 v[34:37], v[150:153], v[34:37], v[176:179]
	v_cmp_lt_i32_e64 s[42:43], s13, v130
	s_waitcnt lgkmcnt(0)
	s_barrier
	v_mfma_f32_16x16x32_bf16 v[30:33], v[14:17], v[18:21], v[30:33]
	v_mfma_f32_16x16x32_bf16 v[26:29], v[138:141], v[18:21], v[180:183]
	v_mfma_f32_16x16x32_bf16 v[22:25], v[198:201], v[18:21], v[190:193]
	v_mfma_f32_16x16x32_bf16 v[18:21], v[150:153], v[18:21], v[194:197]
	v_mfma_f32_16x16x32_bf16 v[14:17], v[14:17], v[144:147], v[10:13]
	v_mfma_f32_16x16x32_bf16 v[10:13], v[138:141], v[144:147], v[134:137]
	v_mfma_f32_16x16x32_bf16 v[6:9], v[198:201], v[144:147], v[6:9]
	s_nop 1
	v_lshlrev_b64 v[134:135], 10, v[132:133]
	v_lshl_add_u64 v[136:137], s[30:31], 0, v[134:135]
	v_lshl_add_u64 v[134:135], v[132:133], 1, s[6:7]
	v_mfma_f32_16x16x32_bf16 v[2:5], v[150:153], v[144:147], v[2:5]
	s_and_saveexec_b64 s[16:17], s[42:43]
	s_xor_b64 s[16:17], exec, s[16:17]
	s_cbranch_execz .LBB0_437
	s_cmpk_gt_u32 s62, 0x5ff
	s_mov_b64 s[36:37], -1
	s_cbranch_scc0 .LBB0_427
	s_and_saveexec_b64 s[36:37], s[0:1]
	s_cbranch_execz .LBB0_426
	v_mov_b32_e32 v131, v1
	v_lshl_add_u64 v[138:139], v[130:131], 1, v[136:137]
	v_add_co_u32_e32 v138, vcc, 0x305f000, v138
	v_cvt_pk_bf16_f32 v140, v126, v127
	v_cvt_pk_bf16_f32 v141, v128, v129
	v_addc_co_u32_e32 v139, vcc, 0, v139, vcc
	global_store_dwordx2 v[138:139], v[140:141], off offset:1024

; #define TIDX opaque_tid()
; template <class Epi>
; DEVI void gemm_tile256b(const bf16_t* __restrict__ A, int lda, const bf16_t* __restrict__ Bt, int K,
;                         int m0, int n0, char* smem, Epi epi) {
;   const int tid = TIDX, lane = tid & 63, wave = tid >> 6;
;   const int wm = wave >> 1, wn = wave & 1, l15 = lane & 15, quad = lane >> 4;
;   f32x4 acc[8][4];
; #pragma unroll
;   for (int i = 0; i < 8; ++i)
; #pragma unroll
;     for (int j = 0; j < 4; ++j) acc[i][j] = f32x4{0.f, 0.f, 0.f, 0.f};
;   const int lrow = tid >> 3, lkc = tid & 7;
;   const bf16_t* ag = A + (size_t)(m0 + lrow) * lda + lkc * 8;
;   const int kb32 = K >> 5;
;   const bf16_t* bp = Bt + ((size_t)((n0 + wn * 64) >> 4) * kb32) * 512 + lane * 8;
;   u32x4 ra[8];
;   bf16x8 b0[4], b1[4];
;   const int lds_w = lrow * 128 + ((lkc ^ (lrow & 7)) << 4);
;   const int nk = K >> 6;
;   const int sw = (quad ^ (l15 & 7)) << 4;
;   const int a_rd = (wm * 128 + l15) * 128 + sw;
; #pragma unroll
;   for (int i = 0; i < 8; ++i) ra[i] = *(const u32x4*)(ag + (size_t)(i * 32) * lda);
; #pragma unroll
;   for (int i = 0; i < 4; ++i) b0[i] = *(const bf16x8*)(bp + ((size_t)i * kb32) * 512);
; #pragma unroll
;   for (int i = 0; i < 8; ++i) *(u32x4*)(smem + lds_w + i * 4096) = ra[i];
;   __syncthreads();
;     ...
;         mt = t / nnt;
;         nt = t - mt * nnt;
.LBB0_1365:
	s_and_b64 vcc, exec, s[0:1]
	s_cbranch_vccz .LBB0_1348
	s_mul_hi_i32 s0, s13, 0x51eb851f
	s_lshr_b32 s1, s0, 31
	s_ashr_i32 s0, s0, 3
	s_add_i32 s0, s0, s1
	v_mov_b32_e32 v169, v206
	s_mul_i32 s1, s0, 0xffffffe7
	s_lshl_b32 s0, s0, 8
	s_add_i32 s1, s1, s13
	v_ashrrev_i32_e32 v7, 3, v169
	v_add_u32_e32 v2, s0, v7
	s_lshl_b32 s1, s1, 7
	v_ashrrev_i32_e32 v3, 31, v2
	v_lshlrev_b64 v[18:19], 11, v[2:3]
	v_lshlrev_b32_e32 v0, 4, v169
	v_and_or_b32 v168, v169, 64, s1
	v_lshl_add_u64 v[2:3], s[14:15], 0, v[18:19]
	v_and_b32_e32 v0, 0x70, v0
	v_ashrrev_i32_e32 v4, 4, v168
	v_lshl_add_u64 v[2:3], v[2:3], 0, v[0:1]
	v_ashrrev_i32_e32 v5, 31, v4
	v_lshlrev_b64 v[20:21], 15, v[4:5]
	v_add_co_u32_e32 v4, vcc, s54, v2
	global_load_dwordx4 v[22:25], v[2:3], off
	s_nop 0
	v_addc_co_u32_e32 v5, vcc, 0, v3, vcc
	global_load_dwordx4 v[26:29], v[4:5], off
	v_add_co_u32_e32 v4, vcc, s53, v2
	v_xor_b32_e32 v0, v7, v169
	s_nop 0
	v_addc_co_u32_e32 v5, vcc, 0, v3, vcc
	global_load_dwordx4 v[30:33], v[4:5], off
	v_add_co_u32_e32 v4, vcc, s52, v2
	v_bfe_u32 v170, v169, 4, 2
	s_nop 0
	v_addc_co_u32_e32 v5, vcc, 0, v3, vcc
	global_load_dwordx4 v[34:37], v[4:5], off
	v_add_co_u32_e32 v4, vcc, s56, v2
	v_lshlrev_b32_e32 v0, 4, v0
	s_nop 0
	v_addc_co_u32_e32 v5, vcc, 0, v3, vcc
	global_load_dwordx4 v[38:41], v[4:5], off
	v_add_co_u32_e32 v4, vcc, s57, v2
	v_and_b32_e32 v54, 0x70, v0
	s_nop 0
	v_addc_co_u32_e32 v5, vcc, 0, v3, vcc
	global_load_dwordx4 v[42:45], v[4:5], off
	v_add_co_u32_e32 v4, vcc, s3, v2
	v_bitop3_b32 v0, v170, v169, 7 bitop3:0x78
	s_nop 0
	v_addc_co_u32_e32 v5, vcc, 0, v3, vcc
	v_add_co_u32_e32 v2, vcc, s19, v2
	v_readlane_b32 s10, v247, 19
	v_and_b32_e32 v6, 63, v169
	v_lshlrev_b32_e32 v56, 4, v0
	v_lshlrev_b32_e32 v0, 7, v169
	v_addc_co_u32_e32 v3, vcc, 0, v3, vcc
	v_readlane_b32 s11, v247, 20
	v_and_b32_e32 v57, 0xffffc780, v0
	global_load_dwordx4 v[46:49], v[4:5], off
	global_load_dwordx4 v[50:53], v[2:3], off
	v_lshl_add_u64 v[2:3], s[10:11], 0, v[20:21]
	v_lshlrev_b32_e32 v0, 4, v6
	v_lshl_add_u64 v[162:163], v[2:3], 0, v[0:1]
	s_mov_b32 s1, 0x8000
	v_add_co_u32_e32 v6, vcc, s1, v162
	v_lshlrev_b32_e32 v58, 7, v7
	s_nop 0
	v_addc_co_u32_e32 v7, vcc, 0, v163, vcc
	global_load_dwordx4 v[2:5], v[162:163], off
	global_load_dwordx4 v[14:17], v[6:7], off
	v_add_co_u32_e32 v6, vcc, s54, v162
	s_mov_b32 s10, 0x18000
	s_nop 0
	v_addc_co_u32_e32 v7, vcc, 0, v163, vcc
	global_load_dwordx4 v[10:13], v[6:7], off
	v_add_co_u32_e32 v6, vcc, s10, v162
	v_and_b32_e32 v55, 7, v169
	s_nop 0
	v_addc_co_u32_e32 v7, vcc, 0, v163, vcc
	global_load_dwordx4 v[6:9], v[6:7], off
	v_add3_u32 v172, 32, v54, v58
	v_or_b32_e32 v20, v20, v0
	v_lshl_or_b32 v18, v55, 4, v18
	v_mov_b32_e32 v90, 0
	s_waitcnt vmcnt(11)
	ds_write_b128 v172, v[22:25]
	s_waitcnt vmcnt(10)
	ds_write_b128 v172, v[26:29] offset:4096
	s_waitcnt vmcnt(9)
	ds_write_b128 v172, v[30:33] offset:8192
	s_waitcnt vmcnt(8)
	ds_write_b128 v172, v[34:37] offset:12288
	s_waitcnt vmcnt(7)
	ds_write_b128 v172, v[38:41] offset:16384
	s_waitcnt vmcnt(6)
	ds_write_b128 v172, v[42:45] offset:20480
	s_waitcnt vmcnt(5)
	ds_write_b128 v172, v[46:49] offset:24576
	s_waitcnt vmcnt(4)
	ds_write_b128 v172, v[50:53] offset:28672
	v_or_b32_e32 v173, v56, v57
	v_bitop3_b32 v171, v56, 64, v57 bitop3:0x36
	v_lshl_add_u64 v[164:165], s[84:85], 0, v[20:21]
	v_lshl_add_u64 v[166:167], s[84:85], 0, v[18:19]
	v_mov_b32_e32 v91, v90
	v_mov_b32_e32 v92, v90
	v_mov_b32_e32 v93, v90
	v_mov_b32_e32 v110, v90
	v_mov_b32_e32 v111, v90
	v_mov_b32_e32 v112, v90
	v_mov_b32_e32 v113, v90
	v_mov_b32_e32 v134, v90
	v_mov_b32_e32 v135, v90
	v_mov_b32_e32 v136, v90
	v_mov_b32_e32 v137, v90
	v_mov_b32_e32 v138, v90
	v_mov_b32_e32 v139, v90
	v_mov_b32_e32 v140, v90
	v_mov_b32_e32 v141, v90
	v_mov_b32_e32 v142, v90
	v_mov_b32_e32 v143, v90
	v_mov_b32_e32 v144, v90
	v_mov_b32_e32 v145, v90
	v_mov_b32_e32 v34, v90
	v_mov_b32_e32 v35, v90
	v_mov_b32_e32 v36, v90
	v_mov_b32_e32 v37, v90
	v_mov_b32_e32 v38, v90
	v_mov_b32_e32 v39, v90
	v_mov_b32_e32 v40, v90
	v_mov_b32_e32 v41, v90
	v_mov_b32_e32 v30, v90
	v_mov_b32_e32 v31, v90
	v_mov_b32_e32 v32, v90
	v_mov_b32_e32 v33, v90
	v_mov_b32_e32 v42, v90
	v_mov_b32_e32 v43, v90
	v_mov_b32_e32 v44, v90
	v_mov_b32_e32 v45, v90
	v_mov_b32_e32 v18, v90
	v_mov_b32_e32 v19, v90
	v_mov_b32_e32 v20, v90
	v_mov_b32_e32 v21, v90
	v_mov_b32_e32 v22, v90
	v_mov_b32_e32 v23, v90
	v_mov_b32_e32 v24, v90
	v_mov_b32_e32 v25, v90
	v_mov_b32_e32 v26, v90
	v_mov_b32_e32 v27, v90
	v_mov_b32_e32 v28, v90
	v_mov_b32_e32 v29, v90
	v_mov_b32_e32 v54, v90
	v_mov_b32_e32 v55, v90
	v_mov_b32_e32 v56, v90
	v_mov_b32_e32 v57, v90
	v_mov_b32_e32 v58, v90
	v_mov_b32_e32 v59, v90
	v_mov_b32_e32 v60, v90
	v_mov_b32_e32 v61, v90
	v_mov_b32_e32 v50, v90
	v_mov_b32_e32 v51, v90
	v_mov_b32_e32 v52, v90
	v_mov_b32_e32 v53, v90
	v_mov_b32_e32 v46, v90
	v_mov_b32_e32 v47, v90
	v_mov_b32_e32 v48, v90
	v_mov_b32_e32 v49, v90
	v_mov_b32_e32 v66, v90
	v_mov_b32_e32 v67, v90
	v_mov_b32_e32 v68, v90
	v_mov_b32_e32 v69, v90
	v_mov_b32_e32 v62, v90
	v_mov_b32_e32 v63, v90
	v_mov_b32_e32 v64, v90
	v_mov_b32_e32 v65, v90
	v_mov_b32_e32 v70, v90
	v_mov_b32_e32 v71, v90
	v_mov_b32_e32 v72, v90
	v_mov_b32_e32 v73, v90
	v_mov_b32_e32 v74, v90
	v_mov_b32_e32 v75, v90
	v_mov_b32_e32 v76, v90
	v_mov_b32_e32 v77, v90
	v_mov_b32_e32 v78, v90
	v_mov_b32_e32 v79, v90
	v_mov_b32_e32 v80, v90
	v_mov_b32_e32 v81, v90
	v_mov_b32_e32 v82, v90
	v_mov_b32_e32 v83, v90
	v_mov_b32_e32 v84, v90
	v_mov_b32_e32 v85, v90
	v_mov_b32_e32 v86, v90
	v_mov_b32_e32 v87, v90
	v_mov_b32_e32 v88, v90
	v_mov_b32_e32 v89, v90
	v_mov_b32_e32 v94, v90
	v_mov_b32_e32 v95, v90
	v_mov_b32_e32 v96, v90
	v_mov_b32_e32 v97, v90
	v_mov_b32_e32 v98, v90
	v_mov_b32_e32 v99, v90
	v_mov_b32_e32 v100, v90
	v_mov_b32_e32 v101, v90
	v_mov_b32_e32 v102, v90
	v_mov_b32_e32 v103, v90
	v_mov_b32_e32 v104, v90
	v_mov_b32_e32 v105, v90
	v_mov_b32_e32 v106, v90
	v_mov_b32_e32 v107, v90
	v_mov_b32_e32 v108, v90
	v_mov_b32_e32 v109, v90
	v_mov_b32_e32 v114, v90
	v_mov_b32_e32 v115, v90
	v_mov_b32_e32 v116, v90
	v_mov_b32_e32 v117, v90
	v_mov_b32_e32 v118, v90
	v_mov_b32_e32 v119, v90
	v_mov_b32_e32 v120, v90
	v_mov_b32_e32 v121, v90
	v_mov_b32_e32 v122, v90
	v_mov_b32_e32 v123, v90
	v_mov_b32_e32 v124, v90
	v_mov_b32_e32 v125, v90
	v_mov_b32_e32 v126, v90
	v_mov_b32_e32 v127, v90
	v_mov_b32_e32 v128, v90
	v_mov_b32_e32 v129, v90
	v_mov_b32_e32 v130, v90
	v_mov_b32_e32 v131, v90
	v_mov_b32_e32 v132, v90
	v_mov_b32_e32 v133, v90
	s_mov_b32 s11, 0x2040000
	s_mov_b32 s13, 0x2048000
	s_mov_b32 s16, 0x2050000
	s_mov_b32 s17, 0x2058000
	s_waitcnt lgkmcnt(0)
	s_barrier
	s_add_i32 s98, s1, 0xffff8000
	s_and_b32 s98, s98, 0x8000
	s_add_i32 s98, s98, 32
	v_add_u32_e32 v226, s98, v173
	ds_read_b128 v[196:199], v226
	ds_read_b128 v[200:203], v226 offset:2048
; #define MFMA16(a, b, c) __builtin_amdgcn_mfma_f32_16x16x32_bf16((a), (b), (c), 0, 0, 0)
; template <class Epi>
; DEVI void gemm_tile256b(const bf16_t* __restrict__ A, int lda, const bf16_t* __restrict__ Bt, int K,
;                         int m0, int n0, char* smem, Epi epi) {
;     ...
;   for (int kt = 0; kt < nk; ++kt) {
;     const char* base = smem + (kt & 1) * 32768;
;     const bool more = kt + 1 < nk;
;     if (more) {
; #pragma unroll
;       for (int i = 0; i < 8; ++i) ra[i] = *(const u32x4*)(ag + (size_t)(i * 32) * lda + (kt + 1) * 64);
;     }
; #pragma unroll
;     for (int i = 0; i < 4; ++i) b1[i] = *(const bf16x8*)(bp + ((size_t)i * kb32 + kt * 2 + 1) * 512);
;     {
;       bf16x8 af[8];
; #pragma unroll
;       for (int i = 0; i < 8; ++i) af[i] = *(const bf16x8*)(base + a_rd + i * 2048);
; #pragma unroll
;       for (int mi = 0; mi < 8; ++mi)
; #pragma unroll
;         for (int ni = 0; ni < 4; ++ni) acc[mi][ni] = MFMA16(b0[ni], af[mi], acc[mi][ni]);
;     }
;     if (more) {
; #pragma unroll
;       for (int i = 0; i < 4; ++i) b0[i] = *(const bf16x8*)(bp + ((size_t)i * kb32 + kt * 2 + 2) * 512);
;     }
;     {
;       bf16x8 af[8];
; #pragma unroll
;       for (int i = 0; i < 8; ++i) af[i] = *(const bf16x8*)(base + ((a_rd + i * 2048) ^ 64));
; #pragma unroll
;       for (int mi = 0; mi < 8; ++mi)
; #pragma unroll
;         for (int ni = 0; ni < 4; ++ni) acc[mi][ni] = MFMA16(b1[ni], af[mi], acc[mi][ni]);
;     }
;     if (more) {
;       char* nb = smem + ((kt + 1) & 1) * 32768 + lds_w;
; #pragma unroll
;       for (int i = 0; i < 8; ++i) *(u32x4*)(nb + i * 4096) = ra[i];
;     }
;     __syncthreads();
;   }
.LBB0_1367:
	s_add_i32 s10, s1, 0xffff8000
	s_and_b32 s10, s10, 0x8000
	s_add_i32 s10, s10, 32
	v_add_u32_e32 v0, s10, v173
	v_lshl_add_u64 v[154:155], v[164:165], 0, s[28:29]
	v_add_co_u32_e32 v156, vcc, s11, v154
	s_waitcnt vmcnt(3) lgkmcnt(1)
	v_mfma_f32_16x16x32_bf16 v[130:133], v[2:5], v[196:199], v[130:133]
	v_addc_co_u32_e32 v157, vcc, 0, v155, vcc
	v_add_co_u32_e32 v158, vcc, s13, v154
	s_waitcnt vmcnt(2)
	v_mfma_f32_16x16x32_bf16 v[126:129], v[14:17], v[196:199], v[126:129]
	v_addc_co_u32_e32 v159, vcc, 0, v155, vcc
	v_add_co_u32_e32 v160, vcc, s16, v154
	s_waitcnt vmcnt(1)
	v_mfma_f32_16x16x32_bf16 v[122:125], v[10:13], v[196:199], v[122:125]
	v_addc_co_u32_e32 v161, vcc, 0, v155, vcc
	v_add_co_u32_e32 v182, vcc, s17, v154
	s_waitcnt vmcnt(0)
	v_mfma_f32_16x16x32_bf16 v[118:121], v[6:9], v[196:199], v[118:121]
	v_addc_co_u32_e32 v183, vcc, 0, v155, vcc
	s_waitcnt lgkmcnt(0)
	v_mfma_f32_16x16x32_bf16 v[114:117], v[2:5], v[200:203], v[114:117]
	v_lshl_add_u64 v[164:165], v[164:165], 0, s[64:65]
	v_mfma_f32_16x16x32_bf16 v[106:109], v[14:17], v[200:203], v[106:109]
	v_mfma_f32_16x16x32_bf16 v[102:105], v[10:13], v[200:203], v[102:105]
	s_nop 0
	v_mfma_f32_16x16x32_bf16 v[98:101], v[6:9], v[200:203], v[98:101]
	ds_read_b128 v[146:149], v0 offset:4096
	ds_read_b128 v[150:153], v0 offset:6144
	s_waitcnt lgkmcnt(1)
	v_mfma_f32_16x16x32_bf16 v[94:97], v[2:5], v[146:149], v[94:97]
	v_lshl_add_u64 v[166:167], v[166:167], 0, s[60:61]
	v_mfma_f32_16x16x32_bf16 v[86:89], v[14:17], v[146:149], v[86:89]
	v_mfma_f32_16x16x32_bf16 v[82:85], v[10:13], v[146:149], v[82:85]
	s_nop 0
	v_mfma_f32_16x16x32_bf16 v[78:81], v[6:9], v[146:149], v[78:81]
	s_nop 0
	s_waitcnt lgkmcnt(0)
	v_mfma_f32_16x16x32_bf16 v[74:77], v[2:5], v[150:153], v[74:77]
	v_mfma_f32_16x16x32_bf16 v[70:73], v[14:17], v[150:153], v[70:73]
	v_mfma_f32_16x16x32_bf16 v[62:65], v[10:13], v[150:153], v[62:65]
	v_mfma_f32_16x16x32_bf16 v[66:69], v[6:9], v[150:153], v[66:69]
	ds_read_b128 v[146:149], v0 offset:8192
	ds_read_b128 v[150:153], v0 offset:10240
	s_waitcnt lgkmcnt(1)
	v_mfma_f32_16x16x32_bf16 v[46:49], v[2:5], v[146:149], v[46:49]
	v_mfma_f32_16x16x32_bf16 v[50:53], v[14:17], v[146:149], v[50:53]
	v_mfma_f32_16x16x32_bf16 v[58:61], v[10:13], v[146:149], v[58:61]
	v_mfma_f32_16x16x32_bf16 v[54:57], v[6:9], v[146:149], v[54:57]
	s_waitcnt lgkmcnt(0)
	v_mfma_f32_16x16x32_bf16 v[26:29], v[2:5], v[150:153], v[26:29]
	v_mfma_f32_16x16x32_bf16 v[22:25], v[14:17], v[150:153], v[22:25]
	v_mfma_f32_16x16x32_bf16 v[18:21], v[10:13], v[150:153], v[18:21]
	v_mfma_f32_16x16x32_bf16 v[42:45], v[6:9], v[150:153], v[42:45]
	ds_read_b128 v[146:149], v0 offset:12288
	ds_read_b128 v[150:153], v0 offset:14336
	v_add_u32_e32 v0, s10, v171
	s_and_b32 s10, s1, 0x8000
	s_waitcnt lgkmcnt(1)
	v_mfma_f32_16x16x32_bf16 v[30:33], v[2:5], v[146:149], v[30:33]
	s_add_i32 s1, s1, 0x8000
	s_cmp_eq_u32 s1, 0x80000
	v_mfma_f32_16x16x32_bf16 v[38:41], v[14:17], v[146:149], v[38:41]
	v_mfma_f32_16x16x32_bf16 v[34:37], v[10:13], v[146:149], v[34:37]
	v_mfma_f32_16x16x32_bf16 v[142:145], v[6:9], v[146:149], v[142:145]
	global_load_dwordx4 v[146:149], v[156:157], off offset:1024
	ds_read_b128 v[174:177], v0
	ds_read_b128 v[178:181], v0 offset:2048
	s_waitcnt lgkmcnt(2)
	v_mfma_f32_16x16x32_bf16 v[138:141], v[2:5], v[150:153], v[138:141]
	global_load_dwordx4 v[2:5], v[156:157], off offset:2048
	v_mfma_f32_16x16x32_bf16 v[134:137], v[14:17], v[150:153], v[134:137]
	v_mfma_f32_16x16x32_bf16 v[110:113], v[10:13], v[150:153], v[110:113]
	v_mfma_f32_16x16x32_bf16 v[90:93], v[6:9], v[150:153], v[90:93]
	global_load_dwordx4 v[150:153], v[158:159], off offset:1024
	global_load_dwordx4 v[14:17], v[158:159], off offset:2048
	global_load_dwordx4 v[154:157], v[160:161], off offset:1024
	global_load_dwordx4 v[10:13], v[160:161], off offset:2048
	s_nop 0
	global_load_dwordx4 v[158:161], v[182:183], off offset:1024
	global_load_dwordx4 v[6:9], v[182:183], off offset:2048
	v_lshrrev_b32_e32 v195, 6, v206
	v_lshl_add_u64 v[190:191], v[166:167], 0, s[28:29]
	v_lshrrev_b32_e32 v194, 3, v206
	v_readfirstlane_b32 s99, v195
	v_and_b32_e32 v194, 7, v194
	s_and_b32 s98, s1, 0x8000
	s_xor_b32 s98, s98, 0x8000
	v_lshlrev_b32_e32 v194, 4, v194
	s_lshl_b32 s99, s99, 10
	v_xor_b32_e32 v190, v194, v190
	s_add_u32 s98, s98, s99
	s_add_u32 s98, s98, 32
	s_mov_b32 s101, 0
	s_mov_b32 s100, 0x0
	v_lshl_add_u64 v[192:193], v[190:191], 0, s[100:101]
	s_mov_b32 m0, s98
	s_nop 0
	global_load_lds_dwordx4 v[192:193], off
	s_add_u32 s100, s54, 0x0
	v_lshl_add_u64 v[192:193], v[190:191], 0, s[100:101]
	s_add_u32 m0, s98, 0x1000
	s_nop 0
	global_load_lds_dwordx4 v[192:193], off
	s_add_u32 s100, s53, 0x0
	v_lshl_add_u64 v[192:193], v[190:191], 0, s[100:101]
	s_add_u32 m0, s98, 0x2000
	s_nop 0
	global_load_lds_dwordx4 v[192:193], off
	s_add_u32 s100, s52, 0x0
	v_lshl_add_u64 v[192:193], v[190:191], 0, s[100:101]
	s_add_u32 m0, s98, 0x3000
	s_nop 0
	global_load_lds_dwordx4 v[192:193], off
	s_add_u32 s100, s56, 0x0
	v_lshl_add_u64 v[192:193], v[190:191], 0, s[100:101]
	s_add_u32 m0, s98, 0x4000
	s_nop 0
	global_load_lds_dwordx4 v[192:193], off
	s_add_u32 s100, s57, 0x0
	v_lshl_add_u64 v[192:193], v[190:191], 0, s[100:101]
	s_add_u32 m0, s98, 0x5000
	s_nop 0
	global_load_lds_dwordx4 v[192:193], off
	s_add_u32 s100, s3, 0x0
	v_lshl_add_u64 v[192:193], v[190:191], 0, s[100:101]
	s_add_u32 m0, s98, 0x6000
	s_nop 0
	global_load_lds_dwordx4 v[192:193], off
	s_add_u32 s100, s19, 0x0
	v_lshl_add_u64 v[192:193], v[190:191], 0, s[100:101]
	s_add_u32 m0, s98, 0x7000
	s_nop 0
	global_load_lds_dwordx4 v[192:193], off
	s_waitcnt vmcnt(15) lgkmcnt(1)
; #define MFMA16(a, b, c) __builtin_amdgcn_mfma_f32_16x16x32_bf16((a), (b), (c), 0, 0, 0)
; template <class Epi>
; DEVI void gemm_tile256b(const bf16_t* __restrict__ A, int lda, const bf16_t* __restrict__ Bt, int K,
;                         int m0, int n0, char* smem, Epi epi) {
;     ...
;   for (int kt = 0; kt < nk; ++kt) {
;     const char* base = smem + (kt & 1) * 32768;
;     const bool more = kt + 1 < nk;
;     if (more) {
; #pragma unroll
;       for (int i = 0; i < 8; ++i) ra[i] = *(const u32x4*)(ag + (size_t)(i * 32) * lda + (kt + 1) * 64);
;     }
; #pragma unroll
;     for (int i = 0; i < 4; ++i) b1[i] = *(const bf16x8*)(bp + ((size_t)i * kb32 + kt * 2 + 1) * 512);
;     {
;       bf16x8 af[8];
; #pragma unroll
;       for (int i = 0; i < 8; ++i) af[i] = *(const bf16x8*)(base + a_rd + i * 2048);
; #pragma unroll
;       for (int mi = 0; mi < 8; ++mi)
; #pragma unroll
;         for (int ni = 0; ni < 4; ++ni) acc[mi][ni] = MFMA16(b0[ni], af[mi], acc[mi][ni]);
;     }
;     if (more) {
; #pragma unroll
;       for (int i = 0; i < 4; ++i) b0[i] = *(const bf16x8*)(bp + ((size_t)i * kb32 + kt * 2 + 2) * 512);
;     }
;     {
;       bf16x8 af[8];
; #pragma unroll
;       for (int i = 0; i < 8; ++i) af[i] = *(const bf16x8*)(base + ((a_rd + i * 2048) ^ 64));
; #pragma unroll
;       for (int mi = 0; mi < 8; ++mi)
; #pragma unroll
;         for (int ni = 0; ni < 4; ++ni) acc[mi][ni] = MFMA16(b1[ni], af[mi], acc[mi][ni]);
;     }
;     if (more) {
;       char* nb = smem + ((kt + 1) & 1) * 32768 + lds_w;
; #pragma unroll
;       for (int i = 0; i < 8; ++i) *(u32x4*)(nb + i * 4096) = ra[i];
;     }
;     __syncthreads();
;   }
	v_mfma_f32_16x16x32_bf16 v[130:133], v[146:149], v[174:177], v[130:133]
	s_waitcnt vmcnt(13)
	v_mfma_f32_16x16x32_bf16 v[126:129], v[150:153], v[174:177], v[126:129]
	s_waitcnt vmcnt(11)
	v_mfma_f32_16x16x32_bf16 v[122:125], v[154:157], v[174:177], v[122:125]
	s_waitcnt vmcnt(9)
	v_mfma_f32_16x16x32_bf16 v[118:121], v[158:161], v[174:177], v[118:121]
	s_waitcnt lgkmcnt(0)
	v_mfma_f32_16x16x32_bf16 v[114:117], v[146:149], v[178:181], v[114:117]
	v_mfma_f32_16x16x32_bf16 v[106:109], v[150:153], v[178:181], v[106:109]
	v_mfma_f32_16x16x32_bf16 v[102:105], v[154:157], v[178:181], v[102:105]
	v_mfma_f32_16x16x32_bf16 v[98:101], v[158:161], v[178:181], v[98:101]
	ds_read_b128 v[174:177], v0 offset:4096
	ds_read_b128 v[178:181], v0 offset:6144
	s_waitcnt lgkmcnt(1)
	v_mfma_f32_16x16x32_bf16 v[94:97], v[146:149], v[174:177], v[94:97]
	v_mfma_f32_16x16x32_bf16 v[86:89], v[150:153], v[174:177], v[86:89]
	v_mfma_f32_16x16x32_bf16 v[82:85], v[154:157], v[174:177], v[82:85]
	v_mfma_f32_16x16x32_bf16 v[78:81], v[158:161], v[174:177], v[78:81]
	s_waitcnt lgkmcnt(0)
	v_mfma_f32_16x16x32_bf16 v[74:77], v[146:149], v[178:181], v[74:77]
	v_mfma_f32_16x16x32_bf16 v[70:73], v[150:153], v[178:181], v[70:73]
	v_mfma_f32_16x16x32_bf16 v[62:65], v[154:157], v[178:181], v[62:65]
	v_mfma_f32_16x16x32_bf16 v[66:69], v[158:161], v[178:181], v[66:69]
	ds_read_b128 v[178:181], v0 offset:8192
	ds_read_b128 v[182:185], v0 offset:10240
	s_waitcnt lgkmcnt(1)
	v_mfma_f32_16x16x32_bf16 v[46:49], v[146:149], v[178:181], v[46:49]
	v_mfma_f32_16x16x32_bf16 v[50:53], v[150:153], v[178:181], v[50:53]
	v_mfma_f32_16x16x32_bf16 v[58:61], v[154:157], v[178:181], v[58:61]
	v_mfma_f32_16x16x32_bf16 v[54:57], v[158:161], v[178:181], v[54:57]
	s_waitcnt lgkmcnt(0)
	v_mfma_f32_16x16x32_bf16 v[26:29], v[146:149], v[182:185], v[26:29]
	v_mfma_f32_16x16x32_bf16 v[22:25], v[150:153], v[182:185], v[22:25]
	v_mfma_f32_16x16x32_bf16 v[18:21], v[154:157], v[182:185], v[18:21]
	v_mfma_f32_16x16x32_bf16 v[42:45], v[158:161], v[182:185], v[42:45]
	ds_read_b128 v[178:181], v0 offset:12288
	ds_read_b128 v[182:185], v0 offset:14336
	s_nop 0
	s_nop 0
	s_nop 0
	s_nop 0
	s_nop 0
	s_waitcnt lgkmcnt(1)
	v_mfma_f32_16x16x32_bf16 v[30:33], v[146:149], v[178:181], v[30:33]
	v_mfma_f32_16x16x32_bf16 v[38:41], v[150:153], v[178:181], v[38:41]
	v_mfma_f32_16x16x32_bf16 v[34:37], v[154:157], v[178:181], v[34:37]
	s_waitcnt vmcnt(0) lgkmcnt(0)
	s_barrier
	s_add_i32 s98, s1, 0xffff8000
	s_and_b32 s98, s98, 0x8000
	s_add_i32 s98, s98, 32
	v_add_u32_e32 v226, s98, v173
	ds_read_b128 v[196:199], v226
	ds_read_b128 v[200:203], v226 offset:2048
	v_mfma_f32_16x16x32_bf16 v[142:145], v[158:161], v[178:181], v[142:145]
	v_mfma_f32_16x16x32_bf16 v[138:141], v[146:149], v[182:185], v[138:141]
	v_mfma_f32_16x16x32_bf16 v[134:137], v[150:153], v[182:185], v[134:137]
	v_mfma_f32_16x16x32_bf16 v[110:113], v[154:157], v[182:185], v[110:113]
	v_mfma_f32_16x16x32_bf16 v[90:93], v[158:161], v[182:185], v[90:93]
	s_cmp_eq_u32 s1, 0x80000
	s_cbranch_scc0 .LBB0_1367
	v_and_b32_e32 v228, 16, v206
	v_lshrrev_b32_e32 v229, 1, v228
	v_add_u32_e32 v228, v228, v229
	v_mov_b32_e32 v229, 0
	v_add_u32_e32 v0, 32, v173
	ds_read_b128 v[146:149], v0 offset:32768
	s_movk_i32 s1, 0x7000
	s_movk_i32 s10, 0x1800
	s_waitcnt lgkmcnt(0)
	v_mfma_f32_16x16x32_bf16 v[130:133], v[2:5], v[146:149], v[130:133]
	v_mfma_f32_16x16x32_bf16 v[150:153], v[14:17], v[146:149], v[126:129]
	v_mfma_f32_16x16x32_bf16 v[154:157], v[10:13], v[146:149], v[122:125]
	v_mfma_f32_16x16x32_bf16 v[146:149], v[6:9], v[146:149], v[118:121]
	s_nop 2
	ds_read_b128 v[118:121], v0 offset:34816
	s_waitcnt lgkmcnt(0)
	v_mfma_f32_16x16x32_bf16 v[158:161], v[2:5], v[118:121], v[114:117]
	s_nop 2
	ds_read_b128 v[114:117], v0 offset:36864
	s_waitcnt lgkmcnt(0)
	v_mfma_f32_16x16x32_bf16 v[94:97], v[2:5], v[114:117], v[94:97]
	v_mfma_f32_16x16x32_bf16 v[86:89], v[14:17], v[114:117], v[86:89]
	v_mfma_f32_16x16x32_bf16 v[82:85], v[10:13], v[114:117], v[82:85]
	v_mfma_f32_16x16x32_bf16 v[78:81], v[6:9], v[114:117], v[78:81]
	ds_read_b128 v[114:117], v0 offset:38912
	s_waitcnt lgkmcnt(0)
	v_mfma_f32_16x16x32_bf16 v[74:77], v[2:5], v[114:117], v[74:77]
	v_mfma_f32_16x16x32_bf16 v[70:73], v[14:17], v[114:117], v[70:73]
	v_mfma_f32_16x16x32_bf16 v[62:65], v[10:13], v[114:117], v[62:65]
	v_mfma_f32_16x16x32_bf16 v[66:69], v[6:9], v[114:117], v[66:69]
	ds_read_b128 v[114:117], v0 offset:40960
	s_waitcnt lgkmcnt(0)
	v_mfma_f32_16x16x32_bf16 v[172:175], v[6:9], v[114:117], v[54:57]
	s_nop 2
	ds_read_b128 v[54:57], v0 offset:43008
	s_waitcnt lgkmcnt(0)
	v_mfma_f32_16x16x32_bf16 v[176:179], v[6:9], v[54:57], v[42:45]
	s_nop 2
	ds_read_b128 v[42:45], v0 offset:45056
	s_waitcnt lgkmcnt(0)
	v_mfma_f32_16x16x32_bf16 v[190:193], v[10:13], v[42:45], v[34:37]
	s_nop 2
	ds_read_b128 v[34:37], v0 offset:47104
	v_add_u32_e32 v0, 32, v171
	v_mfma_f32_16x16x32_bf16 v[106:109], v[14:17], v[118:121], v[106:109]
	v_mfma_f32_16x16x32_bf16 v[50:53], v[14:17], v[114:117], v[50:53]
	v_mfma_f32_16x16x32_bf16 v[22:25], v[14:17], v[54:57], v[22:25]
	v_mfma_f32_16x16x32_bf16 v[180:183], v[14:17], v[42:45], v[38:41]
	s_waitcnt lgkmcnt(0)
; #define MFMA16(a, b, c) __builtin_amdgcn_mfma_f32_16x16x32_bf16((a), (b), (c), 0, 0, 0)
; template <class Epi>
; DEVI void gemm_tile256b(const bf16_t* __restrict__ A, int lda, const bf16_t* __restrict__ Bt, int K,
;                         int m0, int n0, char* smem, Epi epi) {
;     ...
;     {
;       bf16x8 af[8];
; #pragma unroll
;       for (int i = 0; i < 8; ++i) af[i] = *(const bf16x8*)(base + ((a_rd + i * 2048) ^ 64));
; #pragma unroll
;       for (int mi = 0; mi < 8; ++mi)
; #pragma unroll
;         for (int ni = 0; ni < 4; ++ni) acc[mi][ni] = MFMA16(b1[ni], af[mi], acc[mi][ni]);
;     }
;     if (more) {
;       char* nb = smem + ((kt + 1) & 1) * 32768 + lds_w;
; #pragma unroll
;       for (int i = 0; i < 8; ++i) *(u32x4*)(nb + i * 4096) = ra[i];
;     }
;     __syncthreads();
;   }
; #pragma unroll
;   for (int mi = 0; mi < 8; ++mi)
; #pragma unroll
;     for (int ni = 0; ni < 4; ++ni)
;       epi(m0 + wm * 128 + mi * 16 + l15, n0 + wn * 64 + ni * 16 + quad * 4, acc[mi][ni]);
;   DEVI void operator()(int m, int n, f32x4 v) const {
;     if (m >= L) return;
;     if (n < 3072) {
;       *(u32x2*)(raw + (size_t)m * 3072 + n) = u32x2{pack2(v[0], v[1]), pack2(v[2], v[3])};
;     } else if (n < 3088) {
;       *(f32x4*)(ba + (size_t)m * 16 + (n - 3072)) = v;
;     }
	v_mfma_f32_16x16x32_bf16 v[134:137], v[14:17], v[34:37], v[134:137]
	v_add_co_u32_e32 v14, vcc, s1, v162
	s_mov_b32 s1, 0xf000
	s_nop 0
	v_addc_co_u32_e32 v15, vcc, 0, v163, vcc
	v_mfma_f32_16x16x32_bf16 v[102:105], v[10:13], v[118:121], v[102:105]
	global_load_dwordx4 v[14:17], v[14:15], off offset:3072
	v_mfma_f32_16x16x32_bf16 v[46:49], v[2:5], v[114:117], v[46:49]
	v_mfma_f32_16x16x32_bf16 v[164:167], v[10:13], v[114:117], v[58:61]
	v_mfma_f32_16x16x32_bf16 v[26:29], v[2:5], v[54:57], v[26:29]
	v_mfma_f32_16x16x32_bf16 v[18:21], v[10:13], v[54:57], v[18:21]
	v_mfma_f32_16x16x32_bf16 v[30:33], v[2:5], v[42:45], v[30:33]
	v_mfma_f32_16x16x32_bf16 v[2:5], v[2:5], v[34:37], v[138:141]
	v_mfma_f32_16x16x32_bf16 v[138:141], v[10:13], v[34:37], v[110:113]
	v_add_co_u32_e32 v10, vcc, s1, v162
	s_mov_b32 s1, 0x17000
	s_nop 0
	v_addc_co_u32_e32 v11, vcc, 0, v163, vcc
	global_load_dwordx4 v[10:13], v[10:11], off offset:3072
	v_mfma_f32_16x16x32_bf16 v[98:101], v[6:9], v[118:121], v[98:101]
	v_mfma_f32_16x16x32_bf16 v[142:145], v[6:9], v[42:45], v[142:145]
	v_mfma_f32_16x16x32_bf16 v[194:197], v[6:9], v[34:37], v[90:93]
	ds_read_b128 v[6:9], v0 offset:32768
	v_add_co_u32_e32 v34, vcc, s1, v162
	s_mov_b32 s1, 0x1f000
	s_nop 0
	v_addc_co_u32_e32 v35, vcc, 0, v163, vcc
	global_load_dwordx4 v[198:201], v[34:35], off offset:3072
	v_add_co_u32_e32 v34, vcc, s1, v162
	s_waitcnt vmcnt(1) lgkmcnt(0)
	v_mfma_f32_16x16x32_bf16 v[122:125], v[10:13], v[6:9], v[150:153]
	v_addc_co_u32_e32 v35, vcc, 0, v163, vcc
	s_nop 1
	global_load_dwordx4 v[150:153], v[34:35], off offset:3072
	v_mfma_f32_16x16x32_bf16 v[126:129], v[14:17], v[6:9], v[130:133]
	s_waitcnt vmcnt(1)
	v_mfma_f32_16x16x32_bf16 v[118:121], v[198:201], v[6:9], v[154:157]
	s_nop 0
	v_lshl_or_b32 v130, v170, 2, v168
	s_waitcnt vmcnt(0)
	v_mfma_f32_16x16x32_bf16 v[114:117], v[150:153], v[6:9], v[146:149]
	ds_read_b128 v[6:9], v0 offset:34816
	s_nop 1
	ds_read_b128 v[146:149], v0 offset:47104
	s_waitcnt lgkmcnt(1)
	v_mfma_f32_16x16x32_bf16 v[110:113], v[14:17], v[6:9], v[158:161]
	v_mfma_f32_16x16x32_bf16 v[106:109], v[10:13], v[6:9], v[106:109]
	v_mfma_f32_16x16x32_bf16 v[102:105], v[198:201], v[6:9], v[102:105]
	v_mfma_f32_16x16x32_bf16 v[98:101], v[150:153], v[6:9], v[98:101]
	ds_read_b128 v[6:9], v0 offset:36864
	s_waitcnt lgkmcnt(0)
	v_mfma_f32_16x16x32_bf16 v[94:97], v[14:17], v[6:9], v[94:97]
	v_mfma_f32_16x16x32_bf16 v[90:93], v[10:13], v[6:9], v[86:89]
	v_mfma_f32_16x16x32_bf16 v[86:89], v[198:201], v[6:9], v[82:85]
	v_mfma_f32_16x16x32_bf16 v[82:85], v[150:153], v[6:9], v[78:81]
	ds_read_b128 v[6:9], v0 offset:38912
	s_waitcnt lgkmcnt(0)
	v_mfma_f32_16x16x32_bf16 v[78:81], v[14:17], v[6:9], v[74:77]
	v_mfma_f32_16x16x32_bf16 v[74:77], v[10:13], v[6:9], v[70:73]
	v_mfma_f32_16x16x32_bf16 v[70:73], v[198:201], v[6:9], v[62:65]
	v_mfma_f32_16x16x32_bf16 v[66:69], v[150:153], v[6:9], v[66:69]
	ds_read_b128 v[6:9], v0 offset:40960
	s_waitcnt lgkmcnt(0)
	v_mfma_f32_16x16x32_bf16 v[62:65], v[14:17], v[6:9], v[46:49]
	v_mfma_f32_16x16x32_bf16 v[58:61], v[10:13], v[6:9], v[50:53]
	v_mfma_f32_16x16x32_bf16 v[54:57], v[198:201], v[6:9], v[164:167]
	v_mfma_f32_16x16x32_bf16 v[50:53], v[150:153], v[6:9], v[172:175]
	ds_read_b128 v[6:9], v0 offset:43008
	s_waitcnt lgkmcnt(0)
	v_mfma_f32_16x16x32_bf16 v[46:49], v[14:17], v[6:9], v[26:29]
	v_mfma_f32_16x16x32_bf16 v[42:45], v[10:13], v[6:9], v[22:25]
	v_mfma_f32_16x16x32_bf16 v[38:41], v[198:201], v[6:9], v[18:21]
	v_mfma_f32_16x16x32_bf16 v[34:37], v[150:153], v[6:9], v[176:179]
	ds_read_b128 v[6:9], v0 offset:45056
	v_and_b32_e32 v0, 0xffffff80, v169
	v_add_u32_e32 v0, s0, v0
	v_and_or_b32 v132, v169, 15, v0
	v_ashrrev_i32_e32 v133, 31, v132
	s_waitcnt lgkmcnt(0)
	v_mfma_f32_16x16x32_bf16 v[30:33], v[14:17], v[6:9], v[30:33]
	s_movk_i32 s0, 0x4010
	v_cmp_gt_i32_e64 s[0:1], s0, v132
	v_mfma_f32_16x16x32_bf16 v[14:17], v[14:17], v[146:149], v[2:5]
	s_barrier
	s_nop 1
	v_lshlrev_b64 v[2:3], 6, v[132:133]
	v_mfma_f32_16x16x32_bf16 v[26:29], v[10:13], v[6:9], v[180:183]
	v_mfma_f32_16x16x32_bf16 v[10:13], v[10:13], v[146:149], v[134:137]
	s_nop 2
	v_lshl_add_u64 v[136:137], s[6:7], 0, v[2:3]
	v_mov_b64_e32 v[2:3], s[30:31]
	v_mfma_f32_16x16x32_bf16 v[22:25], v[198:201], v[6:9], v[190:193]
	v_mad_i64_i32 v[134:135], s[10:11], v132, s10, v[2:3]
	v_mfma_f32_16x16x32_bf16 v[18:21], v[150:153], v[6:9], v[142:145]
	v_mfma_f32_16x16x32_bf16 v[6:9], v[198:201], v[146:149], v[138:141]
	v_mfma_f32_16x16x32_bf16 v[2:5], v[150:153], v[146:149], v[194:197]
	s_and_saveexec_b64 s[10:11], s[0:1]
	s_cbranch_execz .LBB0_1375
	s_movk_i32 s13, 0xbff
	v_cmp_lt_i32_e32 vcc, s13, v130
	s_and_saveexec_b64 s[16:17], vcc
	s_xor_b64 s[16:17], exec, s[16:17]
	s_cbranch_execz .LBB0_1373
	s_movk_i32 s13, 0xc10
	v_cmp_gt_u32_e32 vcc, s13, v168
	s_and_saveexec_b64 s[34:35], vcc
	s_cbranch_execz .LBB0_1372
	v_mov_b32_e32 v131, v1
	v_lshl_add_u64 v[138:139], v[130:131], 2, v[136:137]
	v_add_co_u32_e32 v138, vcc, 0xffffd000, v138
	s_nop 1
	v_addc_co_u32_e32 v139, vcc, -1, v139, vcc
	global_store_dwordx4 v[138:139], v[126:129], off

; #define TIDX opaque_tid()
; template <class Epi>
; DEVI void gemm_tile256b(const bf16_t* __restrict__ A, int lda, const bf16_t* __restrict__ Bt, int K,
;                         int m0, int n0, char* smem, Epi epi) {
;   const int tid = TIDX, lane = tid & 63, wave = tid >> 6;
;   const int wm = wave >> 1, wn = wave & 1, l15 = lane & 15, quad = lane >> 4;
;   f32x4 acc[8][4];
; #pragma unroll
;   for (int i = 0; i < 8; ++i)
; #pragma unroll
;     for (int j = 0; j < 4; ++j) acc[i][j] = f32x4{0.f, 0.f, 0.f, 0.f};
;   const int lrow = tid >> 3, lkc = tid & 7;
;   const bf16_t* ag = A + (size_t)(m0 + lrow) * lda + lkc * 8;
;   const int kb32 = K >> 5;
;   const bf16_t* bp = Bt + ((size_t)((n0 + wn * 64) >> 4) * kb32) * 512 + lane * 8;
;   u32x4 ra[8];
;   bf16x8 b0[4], b1[4];
;   const int lds_w = lrow * 128 + ((lkc ^ (lrow & 7)) << 4);
;   const int nk = K >> 6;
;   const int sw = (quad ^ (l15 & 7)) << 4;
;   const int a_rd = (wm * 128 + l15) * 128 + sw;
; #pragma unroll
;   for (int i = 0; i < 8; ++i) ra[i] = *(const u32x4*)(ag + (size_t)(i * 32) * lda);
; #pragma unroll
;   for (int i = 0; i < 4; ++i) b0[i] = *(const bf16x8*)(bp + ((size_t)i * kb32) * 512);
; #pragma unroll
;   for (int i = 0; i < 8; ++i) *(u32x4*)(smem + lds_w + i * 4096) = ra[i];
;   __syncthreads();
;     ...
;       if (xmap) {
;         const int s_ = t >> 6, w_ = t & 63, spr = nnt >> 3;
;         const int sm = s_ / spr, sn = s_ - sm * spr;
;         mt = sm * 8 + (w_ >> 3);
;         nt = sn * 8 + (w_ & 7);
.LBB0_1837:
	v_mov_b32_e32 v168, v206
	s_lshl_b32 s0, s13, 8
	s_lshl_b32 s1, s17, 7
	v_ashrrev_i32_e32 v7, 3, v168
	v_add_u32_e32 v2, s0, v7
	v_ashrrev_i32_e32 v3, 31, v2
	v_lshlrev_b64 v[18:19], 13, v[2:3]
	v_lshlrev_b32_e32 v0, 4, v168
	v_and_or_b32 v170, v168, 64, s1
	v_lshl_add_u64 v[2:3], s[30:31], 0, v[18:19]
	v_and_b32_e32 v0, 0x70, v0
	v_ashrrev_i32_e32 v4, 4, v170
	v_lshl_add_u64 v[2:3], v[2:3], 0, v[0:1]
	v_ashrrev_i32_e32 v5, 31, v4
	v_lshlrev_b64 v[20:21], 17, v[4:5]
	v_add_co_u32_e32 v4, vcc, s56, v2
	s_mov_b32 s1, 0x80000
	s_nop 0
	v_addc_co_u32_e32 v5, vcc, 0, v3, vcc
	global_load_dwordx4 v[22:25], v[2:3], off
	global_load_dwordx4 v[26:29], v[4:5], off
	v_add_co_u32_e32 v4, vcc, s1, v2
	s_mov_b32 s1, 0xc0000
	s_nop 0
	v_addc_co_u32_e32 v5, vcc, 0, v3, vcc
	global_load_dwordx4 v[30:33], v[4:5], off
	v_add_co_u32_e32 v4, vcc, s1, v2
	s_mov_b32 s1, 0x100000
	s_nop 0
	v_addc_co_u32_e32 v5, vcc, 0, v3, vcc
	global_load_dwordx4 v[34:37], v[4:5], off
	v_add_co_u32_e32 v4, vcc, s1, v2
	s_mov_b32 s1, 0x140000
	s_nop 0
	v_addc_co_u32_e32 v5, vcc, 0, v3, vcc
	global_load_dwordx4 v[38:41], v[4:5], off
	v_add_co_u32_e32 v4, vcc, s1, v2
	s_mov_b32 s1, 0x180000
	s_nop 0
	v_addc_co_u32_e32 v5, vcc, 0, v3, vcc
	v_xor_b32_e32 v0, v7, v168
	global_load_dwordx4 v[42:45], v[4:5], off
	v_add_co_u32_e32 v4, vcc, s1, v2
	v_bfe_u32 v169, v168, 4, 2
	v_lshlrev_b32_e32 v0, 4, v0
	v_addc_co_u32_e32 v5, vcc, 0, v3, vcc
	s_mov_b32 s1, 0x1c0000
	v_and_b32_e32 v55, 0x70, v0
	v_bitop3_b32 v0, v169, v168, 7 bitop3:0x78
	v_add_co_u32_e32 v2, vcc, s1, v2
	v_and_b32_e32 v6, 63, v168
	v_lshlrev_b32_e32 v57, 4, v0
	v_lshlrev_b32_e32 v0, 7, v168
	v_addc_co_u32_e32 v3, vcc, 0, v3, vcc
	v_and_b32_e32 v58, 0xffffc780, v0
	global_load_dwordx4 v[46:49], v[4:5], off
	global_load_dwordx4 v[50:53], v[2:3], off
	v_lshl_add_u64 v[2:3], s[10:11], 0, v[20:21]
	v_lshlrev_b32_e32 v0, 4, v6
	v_lshl_add_u64 v[162:163], v[2:3], 0, v[0:1]
	v_add_co_u32_e32 v2, vcc, s53, v162
	global_load_dwordx4 v[14:17], v[162:163], off
	s_nop 0
	v_addc_co_u32_e32 v3, vcc, 0, v163, vcc
	global_load_dwordx4 v[10:13], v[2:3], off
	v_add_co_u32_e32 v2, vcc, s56, v162
	v_lshlrev_b32_e32 v54, 7, v7
	s_nop 0
	v_addc_co_u32_e32 v3, vcc, 0, v163, vcc
	global_load_dwordx4 v[6:9], v[2:3], off
	v_add_co_u32_e32 v2, vcc, s3, v162
	v_and_b32_e32 v56, 7, v168
	s_nop 0
	v_addc_co_u32_e32 v3, vcc, 0, v163, vcc
	global_load_dwordx4 v[2:5], v[2:3], off
	v_add3_u32 v172, 32, v55, v54
	v_or_b32_e32 v20, v20, v0
	v_lshl_or_b32 v18, v56, 4, v18
	v_mov_b32_e32 v126, 0
	v_or_b32_e32 v173, v57, v58
	v_bitop3_b32 v171, v57, 64, v58 bitop3:0x36
	s_waitcnt vmcnt(11)
	ds_write_b128 v172, v[22:25]
	s_waitcnt vmcnt(10)
	ds_write_b128 v172, v[26:29] offset:4096
	s_waitcnt vmcnt(9)
	ds_write_b128 v172, v[30:33] offset:8192
	s_waitcnt vmcnt(8)
	ds_write_b128 v172, v[34:37] offset:12288
	s_waitcnt vmcnt(7)
	ds_write_b128 v172, v[38:41] offset:16384
	s_waitcnt vmcnt(6)
	ds_write_b128 v172, v[42:45] offset:20480
	s_waitcnt vmcnt(5)
	ds_write_b128 v172, v[46:49] offset:24576
	s_waitcnt vmcnt(4)
	ds_write_b128 v172, v[50:53] offset:28672
	v_lshl_add_u64 v[164:165], s[84:85], 0, v[20:21]
	v_lshl_add_u64 v[166:167], s[84:85], 0, v[18:19]
	s_mov_b32 s1, 0x8000
	v_mov_b32_e32 v127, v126
	v_mov_b32_e32 v128, v126
	v_mov_b32_e32 v129, v126
	v_mov_b32_e32 v130, v126
	v_mov_b32_e32 v131, v126
	v_mov_b32_e32 v132, v126
	v_mov_b32_e32 v133, v126
	v_mov_b32_e32 v134, v126
	v_mov_b32_e32 v135, v126
	v_mov_b32_e32 v136, v126
	v_mov_b32_e32 v137, v126
	v_mov_b32_e32 v138, v126
	v_mov_b32_e32 v139, v126
	v_mov_b32_e32 v140, v126
	v_mov_b32_e32 v141, v126
	v_mov_b32_e32 v142, v126
	v_mov_b32_e32 v143, v126
	v_mov_b32_e32 v144, v126
	v_mov_b32_e32 v145, v126
	v_mov_b32_e32 v82, v126
	v_mov_b32_e32 v83, v126
	v_mov_b32_e32 v84, v126
	v_mov_b32_e32 v85, v126
	v_mov_b32_e32 v94, v126
	v_mov_b32_e32 v95, v126
	v_mov_b32_e32 v96, v126
	v_mov_b32_e32 v97, v126
	v_mov_b32_e32 v86, v126
	v_mov_b32_e32 v87, v126
	v_mov_b32_e32 v88, v126
	v_mov_b32_e32 v89, v126
	v_mov_b32_e32 v118, v126
	v_mov_b32_e32 v119, v126
	v_mov_b32_e32 v120, v126
	v_mov_b32_e32 v121, v126
	v_mov_b32_e32 v98, v126
	v_mov_b32_e32 v99, v126
	v_mov_b32_e32 v100, v126
	v_mov_b32_e32 v101, v126
	v_mov_b32_e32 v62, v126
	v_mov_b32_e32 v63, v126
	v_mov_b32_e32 v64, v126
	v_mov_b32_e32 v65, v126
	v_mov_b32_e32 v54, v126
	v_mov_b32_e32 v55, v126
	v_mov_b32_e32 v56, v126
	v_mov_b32_e32 v57, v126
	v_mov_b32_e32 v50, v126
	v_mov_b32_e32 v51, v126
	v_mov_b32_e32 v52, v126
	v_mov_b32_e32 v53, v126
	v_mov_b32_e32 v38, v126
	v_mov_b32_e32 v39, v126
	v_mov_b32_e32 v40, v126
	v_mov_b32_e32 v41, v126
	v_mov_b32_e32 v26, v126
	v_mov_b32_e32 v27, v126
	v_mov_b32_e32 v28, v126
	v_mov_b32_e32 v29, v126
	v_mov_b32_e32 v18, v126
	v_mov_b32_e32 v19, v126
	v_mov_b32_e32 v20, v126
	v_mov_b32_e32 v21, v126
	v_mov_b32_e32 v42, v126
	v_mov_b32_e32 v43, v126
	v_mov_b32_e32 v44, v126
	v_mov_b32_e32 v45, v126
	v_mov_b32_e32 v30, v126
	v_mov_b32_e32 v31, v126
	v_mov_b32_e32 v32, v126
	v_mov_b32_e32 v33, v126
	v_mov_b32_e32 v22, v126
	v_mov_b32_e32 v23, v126
	v_mov_b32_e32 v24, v126
	v_mov_b32_e32 v25, v126
	v_mov_b32_e32 v34, v126
	v_mov_b32_e32 v35, v126
	v_mov_b32_e32 v36, v126
	v_mov_b32_e32 v37, v126
	v_mov_b32_e32 v46, v126
	v_mov_b32_e32 v47, v126
	v_mov_b32_e32 v48, v126
	v_mov_b32_e32 v49, v126
	v_mov_b32_e32 v58, v126
	v_mov_b32_e32 v59, v126
	v_mov_b32_e32 v60, v126
	v_mov_b32_e32 v61, v126
	v_mov_b32_e32 v66, v126
	v_mov_b32_e32 v67, v126
	v_mov_b32_e32 v68, v126
	v_mov_b32_e32 v69, v126
	v_mov_b32_e32 v70, v126
	v_mov_b32_e32 v71, v126
	v_mov_b32_e32 v72, v126
	v_mov_b32_e32 v73, v126
	v_mov_b32_e32 v74, v126
	v_mov_b32_e32 v75, v126
	v_mov_b32_e32 v76, v126
	v_mov_b32_e32 v77, v126
	v_mov_b32_e32 v78, v126
	v_mov_b32_e32 v79, v126
	v_mov_b32_e32 v80, v126
	v_mov_b32_e32 v81, v126
	v_mov_b32_e32 v90, v126
	v_mov_b32_e32 v91, v126
	v_mov_b32_e32 v92, v126
	v_mov_b32_e32 v93, v126
	v_mov_b32_e32 v102, v126
	v_mov_b32_e32 v103, v126
	v_mov_b32_e32 v104, v126
	v_mov_b32_e32 v105, v126
	v_mov_b32_e32 v106, v126
	v_mov_b32_e32 v107, v126
	v_mov_b32_e32 v108, v126
	v_mov_b32_e32 v109, v126
	v_mov_b32_e32 v110, v126
	v_mov_b32_e32 v111, v126
	v_mov_b32_e32 v112, v126
	v_mov_b32_e32 v113, v126
	v_mov_b32_e32 v114, v126
	v_mov_b32_e32 v115, v126
	v_mov_b32_e32 v116, v126
	v_mov_b32_e32 v117, v126
	v_mov_b32_e32 v122, v126
	v_mov_b32_e32 v123, v126
	v_mov_b32_e32 v124, v126
	v_mov_b32_e32 v125, v126
	s_waitcnt lgkmcnt(0)
	s_barrier
	s_add_i32 s98, s1, 0xffff8000
	s_and_b32 s98, s98, 0x8000
	s_add_i32 s98, s98, 32
	v_add_u32_e32 v226, s98, v173
	ds_read_b128 v[196:199], v226
	ds_read_b128 v[200:203], v226 offset:2048
; #define MFMA16(a, b, c) __builtin_amdgcn_mfma_f32_16x16x32_bf16((a), (b), (c), 0, 0, 0)
; template <class Epi>
; DEVI void gemm_tile256b(const bf16_t* __restrict__ A, int lda, const bf16_t* __restrict__ Bt, int K,
;                         int m0, int n0, char* smem, Epi epi) {
;     ...
;   for (int kt = 0; kt < nk; ++kt) {
;     const char* base = smem + (kt & 1) * 32768;
;     const bool more = kt + 1 < nk;
;     if (more) {
; #pragma unroll
;       for (int i = 0; i < 8; ++i) ra[i] = *(const u32x4*)(ag + (size_t)(i * 32) * lda + (kt + 1) * 64);
;     }
; #pragma unroll
;     for (int i = 0; i < 4; ++i) b1[i] = *(const bf16x8*)(bp + ((size_t)i * kb32 + kt * 2 + 1) * 512);
;     {
;       bf16x8 af[8];
; #pragma unroll
;       for (int i = 0; i < 8; ++i) af[i] = *(const bf16x8*)(base + a_rd + i * 2048);
; #pragma unroll
;       for (int mi = 0; mi < 8; ++mi)
; #pragma unroll
;         for (int ni = 0; ni < 4; ++ni) acc[mi][ni] = MFMA16(b0[ni], af[mi], acc[mi][ni]);
;     }
;     if (more) {
; #pragma unroll
;       for (int i = 0; i < 4; ++i) b0[i] = *(const bf16x8*)(bp + ((size_t)i * kb32 + kt * 2 + 2) * 512);
;     }
;     {
;       bf16x8 af[8];
; #pragma unroll
;       for (int i = 0; i < 8; ++i) af[i] = *(const bf16x8*)(base + ((a_rd + i * 2048) ^ 64));
; #pragma unroll
;       for (int mi = 0; mi < 8; ++mi)
; #pragma unroll
;         for (int ni = 0; ni < 4; ++ni) acc[mi][ni] = MFMA16(b1[ni], af[mi], acc[mi][ni]);
;     }
;     if (more) {
;       char* nb = smem + ((kt + 1) & 1) * 32768 + lds_w;
; #pragma unroll
;       for (int i = 0; i < 8; ++i) *(u32x4*)(nb + i * 4096) = ra[i];
;     }
;     __syncthreads();
;   }
.LBB0_1838:
	s_add_i32 s13, s1, 0xffff8000
	s_and_b32 s13, s13, 0x8000
	s_add_i32 s13, s13, 32
	v_add_u32_e32 v0, s13, v173
	v_lshl_add_u64 v[154:155], v[164:165], 0, s[28:29]
	s_mov_b32 s16, 0x3280000
	v_add_co_u32_e32 v156, vcc, s16, v154
	s_waitcnt vmcnt(3) lgkmcnt(1)
	v_mfma_f32_16x16x32_bf16 v[122:125], v[14:17], v[196:199], v[122:125]
	v_addc_co_u32_e32 v157, vcc, 0, v155, vcc
	s_mov_b32 s16, 0x32a0000
	s_waitcnt vmcnt(2)
	v_mfma_f32_16x16x32_bf16 v[114:117], v[10:13], v[196:199], v[114:117]
	v_add_co_u32_e32 v158, vcc, s16, v154
	s_mov_b32 s16, 0x32c0000
	s_waitcnt vmcnt(1)
	v_mfma_f32_16x16x32_bf16 v[110:113], v[6:9], v[196:199], v[110:113]
	v_addc_co_u32_e32 v159, vcc, 0, v155, vcc
	v_add_co_u32_e32 v160, vcc, s16, v154
	s_waitcnt vmcnt(0)
	v_mfma_f32_16x16x32_bf16 v[106:109], v[2:5], v[196:199], v[106:109]
	v_addc_co_u32_e32 v161, vcc, 0, v155, vcc
	s_mov_b32 s16, 0x32e0000
	s_waitcnt lgkmcnt(0)
	v_mfma_f32_16x16x32_bf16 v[102:105], v[14:17], v[200:203], v[102:105]
	v_add_co_u32_e32 v182, vcc, s16, v154
	v_lshl_add_u64 v[164:165], v[164:165], 0, s[64:65]
	v_mfma_f32_16x16x32_bf16 v[90:93], v[10:13], v[200:203], v[90:93]
	v_addc_co_u32_e32 v183, vcc, 0, v155, vcc
	v_mfma_f32_16x16x32_bf16 v[78:81], v[6:9], v[200:203], v[78:81]
	v_mfma_f32_16x16x32_bf16 v[74:77], v[2:5], v[200:203], v[74:77]
	ds_read_b128 v[146:149], v0 offset:4096
	ds_read_b128 v[150:153], v0 offset:6144
	s_waitcnt lgkmcnt(1)
	v_mfma_f32_16x16x32_bf16 v[70:73], v[14:17], v[146:149], v[70:73]
	v_mfma_f32_16x16x32_bf16 v[66:69], v[10:13], v[146:149], v[66:69]
	v_mfma_f32_16x16x32_bf16 v[58:61], v[6:9], v[146:149], v[58:61]
	v_mfma_f32_16x16x32_bf16 v[46:49], v[2:5], v[146:149], v[46:49]
	s_waitcnt lgkmcnt(0)
	v_mfma_f32_16x16x32_bf16 v[34:37], v[14:17], v[150:153], v[34:37]
	v_mfma_f32_16x16x32_bf16 v[22:25], v[10:13], v[150:153], v[22:25]
	v_mfma_f32_16x16x32_bf16 v[30:33], v[6:9], v[150:153], v[30:33]
	v_mfma_f32_16x16x32_bf16 v[42:45], v[2:5], v[150:153], v[42:45]
	ds_read_b128 v[146:149], v0 offset:8192
	ds_read_b128 v[150:153], v0 offset:10240
	s_waitcnt lgkmcnt(1)
	v_mfma_f32_16x16x32_bf16 v[18:21], v[14:17], v[146:149], v[18:21]
	v_mfma_f32_16x16x32_bf16 v[26:29], v[10:13], v[146:149], v[26:29]
	v_mfma_f32_16x16x32_bf16 v[38:41], v[6:9], v[146:149], v[38:41]
	v_mfma_f32_16x16x32_bf16 v[50:53], v[2:5], v[146:149], v[50:53]
	s_waitcnt lgkmcnt(0)
	v_mfma_f32_16x16x32_bf16 v[54:57], v[14:17], v[150:153], v[54:57]
	v_mfma_f32_16x16x32_bf16 v[62:65], v[10:13], v[150:153], v[62:65]
	v_mfma_f32_16x16x32_bf16 v[98:101], v[6:9], v[150:153], v[98:101]
	v_mfma_f32_16x16x32_bf16 v[118:121], v[2:5], v[150:153], v[118:121]
	ds_read_b128 v[146:149], v0 offset:12288
	ds_read_b128 v[150:153], v0 offset:14336
	v_add_u32_e32 v0, s13, v171
	s_waitcnt lgkmcnt(1)
	v_mfma_f32_16x16x32_bf16 v[86:89], v[14:17], v[146:149], v[86:89]
	v_mfma_f32_16x16x32_bf16 v[94:97], v[10:13], v[146:149], v[94:97]
	v_mfma_f32_16x16x32_bf16 v[82:85], v[6:9], v[146:149], v[82:85]
	v_mfma_f32_16x16x32_bf16 v[142:145], v[2:5], v[146:149], v[142:145]
	global_load_dwordx4 v[146:149], v[156:157], off offset:1024
	ds_read_b128 v[174:177], v0
	ds_read_b128 v[178:181], v0 offset:2048
	s_waitcnt lgkmcnt(2)
	v_mfma_f32_16x16x32_bf16 v[138:141], v[14:17], v[150:153], v[138:141]
	global_load_dwordx4 v[14:17], v[156:157], off offset:2048
	v_mfma_f32_16x16x32_bf16 v[134:137], v[10:13], v[150:153], v[134:137]
	v_mfma_f32_16x16x32_bf16 v[130:133], v[6:9], v[150:153], v[130:133]
	v_mfma_f32_16x16x32_bf16 v[126:129], v[2:5], v[150:153], v[126:129]
	global_load_dwordx4 v[150:153], v[158:159], off offset:1024
	global_load_dwordx4 v[10:13], v[158:159], off offset:2048
	global_load_dwordx4 v[154:157], v[160:161], off offset:1024
	global_load_dwordx4 v[6:9], v[160:161], off offset:2048
	s_nop 0
	global_load_dwordx4 v[158:161], v[182:183], off offset:1024
	global_load_dwordx4 v[2:5], v[182:183], off offset:2048
	v_lshrrev_b32_e32 v195, 6, v206
	v_lshl_add_u64 v[190:191], v[166:167], 0, s[28:29]
	v_lshrrev_b32_e32 v194, 3, v206
	v_readfirstlane_b32 s99, v195
	v_and_b32_e32 v194, 7, v194
	s_and_b32 s98, s1, 0x8000
	v_lshlrev_b32_e32 v194, 4, v194
	s_lshl_b32 s99, s99, 10
	v_xor_b32_e32 v190, v194, v190
	s_add_u32 s98, s98, s99
	s_add_u32 s98, s98, 32
	s_mov_b32 s101, 0
	s_mov_b32 s100, 0x3b93080
	v_lshl_add_u64 v[192:193], v[190:191], 0, s[100:101]
	s_mov_b32 m0, s98
	s_nop 0
	global_load_lds_dwordx4 v[192:193], off
	s_mov_b32 s100, 0x3bd3080
	v_lshl_add_u64 v[192:193], v[190:191], 0, s[100:101]
	s_add_u32 m0, s98, 0x1000
	s_nop 0
	global_load_lds_dwordx4 v[192:193], off
	s_mov_b32 s100, 0x3c13080
	v_lshl_add_u64 v[192:193], v[190:191], 0, s[100:101]
	s_add_u32 m0, s98, 0x2000
	s_nop 0
	global_load_lds_dwordx4 v[192:193], off
	s_mov_b32 s100, 0x3c53080
	v_lshl_add_u64 v[192:193], v[190:191], 0, s[100:101]
	s_add_u32 m0, s98, 0x3000
	s_nop 0
	global_load_lds_dwordx4 v[192:193], off
	s_mov_b32 s100, 0x3c93080
	v_lshl_add_u64 v[192:193], v[190:191], 0, s[100:101]
	s_add_u32 m0, s98, 0x4000
	s_nop 0
	global_load_lds_dwordx4 v[192:193], off
	s_mov_b32 s100, 0x3cd3080
	v_lshl_add_u64 v[192:193], v[190:191], 0, s[100:101]
	s_add_u32 m0, s98, 0x5000
	s_nop 0
	global_load_lds_dwordx4 v[192:193], off
	s_mov_b32 s100, 0x3d13080
	v_lshl_add_u64 v[192:193], v[190:191], 0, s[100:101]
	s_add_u32 m0, s98, 0x6000
	s_nop 0
	global_load_lds_dwordx4 v[192:193], off
	s_mov_b32 s100, 0x3d53080
	v_lshl_add_u64 v[192:193], v[190:191], 0, s[100:101]
	s_add_u32 m0, s98, 0x7000
	s_nop 0
	global_load_lds_dwordx4 v[192:193], off
	s_nop 0
	s_nop 0
	s_waitcnt vmcnt(15) lgkmcnt(1)
	v_mfma_f32_16x16x32_bf16 v[122:125], v[146:149], v[174:177], v[122:125]
	s_waitcnt vmcnt(13)
; #define MFMA16(a, b, c) __builtin_amdgcn_mfma_f32_16x16x32_bf16((a), (b), (c), 0, 0, 0)
; template <class Epi>
; DEVI void gemm_tile256b(const bf16_t* __restrict__ A, int lda, const bf16_t* __restrict__ Bt, int K,
;                         int m0, int n0, char* smem, Epi epi) {
;     ...
;   for (int kt = 0; kt < nk; ++kt) {
;     const char* base = smem + (kt & 1) * 32768;
;     const bool more = kt + 1 < nk;
;     if (more) {
; #pragma unroll
;       for (int i = 0; i < 8; ++i) ra[i] = *(const u32x4*)(ag + (size_t)(i * 32) * lda + (kt + 1) * 64);
;     }
; #pragma unroll
;     for (int i = 0; i < 4; ++i) b1[i] = *(const bf16x8*)(bp + ((size_t)i * kb32 + kt * 2 + 1) * 512);
;     {
;       bf16x8 af[8];
; #pragma unroll
;       for (int i = 0; i < 8; ++i) af[i] = *(const bf16x8*)(base + a_rd + i * 2048);
; #pragma unroll
;       for (int mi = 0; mi < 8; ++mi)
; #pragma unroll
;         for (int ni = 0; ni < 4; ++ni) acc[mi][ni] = MFMA16(b0[ni], af[mi], acc[mi][ni]);
;     }
;     if (more) {
; #pragma unroll
;       for (int i = 0; i < 4; ++i) b0[i] = *(const bf16x8*)(bp + ((size_t)i * kb32 + kt * 2 + 2) * 512);
;     }
;     {
;       bf16x8 af[8];
; #pragma unroll
;       for (int i = 0; i < 8; ++i) af[i] = *(const bf16x8*)(base + ((a_rd + i * 2048) ^ 64));
; #pragma unroll
;       for (int mi = 0; mi < 8; ++mi)
; #pragma unroll
;         for (int ni = 0; ni < 4; ++ni) acc[mi][ni] = MFMA16(b1[ni], af[mi], acc[mi][ni]);
;     }
;     if (more) {
;       char* nb = smem + ((kt + 1) & 1) * 32768 + lds_w;
; #pragma unroll
;       for (int i = 0; i < 8; ++i) *(u32x4*)(nb + i * 4096) = ra[i];
;     }
;     __syncthreads();
;   }
	v_mfma_f32_16x16x32_bf16 v[114:117], v[150:153], v[174:177], v[114:117]
	s_waitcnt vmcnt(11)
	v_mfma_f32_16x16x32_bf16 v[110:113], v[154:157], v[174:177], v[110:113]
	s_waitcnt vmcnt(9)
	v_mfma_f32_16x16x32_bf16 v[106:109], v[158:161], v[174:177], v[106:109]
	s_waitcnt lgkmcnt(0)
	v_mfma_f32_16x16x32_bf16 v[102:105], v[146:149], v[178:181], v[102:105]
	v_mfma_f32_16x16x32_bf16 v[90:93], v[150:153], v[178:181], v[90:93]
	v_mfma_f32_16x16x32_bf16 v[78:81], v[154:157], v[178:181], v[78:81]
	s_nop 0
	v_mfma_f32_16x16x32_bf16 v[74:77], v[158:161], v[178:181], v[74:77]
	ds_read_b128 v[174:177], v0 offset:4096
	ds_read_b128 v[178:181], v0 offset:6144
	s_waitcnt lgkmcnt(1)
	v_mfma_f32_16x16x32_bf16 v[70:73], v[146:149], v[174:177], v[70:73]
	s_and_b32 s13, s1, 0x8000
	v_mfma_f32_16x16x32_bf16 v[66:69], v[150:153], v[174:177], v[66:69]
	s_add_i32 s1, s1, 0x8000
	v_lshl_add_u64 v[166:167], v[166:167], 0, s[60:61]
	s_cmp_eq_u32 s1, 0x200000
	v_mfma_f32_16x16x32_bf16 v[58:61], v[154:157], v[174:177], v[58:61]
	v_mfma_f32_16x16x32_bf16 v[46:49], v[158:161], v[174:177], v[46:49]
	s_waitcnt lgkmcnt(0)
	v_mfma_f32_16x16x32_bf16 v[34:37], v[146:149], v[178:181], v[34:37]
	v_mfma_f32_16x16x32_bf16 v[22:25], v[150:153], v[178:181], v[22:25]
	v_mfma_f32_16x16x32_bf16 v[30:33], v[154:157], v[178:181], v[30:33]
	v_mfma_f32_16x16x32_bf16 v[42:45], v[158:161], v[178:181], v[42:45]
	ds_read_b128 v[174:177], v0 offset:8192
	ds_read_b128 v[178:181], v0 offset:10240
	s_waitcnt lgkmcnt(1)
	v_mfma_f32_16x16x32_bf16 v[18:21], v[146:149], v[174:177], v[18:21]
	v_mfma_f32_16x16x32_bf16 v[26:29], v[150:153], v[174:177], v[26:29]
	v_mfma_f32_16x16x32_bf16 v[38:41], v[154:157], v[174:177], v[38:41]
	v_mfma_f32_16x16x32_bf16 v[50:53], v[158:161], v[174:177], v[50:53]
	s_waitcnt lgkmcnt(0)
	v_mfma_f32_16x16x32_bf16 v[54:57], v[146:149], v[178:181], v[54:57]
	v_mfma_f32_16x16x32_bf16 v[62:65], v[150:153], v[178:181], v[62:65]
	v_mfma_f32_16x16x32_bf16 v[98:101], v[154:157], v[178:181], v[98:101]
	v_mfma_f32_16x16x32_bf16 v[118:121], v[158:161], v[178:181], v[118:121]
	ds_read_b128 v[178:181], v0 offset:12288
	ds_read_b128 v[182:185], v0 offset:14336
	s_nop 0
	s_nop 0
	s_nop 0
	s_nop 0
	s_nop 0
	s_waitcnt lgkmcnt(1)
	v_mfma_f32_16x16x32_bf16 v[86:89], v[146:149], v[178:181], v[86:89]
	v_mfma_f32_16x16x32_bf16 v[94:97], v[150:153], v[178:181], v[94:97]
	v_mfma_f32_16x16x32_bf16 v[82:85], v[154:157], v[178:181], v[82:85]
	s_waitcnt vmcnt(0) lgkmcnt(0)
	s_barrier
	s_add_i32 s98, s1, 0xffff8000
	s_and_b32 s98, s98, 0x8000
	s_add_i32 s98, s98, 32
	v_add_u32_e32 v226, s98, v173
	ds_read_b128 v[196:199], v226
	ds_read_b128 v[200:203], v226 offset:2048
	v_mfma_f32_16x16x32_bf16 v[142:145], v[158:161], v[178:181], v[142:145]
	v_mfma_f32_16x16x32_bf16 v[138:141], v[146:149], v[182:185], v[138:141]
	v_mfma_f32_16x16x32_bf16 v[134:137], v[150:153], v[182:185], v[134:137]
	v_mfma_f32_16x16x32_bf16 v[130:133], v[154:157], v[182:185], v[130:133]
	v_mfma_f32_16x16x32_bf16 v[126:129], v[158:161], v[182:185], v[126:129]
	s_cmp_eq_u32 s1, 0x200000
	s_cbranch_scc0 .LBB0_1838
	v_add_u32_e32 v0, 32, v173
	ds_read_b128 v[146:149], v0 offset:32768
	ds_read_b128 v[150:153], v0 offset:34816
	s_waitcnt lgkmcnt(1)
	v_mfma_f32_16x16x32_bf16 v[122:125], v[14:17], v[146:149], v[122:125]
	v_mfma_f32_16x16x32_bf16 v[114:117], v[10:13], v[146:149], v[114:117]
	v_mfma_f32_16x16x32_bf16 v[110:113], v[6:9], v[146:149], v[110:113]
	v_mfma_f32_16x16x32_bf16 v[106:109], v[2:5], v[146:149], v[106:109]
	s_waitcnt lgkmcnt(0)
	v_mfma_f32_16x16x32_bf16 v[102:105], v[14:17], v[150:153], v[102:105]
	v_mfma_f32_16x16x32_bf16 v[90:93], v[10:13], v[150:153], v[90:93]
	v_mfma_f32_16x16x32_bf16 v[78:81], v[6:9], v[150:153], v[78:81]
	v_mfma_f32_16x16x32_bf16 v[74:77], v[2:5], v[150:153], v[74:77]
	ds_read_b128 v[146:149], v0 offset:36864
	ds_read_b128 v[150:153], v0 offset:38912
	s_waitcnt lgkmcnt(1)
	v_mfma_f32_16x16x32_bf16 v[70:73], v[14:17], v[146:149], v[70:73]
	v_mfma_f32_16x16x32_bf16 v[66:69], v[10:13], v[146:149], v[66:69]
	v_mfma_f32_16x16x32_bf16 v[58:61], v[6:9], v[146:149], v[58:61]
	v_mfma_f32_16x16x32_bf16 v[46:49], v[2:5], v[146:149], v[46:49]
	s_waitcnt lgkmcnt(0)
	v_mfma_f32_16x16x32_bf16 v[34:37], v[14:17], v[150:153], v[34:37]
	v_mfma_f32_16x16x32_bf16 v[22:25], v[10:13], v[150:153], v[22:25]
	v_mfma_f32_16x16x32_bf16 v[30:33], v[6:9], v[150:153], v[30:33]
	v_mfma_f32_16x16x32_bf16 v[42:45], v[2:5], v[150:153], v[42:45]
	ds_read_b128 v[146:149], v0 offset:40960
	ds_read_b128 v[150:153], v0 offset:43008
	s_waitcnt lgkmcnt(1)
	v_mfma_f32_16x16x32_bf16 v[18:21], v[14:17], v[146:149], v[18:21]
	v_mfma_f32_16x16x32_bf16 v[26:29], v[10:13], v[146:149], v[26:29]
	v_mfma_f32_16x16x32_bf16 v[38:41], v[6:9], v[146:149], v[38:41]
	v_mfma_f32_16x16x32_bf16 v[50:53], v[2:5], v[146:149], v[50:53]
	s_waitcnt lgkmcnt(0)
	v_mfma_f32_16x16x32_bf16 v[146:149], v[14:17], v[150:153], v[54:57]
	v_mfma_f32_16x16x32_bf16 v[154:157], v[10:13], v[150:153], v[62:65]
	s_nop 1
	ds_read_b128 v[54:57], v0 offset:45056
	ds_read_b128 v[62:65], v0 offset:47104
	v_add_u32_e32 v0, 32, v171
	s_waitcnt lgkmcnt(1)
	v_mfma_f32_16x16x32_bf16 v[176:179], v[6:9], v[54:57], v[82:85]
	s_nop 2
	v_add_co_u32_e32 v82, vcc, 0x1f000, v162
	v_mfma_f32_16x16x32_bf16 v[164:167], v[14:17], v[54:57], v[86:89]
	s_nop 0
	v_addc_co_u32_e32 v83, vcc, 0, v163, vcc
	v_mfma_f32_16x16x32_bf16 v[172:175], v[10:13], v[54:57], v[94:97]
	v_mfma_f32_16x16x32_bf16 v[142:145], v[2:5], v[54:57], v[142:145]
	v_add_co_u32_e32 v54, vcc, 0x3f000, v162
	s_nop 1
	v_addc_co_u32_e32 v55, vcc, 0, v163, vcc
	s_waitcnt lgkmcnt(0)
; #define MFMA16(a, b, c) __builtin_amdgcn_mfma_f32_16x16x32_bf16((a), (b), (c), 0, 0, 0)
; template <class Epi>
; DEVI void gemm_tile256b(const bf16_t* __restrict__ A, int lda, const bf16_t* __restrict__ Bt, int K,
;                         int m0, int n0, char* smem, Epi epi) {
;     ...
;     {
;       bf16x8 af[8];
; #pragma unroll
;       for (int i = 0; i < 8; ++i) af[i] = *(const bf16x8*)(base + ((a_rd + i * 2048) ^ 64));
; #pragma unroll
;       for (int mi = 0; mi < 8; ++mi)
; #pragma unroll
;         for (int ni = 0; ni < 4; ++ni) acc[mi][ni] = MFMA16(b1[ni], af[mi], acc[mi][ni]);
;     }
;     if (more) {
;       char* nb = smem + ((kt + 1) & 1) * 32768 + lds_w;
; #pragma unroll
;       for (int i = 0; i < 8; ++i) *(u32x4*)(nb + i * 4096) = ra[i];
;     }
;     __syncthreads();
;   }
; #pragma unroll
;   for (int mi = 0; mi < 8; ++mi)
; #pragma unroll
;     for (int ni = 0; ni < 4; ++ni)
;       epi(m0 + wm * 128 + mi * 16 + l15, n0 + wn * 64 + ni * 16 + quad * 4, acc[mi][ni]);
;   DEVI void operator()(int m, int n, f32x4 v) const {
;     if (m >= L) return;
;     float* h = hfrow(p, m) + n;
;     const float* src = (first && m >= 16) ? p.in[0] + (size_t)(m - 16) * 1024 + n : h;
;     f32x4 o = *(const f32x4*)src;
;     o = o * ALPHA + v;
;     *(f32x4*)h = o;
;   }
	v_mfma_f32_16x16x32_bf16 v[14:17], v[14:17], v[62:65], v[138:141]
	s_nop 2
	global_load_dwordx4 v[138:141], v[82:83], off offset:3072
	v_mfma_f32_16x16x32_bf16 v[10:13], v[10:13], v[62:65], v[134:137]
	s_nop 2
	global_load_dwordx4 v[134:137], v[54:55], off offset:3072
	v_add_co_u32_e32 v82, vcc, 0x5f000, v162
	v_mfma_f32_16x16x32_bf16 v[158:161], v[6:9], v[150:153], v[98:101]
	s_nop 0
	v_addc_co_u32_e32 v83, vcc, 0, v163, vcc
	ds_read_b128 v[54:57], v0 offset:32768
	v_mfma_f32_16x16x32_bf16 v[6:9], v[6:9], v[62:65], v[130:133]
	s_nop 2
	global_load_dwordx4 v[130:133], v[82:83], off offset:3072
	v_add_co_u32_e32 v82, vcc, 0x7f000, v162
	v_mfma_f32_16x16x32_bf16 v[150:153], v[2:5], v[150:153], v[118:121]
	s_nop 0
	v_addc_co_u32_e32 v83, vcc, 0, v163, vcc
	global_load_dwordx4 v[180:183], v[82:83], off offset:3072
	v_mfma_f32_16x16x32_bf16 v[2:5], v[2:5], v[62:65], v[126:129]
	ds_read_b128 v[62:65], v0 offset:34816
	s_waitcnt vmcnt(3) lgkmcnt(1)
	v_mfma_f32_16x16x32_bf16 v[126:129], v[138:141], v[54:57], v[122:125]
	s_waitcnt vmcnt(2)
	v_mfma_f32_16x16x32_bf16 v[122:125], v[134:137], v[54:57], v[114:117]
	s_waitcnt vmcnt(1)
	v_mfma_f32_16x16x32_bf16 v[118:121], v[130:133], v[54:57], v[110:113]
	s_waitcnt vmcnt(0)
	v_mfma_f32_16x16x32_bf16 v[114:117], v[180:183], v[54:57], v[106:109]
	s_waitcnt lgkmcnt(0)
	v_mfma_f32_16x16x32_bf16 v[110:113], v[138:141], v[62:65], v[102:105]
	v_mfma_f32_16x16x32_bf16 v[106:109], v[134:137], v[62:65], v[90:93]
	v_mfma_f32_16x16x32_bf16 v[102:105], v[130:133], v[62:65], v[78:81]
	v_mfma_f32_16x16x32_bf16 v[98:101], v[180:183], v[62:65], v[74:77]
	ds_read_b128 v[54:57], v0 offset:36864
	ds_read_b128 v[62:65], v0 offset:38912
	s_waitcnt lgkmcnt(1)
	v_mfma_f32_16x16x32_bf16 v[94:97], v[138:141], v[54:57], v[70:73]
	s_waitcnt lgkmcnt(0)
	v_mfma_f32_16x16x32_bf16 v[74:77], v[134:137], v[62:65], v[22:25]
	v_mfma_f32_16x16x32_bf16 v[70:73], v[130:133], v[62:65], v[30:33]
	s_nop 1
	ds_read_b128 v[22:25], v0 offset:40960
	ds_read_b128 v[30:33], v0 offset:43008
	v_mfma_f32_16x16x32_bf16 v[90:93], v[134:137], v[54:57], v[66:69]
	v_mfma_f32_16x16x32_bf16 v[82:85], v[180:183], v[54:57], v[46:49]
	v_mfma_f32_16x16x32_bf16 v[78:81], v[138:141], v[62:65], v[34:37]
	v_mfma_f32_16x16x32_bf16 v[66:69], v[180:183], v[62:65], v[42:45]
	s_waitcnt lgkmcnt(1)
	v_mfma_f32_16x16x32_bf16 v[62:65], v[138:141], v[22:25], v[18:21]
	s_waitcnt lgkmcnt(0)
	v_mfma_f32_16x16x32_bf16 v[46:49], v[138:141], v[30:33], v[146:149]
	s_nop 0
	ds_read_b128 v[18:21], v0 offset:45056
	s_nop 0
	ds_read_b128 v[146:149], v0 offset:47104
	v_and_b32_e32 v0, 0xffffff80, v168
	v_add_u32_e32 v0, s0, v0
	v_mfma_f32_16x16x32_bf16 v[86:89], v[130:133], v[54:57], v[58:61]
	s_movk_i32 s0, 0x4010
	s_waitcnt lgkmcnt(0)
	s_barrier
	v_mfma_f32_16x16x32_bf16 v[58:61], v[134:137], v[22:25], v[26:29]
	v_mfma_f32_16x16x32_bf16 v[54:57], v[130:133], v[22:25], v[38:41]
	v_mfma_f32_16x16x32_bf16 v[50:53], v[180:183], v[22:25], v[50:53]
	v_mfma_f32_16x16x32_bf16 v[42:45], v[134:137], v[30:33], v[154:157]
	v_mfma_f32_16x16x32_bf16 v[38:41], v[130:133], v[30:33], v[158:161]
	v_mfma_f32_16x16x32_bf16 v[34:37], v[180:183], v[30:33], v[150:153]
	v_mfma_f32_16x16x32_bf16 v[30:33], v[138:141], v[18:21], v[164:167]
	v_mfma_f32_16x16x32_bf16 v[26:29], v[134:137], v[18:21], v[172:175]
	v_mfma_f32_16x16x32_bf16 v[22:25], v[130:133], v[18:21], v[176:179]
	v_mfma_f32_16x16x32_bf16 v[18:21], v[180:183], v[18:21], v[142:145]
	v_mfma_f32_16x16x32_bf16 v[14:17], v[138:141], v[146:149], v[14:17]
	v_mfma_f32_16x16x32_bf16 v[10:13], v[134:137], v[146:149], v[10:13]
	v_mfma_f32_16x16x32_bf16 v[6:9], v[130:133], v[146:149], v[6:9]
	v_and_or_b32 v132, v168, 15, v0
	v_lshl_or_b32 v130, v169, 2, v170
	v_cmp_gt_i32_e32 vcc, s0, v132
	v_mfma_f32_16x16x32_bf16 v[2:5], v[180:183], v[146:149], v[2:5]
	v_ashrrev_i32_e32 v131, 31, v130
	s_and_saveexec_b64 s[0:1], vcc
	s_cbranch_execz .LBB0_1841
	v_lshlrev_b32_e32 v134, 10, v132
	v_add_u32_e32 v136, -16, v132
	v_mov_b32_e32 v137, v1
	v_ashrrev_i32_e32 v135, 31, v134
	v_lshlrev_b64 v[136:137], 12, v[136:137]
	v_lshl_add_u64 v[134:135], v[134:135], 2, s[34:35]
	v_lshl_add_u64 v[136:137], s[26:27], 0, v[136:137]
	v_cmp_gt_i32_e32 vcc, 16, v132
	s_nop 1
	v_cndmask_b32_e32 v135, v137, v135, vcc
	v_cndmask_b32_e32 v134, v136, v134, vcc
	v_lshl_add_u64 v[138:139], v[130:131], 2, v[134:135]
	global_load_dwordx4 v[134:137], v[138:139], off
	s_waitcnt vmcnt(0)
	v_pk_fma_f32 v[128:129], v[136:137], s[66:67], v[128:129] op_sel_hi:[1,0,1]
	v_pk_fma_f32 v[126:127], v[134:135], s[66:67], v[126:127] op_sel_hi:[1,0,1]
	global_store_dwordx4 v[138:139], v[126:129], off
	global_load_dwordx4 v[126:129], v[138:139], off offset:64
	s_waitcnt vmcnt(0)
	v_pk_fma_f32 v[124:125], v[128:129], s[66:67], v[124:125] op_sel_hi:[1,0,1]
	v_pk_fma_f32 v[122:123], v[126:127], s[66:67], v[122:123] op_sel_hi:[1,0,1]
	global_store_dwordx4 v[138:139], v[122:125], off offset:64
	global_load_dwordx4 v[122:125], v[138:139], off offset:128
	s_waitcnt vmcnt(0)
	v_pk_fma_f32 v[120:121], v[124:125], s[66:67], v[120:121] op_sel_hi:[1,0,1]
	v_pk_fma_f32 v[118:119], v[122:123], s[66:67], v[118:119] op_sel_hi:[1,0,1]
	global_store_dwordx4 v[138:139], v[118:121], off offset:128
	global_load_dwordx4 v[118:121], v[138:139], off offset:192
	s_waitcnt vmcnt(0)
	v_pk_fma_f32 v[116:117], v[120:121], s[66:67], v[116:117] op_sel_hi:[1,0,1]
	v_pk_fma_f32 v[114:115], v[118:119], s[66:67], v[114:115] op_sel_hi:[1,0,1]
	global_store_dwordx4 v[138:139], v[114:117], off offset:192

; #define TIDX opaque_tid()
; template <class Epi>
; DEVI void gemm_tile256b(const bf16_t* __restrict__ A, int lda, const bf16_t* __restrict__ Bt, int K,
;                         int m0, int n0, char* smem, Epi epi) {
;   const int tid = TIDX, lane = tid & 63, wave = tid >> 6;
;   const int wm = wave >> 1, wn = wave & 1, l15 = lane & 15, quad = lane >> 4;
;   f32x4 acc[8][4];
; #pragma unroll
;   for (int i = 0; i < 8; ++i)
; #pragma unroll
;     for (int j = 0; j < 4; ++j) acc[i][j] = f32x4{0.f, 0.f, 0.f, 0.f};
;   const int lrow = tid >> 3, lkc = tid & 7;
;   const bf16_t* ag = A + (size_t)(m0 + lrow) * lda + lkc * 8;
;   const int kb32 = K >> 5;
;   const bf16_t* bp = Bt + ((size_t)((n0 + wn * 64) >> 4) * kb32) * 512 + lane * 8;
;   u32x4 ra[8];
;   bf16x8 b0[4], b1[4];
;   const int lds_w = lrow * 128 + ((lkc ^ (lrow & 7)) << 4);
;   const int nk = K >> 6;
;   const int sw = (quad ^ (l15 & 7)) << 4;
;   const int a_rd = (wm * 128 + l15) * 128 + sw;
; #pragma unroll
;   for (int i = 0; i < 8; ++i) ra[i] = *(const u32x4*)(ag + (size_t)(i * 32) * lda);
; #pragma unroll
;   for (int i = 0; i < 4; ++i) b0[i] = *(const bf16x8*)(bp + ((size_t)i * kb32) * 512);
; #pragma unroll
;   for (int i = 0; i < 8; ++i) *(u32x4*)(smem + lds_w + i * 4096) = ra[i];
;   __syncthreads();
;     ...
;       if (xmap) {
;         const int s_ = t >> 6, w_ = t & 63, spr = nnt >> 3;
;         const int sm = s_ / spr, sn = s_ - sm * spr;
;         mt = sm * 8 + (w_ >> 3);
;         nt = sn * 8 + (w_ & 7);
.LBB0_1872:
	v_mov_b32_e32 v168, v206
	s_lshl_b32 s0, s13, 8
	s_lshl_b32 s10, s11, 7
	v_ashrrev_i32_e32 v8, 3, v168
	v_add_u32_e32 v2, s0, v8
	v_ashrrev_i32_e32 v3, 31, v2
	v_lshlrev_b64 v[50:51], 11, v[2:3]
	v_lshlrev_b32_e32 v0, 4, v168
	v_lshl_add_u64 v[2:3], s[14:15], 0, v[50:51]
	v_and_b32_e32 v0, 0x70, v0
	v_lshl_add_u64 v[2:3], v[2:3], 0, v[0:1]
	v_add_co_u32_e32 v4, vcc, s54, v2
	global_load_dwordx4 v[18:21], v[2:3], off
	s_nop 0
	v_addc_co_u32_e32 v5, vcc, 0, v3, vcc
	v_add_co_u32_e32 v6, vcc, s53, v2
	v_and_or_b32 v170, v168, 64, s10
	s_nop 0
	v_addc_co_u32_e32 v7, vcc, 0, v3, vcc
	global_load_dwordx4 v[22:25], v[4:5], off
	global_load_dwordx4 v[26:29], v[6:7], off
	v_add_co_u32_e32 v4, vcc, s52, v2
	v_and_b32_e32 v0, 63, v168
	s_nop 0
	v_addc_co_u32_e32 v5, vcc, 0, v3, vcc
	v_add_co_u32_e32 v6, vcc, s56, v2
	v_lshlrev_b32_e32 v0, 4, v0
	s_nop 0
	v_addc_co_u32_e32 v7, vcc, 0, v3, vcc
	global_load_dwordx4 v[30:33], v[4:5], off
	global_load_dwordx4 v[34:37], v[6:7], off
	v_add_co_u32_e32 v4, vcc, s57, v2
	s_mov_b32 s1, 0x8000
	s_nop 0
	v_addc_co_u32_e32 v5, vcc, 0, v3, vcc
	v_add_co_u32_e32 v6, vcc, s3, v2
	v_bfe_u32 v169, v168, 4, 2
	s_nop 0
	v_addc_co_u32_e32 v7, vcc, 0, v3, vcc
	v_add_co_u32_e32 v2, vcc, s19, v2
	global_load_dwordx4 v[38:41], v[4:5], off
	global_load_dwordx4 v[42:45], v[6:7], off
	v_addc_co_u32_e32 v3, vcc, 0, v3, vcc
	global_load_dwordx4 v[46:49], v[2:3], off
	v_lshlrev_b32_e32 v3, 7, v168
	v_ashrrev_i32_e32 v2, 4, v170
	v_and_b32_e32 v57, 0xffffc780, v3
	v_ashrrev_i32_e32 v3, 31, v2
	v_lshlrev_b64 v[52:53], 15, v[2:3]
	v_lshl_add_u64 v[2:3], s[6:7], 0, v[52:53]
	v_xor_b32_e32 v4, v8, v168
	v_lshl_add_u64 v[162:163], v[2:3], 0, v[0:1]
	v_lshlrev_b32_e32 v4, 4, v4
	v_add_co_u32_e32 v2, vcc, s1, v162
	v_lshlrev_b32_e32 v6, 7, v8
	v_and_b32_e32 v4, 0x70, v4
	v_addc_co_u32_e32 v3, vcc, 0, v163, vcc
	v_bitop3_b32 v5, v169, v168, 7 bitop3:0x78
	v_add3_u32 v172, 32, v4, v6
	v_add_co_u32_e32 v4, vcc, s54, v162
	v_lshlrev_b32_e32 v58, 4, v5
	s_nop 0
	v_addc_co_u32_e32 v5, vcc, 0, v163, vcc
	s_mov_b32 s10, 0x18000
	v_add_co_u32_e32 v54, vcc, s10, v162
	global_load_dwordx4 v[10:13], v[162:163], off
	s_nop 0
	v_addc_co_u32_e32 v55, vcc, 0, v163, vcc
	global_load_dwordx4 v[14:17], v[2:3], off
	global_load_dwordx4 v[6:9], v[4:5], off
	s_nop 0
	global_load_dwordx4 v[2:5], v[54:55], off
	v_and_b32_e32 v56, 7, v168
	v_or_b32_e32 v52, v52, v0
	v_lshl_or_b32 v50, v56, 4, v50
	v_mov_b32_e32 v78, 0
	v_or_b32_e32 v173, v58, v57
	v_bitop3_b32 v171, v58, 64, v57 bitop3:0x36
	v_lshl_add_u64 v[164:165], s[84:85], 0, v[52:53]
	v_lshl_add_u64 v[166:167], s[84:85], 0, v[50:51]
	v_mov_b32_e32 v79, v78
	v_mov_b32_e32 v80, v78
	v_mov_b32_e32 v81, v78
	v_mov_b32_e32 v90, v78
	v_mov_b32_e32 v91, v78
	v_mov_b32_e32 v92, v78
	v_mov_b32_e32 v93, v78
	v_mov_b32_e32 v118, v78
	v_mov_b32_e32 v119, v78
	v_mov_b32_e32 v120, v78
	v_mov_b32_e32 v121, v78
	s_waitcnt vmcnt(11)
	ds_write_b128 v172, v[18:21]
	s_waitcnt vmcnt(10)
	ds_write_b128 v172, v[22:25] offset:4096
	s_waitcnt vmcnt(9)
	ds_write_b128 v172, v[26:29] offset:8192
	s_waitcnt vmcnt(8)
	ds_write_b128 v172, v[30:33] offset:12288
	s_waitcnt vmcnt(7)
	ds_write_b128 v172, v[34:37] offset:16384
	s_waitcnt vmcnt(6)
	ds_write_b128 v172, v[38:41] offset:20480
	s_waitcnt vmcnt(5)
	ds_write_b128 v172, v[42:45] offset:24576
	s_waitcnt vmcnt(4)
	ds_write_b128 v172, v[46:49] offset:28672
	v_mov_b32_e32 v138, v78
	v_mov_b32_e32 v139, v78
	v_mov_b32_e32 v140, v78
	v_mov_b32_e32 v141, v78
	v_mov_b32_e32 v142, v78
	v_mov_b32_e32 v143, v78
	v_mov_b32_e32 v144, v78
	v_mov_b32_e32 v145, v78
	v_mov_b32_e32 v30, v78
	v_mov_b32_e32 v31, v78
	v_mov_b32_e32 v32, v78
	v_mov_b32_e32 v33, v78
	v_mov_b32_e32 v38, v78
	v_mov_b32_e32 v39, v78
	v_mov_b32_e32 v40, v78
	v_mov_b32_e32 v41, v78
	v_mov_b32_e32 v34, v78
	v_mov_b32_e32 v35, v78
	v_mov_b32_e32 v36, v78
	v_mov_b32_e32 v37, v78
	v_mov_b32_e32 v42, v78
	v_mov_b32_e32 v43, v78
	v_mov_b32_e32 v44, v78
	v_mov_b32_e32 v45, v78
	v_mov_b32_e32 v18, v78
	v_mov_b32_e32 v19, v78
	v_mov_b32_e32 v20, v78
	v_mov_b32_e32 v21, v78
	v_mov_b32_e32 v22, v78
	v_mov_b32_e32 v23, v78
	v_mov_b32_e32 v24, v78
	v_mov_b32_e32 v25, v78
	v_mov_b32_e32 v26, v78
	v_mov_b32_e32 v27, v78
	v_mov_b32_e32 v28, v78
	v_mov_b32_e32 v29, v78
	v_mov_b32_e32 v54, v78
	v_mov_b32_e32 v55, v78
	v_mov_b32_e32 v56, v78
	v_mov_b32_e32 v57, v78
	v_mov_b32_e32 v58, v78
	v_mov_b32_e32 v59, v78
	v_mov_b32_e32 v60, v78
	v_mov_b32_e32 v61, v78
	v_mov_b32_e32 v50, v78
	v_mov_b32_e32 v51, v78
	v_mov_b32_e32 v52, v78
	v_mov_b32_e32 v53, v78
	v_mov_b32_e32 v46, v78
	v_mov_b32_e32 v47, v78
	v_mov_b32_e32 v48, v78
	v_mov_b32_e32 v49, v78
	v_mov_b32_e32 v66, v78
	v_mov_b32_e32 v67, v78
	v_mov_b32_e32 v68, v78
	v_mov_b32_e32 v69, v78
	v_mov_b32_e32 v62, v78
	v_mov_b32_e32 v63, v78
	v_mov_b32_e32 v64, v78
	v_mov_b32_e32 v65, v78
	v_mov_b32_e32 v70, v78
	v_mov_b32_e32 v71, v78
	v_mov_b32_e32 v72, v78
	v_mov_b32_e32 v73, v78
	v_mov_b32_e32 v74, v78
	v_mov_b32_e32 v75, v78
	v_mov_b32_e32 v76, v78
	v_mov_b32_e32 v77, v78
	v_mov_b32_e32 v82, v78
	v_mov_b32_e32 v83, v78
	v_mov_b32_e32 v84, v78
	v_mov_b32_e32 v85, v78
	v_mov_b32_e32 v86, v78
	v_mov_b32_e32 v87, v78
	v_mov_b32_e32 v88, v78
	v_mov_b32_e32 v89, v78
	v_mov_b32_e32 v94, v78
	v_mov_b32_e32 v95, v78
	v_mov_b32_e32 v96, v78
	v_mov_b32_e32 v97, v78
	v_mov_b32_e32 v98, v78
	v_mov_b32_e32 v99, v78
	v_mov_b32_e32 v100, v78
	v_mov_b32_e32 v101, v78
	v_mov_b32_e32 v102, v78
	v_mov_b32_e32 v103, v78
	v_mov_b32_e32 v104, v78
	v_mov_b32_e32 v105, v78
	v_mov_b32_e32 v106, v78
	v_mov_b32_e32 v107, v78
	v_mov_b32_e32 v108, v78
	v_mov_b32_e32 v109, v78
	v_mov_b32_e32 v110, v78
	v_mov_b32_e32 v111, v78
	v_mov_b32_e32 v112, v78
	v_mov_b32_e32 v113, v78
	v_mov_b32_e32 v114, v78
	v_mov_b32_e32 v115, v78
	v_mov_b32_e32 v116, v78
	v_mov_b32_e32 v117, v78
	v_mov_b32_e32 v122, v78
	v_mov_b32_e32 v123, v78
	v_mov_b32_e32 v124, v78
	v_mov_b32_e32 v125, v78
	v_mov_b32_e32 v126, v78
	v_mov_b32_e32 v127, v78
	v_mov_b32_e32 v128, v78
	v_mov_b32_e32 v129, v78
	v_mov_b32_e32 v130, v78
	v_mov_b32_e32 v131, v78
	v_mov_b32_e32 v132, v78
	v_mov_b32_e32 v133, v78
	v_mov_b32_e32 v134, v78
	v_mov_b32_e32 v135, v78
	v_mov_b32_e32 v136, v78
	v_mov_b32_e32 v137, v78
	s_waitcnt lgkmcnt(0)
	s_barrier
	s_add_i32 s98, s1, 0xffff8000
	s_and_b32 s98, s98, 0x8000
	s_add_i32 s98, s98, 32
	v_add_u32_e32 v226, s98, v173
	ds_read_b128 v[196:199], v226
	ds_read_b128 v[200:203], v226 offset:2048
; #define MFMA16(a, b, c) __builtin_amdgcn_mfma_f32_16x16x32_bf16((a), (b), (c), 0, 0, 0)
; template <class Epi>
; DEVI void gemm_tile256b(const bf16_t* __restrict__ A, int lda, const bf16_t* __restrict__ Bt, int K,
;                         int m0, int n0, char* smem, Epi epi) {
;     ...
;   for (int kt = 0; kt < nk; ++kt) {
;     const char* base = smem + (kt & 1) * 32768;
;     const bool more = kt + 1 < nk;
;     if (more) {
; #pragma unroll
;       for (int i = 0; i < 8; ++i) ra[i] = *(const u32x4*)(ag + (size_t)(i * 32) * lda + (kt + 1) * 64);
;     }
; #pragma unroll
;     for (int i = 0; i < 4; ++i) b1[i] = *(const bf16x8*)(bp + ((size_t)i * kb32 + kt * 2 + 1) * 512);
;     {
;       bf16x8 af[8];
; #pragma unroll
;       for (int i = 0; i < 8; ++i) af[i] = *(const bf16x8*)(base + a_rd + i * 2048);
; #pragma unroll
;       for (int mi = 0; mi < 8; ++mi)
; #pragma unroll
;         for (int ni = 0; ni < 4; ++ni) acc[mi][ni] = MFMA16(b0[ni], af[mi], acc[mi][ni]);
;     }
;     if (more) {
; #pragma unroll
;       for (int i = 0; i < 4; ++i) b0[i] = *(const bf16x8*)(bp + ((size_t)i * kb32 + kt * 2 + 2) * 512);
;     }
;     {
;       bf16x8 af[8];
; #pragma unroll
;       for (int i = 0; i < 8; ++i) af[i] = *(const bf16x8*)(base + ((a_rd + i * 2048) ^ 64));
; #pragma unroll
;       for (int mi = 0; mi < 8; ++mi)
; #pragma unroll
;         for (int ni = 0; ni < 4; ++ni) acc[mi][ni] = MFMA16(b1[ni], af[mi], acc[mi][ni]);
;     }
;     if (more) {
;       char* nb = smem + ((kt + 1) & 1) * 32768 + lds_w;
; #pragma unroll
;       for (int i = 0; i < 8; ++i) *(u32x4*)(nb + i * 4096) = ra[i];
;     }
;     __syncthreads();
;   }
.LBB0_1873:
	s_add_i32 s10, s1, 0xffff8000
	s_and_b32 s10, s10, 0x8000
	s_add_i32 s10, s10, 32
	v_add_u32_e32 v0, s10, v173
	v_lshl_add_u64 v[154:155], v[164:165], 0, s[28:29]
	s_mov_b32 s11, 0x2a80000
	v_add_co_u32_e32 v156, vcc, s11, v154
	s_waitcnt vmcnt(3) lgkmcnt(1)
	v_mfma_f32_16x16x32_bf16 v[134:137], v[10:13], v[196:199], v[134:137]
	v_addc_co_u32_e32 v157, vcc, 0, v155, vcc
	s_mov_b32 s11, 0x2a88000
	s_waitcnt vmcnt(2)
	v_mfma_f32_16x16x32_bf16 v[130:133], v[14:17], v[196:199], v[130:133]
	v_add_co_u32_e32 v158, vcc, s11, v154
	s_mov_b32 s11, 0x2a90000
	s_waitcnt vmcnt(1)
	v_mfma_f32_16x16x32_bf16 v[126:129], v[6:9], v[196:199], v[126:129]
	v_addc_co_u32_e32 v159, vcc, 0, v155, vcc
	v_add_co_u32_e32 v160, vcc, s11, v154
	s_waitcnt vmcnt(0)
	v_mfma_f32_16x16x32_bf16 v[122:125], v[2:5], v[196:199], v[122:125]
	v_addc_co_u32_e32 v161, vcc, 0, v155, vcc
	s_mov_b32 s11, 0x2a98000
	s_waitcnt lgkmcnt(0)
	v_mfma_f32_16x16x32_bf16 v[114:117], v[10:13], v[200:203], v[114:117]
	v_add_co_u32_e32 v182, vcc, s11, v154
	v_mfma_f32_16x16x32_bf16 v[110:113], v[14:17], v[200:203], v[110:113]
	v_addc_co_u32_e32 v183, vcc, 0, v155, vcc
	v_mfma_f32_16x16x32_bf16 v[106:109], v[6:9], v[200:203], v[106:109]
	s_nop 0
	v_mfma_f32_16x16x32_bf16 v[102:105], v[2:5], v[200:203], v[102:105]
	ds_read_b128 v[146:149], v0 offset:4096
	ds_read_b128 v[150:153], v0 offset:6144
	s_waitcnt lgkmcnt(1)
	v_mfma_f32_16x16x32_bf16 v[98:101], v[10:13], v[146:149], v[98:101]
	v_lshl_add_u64 v[164:165], v[164:165], 0, s[64:65]
	v_mfma_f32_16x16x32_bf16 v[94:97], v[14:17], v[146:149], v[94:97]
	v_mfma_f32_16x16x32_bf16 v[86:89], v[6:9], v[146:149], v[86:89]
	s_nop 0
	v_mfma_f32_16x16x32_bf16 v[82:85], v[2:5], v[146:149], v[82:85]
	s_nop 0
	s_waitcnt lgkmcnt(0)
	v_mfma_f32_16x16x32_bf16 v[74:77], v[10:13], v[150:153], v[74:77]
	v_mfma_f32_16x16x32_bf16 v[70:73], v[14:17], v[150:153], v[70:73]
	s_nop 0
	v_lshl_add_u64 v[166:167], v[166:167], 0, s[60:61]
	v_mfma_f32_16x16x32_bf16 v[62:65], v[6:9], v[150:153], v[62:65]
	v_mfma_f32_16x16x32_bf16 v[66:69], v[2:5], v[150:153], v[66:69]
	ds_read_b128 v[146:149], v0 offset:8192
	ds_read_b128 v[150:153], v0 offset:10240
	s_waitcnt lgkmcnt(1)
	v_mfma_f32_16x16x32_bf16 v[46:49], v[10:13], v[146:149], v[46:49]
	v_mfma_f32_16x16x32_bf16 v[50:53], v[14:17], v[146:149], v[50:53]
	v_mfma_f32_16x16x32_bf16 v[58:61], v[6:9], v[146:149], v[58:61]
	v_mfma_f32_16x16x32_bf16 v[54:57], v[2:5], v[146:149], v[54:57]
	s_waitcnt lgkmcnt(0)
	v_mfma_f32_16x16x32_bf16 v[26:29], v[10:13], v[150:153], v[26:29]
	v_mfma_f32_16x16x32_bf16 v[22:25], v[14:17], v[150:153], v[22:25]
	v_mfma_f32_16x16x32_bf16 v[18:21], v[6:9], v[150:153], v[18:21]
	v_mfma_f32_16x16x32_bf16 v[42:45], v[2:5], v[150:153], v[42:45]
	ds_read_b128 v[146:149], v0 offset:12288
	ds_read_b128 v[150:153], v0 offset:14336
	v_add_u32_e32 v0, s10, v171
	s_and_b32 s10, s1, 0x8000
	s_waitcnt lgkmcnt(1)
	v_mfma_f32_16x16x32_bf16 v[34:37], v[10:13], v[146:149], v[34:37]
	s_add_i32 s1, s1, 0x8000
	s_cmp_eq_u32 s1, 0x80000
	v_mfma_f32_16x16x32_bf16 v[38:41], v[14:17], v[146:149], v[38:41]
	v_mfma_f32_16x16x32_bf16 v[30:33], v[6:9], v[146:149], v[30:33]
	v_mfma_f32_16x16x32_bf16 v[142:145], v[2:5], v[146:149], v[142:145]
	global_load_dwordx4 v[146:149], v[156:157], off offset:1024
	ds_read_b128 v[174:177], v0
	ds_read_b128 v[178:181], v0 offset:2048
	s_waitcnt lgkmcnt(2)
	v_mfma_f32_16x16x32_bf16 v[138:141], v[10:13], v[150:153], v[138:141]
	global_load_dwordx4 v[10:13], v[156:157], off offset:2048
	v_mfma_f32_16x16x32_bf16 v[118:121], v[14:17], v[150:153], v[118:121]
	v_mfma_f32_16x16x32_bf16 v[90:93], v[6:9], v[150:153], v[90:93]
	v_mfma_f32_16x16x32_bf16 v[78:81], v[2:5], v[150:153], v[78:81]
	global_load_dwordx4 v[150:153], v[158:159], off offset:1024
	global_load_dwordx4 v[14:17], v[158:159], off offset:2048
	global_load_dwordx4 v[154:157], v[160:161], off offset:1024
	global_load_dwordx4 v[6:9], v[160:161], off offset:2048
	s_nop 0
	global_load_dwordx4 v[158:161], v[182:183], off offset:1024
	global_load_dwordx4 v[2:5], v[182:183], off offset:2048
	v_lshrrev_b32_e32 v195, 6, v206
	v_lshl_add_u64 v[190:191], v[166:167], 0, s[28:29]
	v_lshrrev_b32_e32 v194, 3, v206
	v_readfirstlane_b32 s99, v195
	v_and_b32_e32 v194, 7, v194
	s_and_b32 s98, s1, 0x8000
	s_xor_b32 s98, s98, 0x8000
	v_lshlrev_b32_e32 v194, 4, v194
	s_lshl_b32 s99, s99, 10
	v_xor_b32_e32 v190, v194, v190
	s_add_u32 s98, s98, s99
	s_add_u32 s98, s98, 32
	s_mov_b32 s101, 0
	s_mov_b32 s100, 0x0
	v_lshl_add_u64 v[192:193], v[190:191], 0, s[100:101]
	s_mov_b32 m0, s98
	s_nop 0
	global_load_lds_dwordx4 v[192:193], off
	s_add_u32 s100, s54, 0x0
	v_lshl_add_u64 v[192:193], v[190:191], 0, s[100:101]
	s_add_u32 m0, s98, 0x1000
	s_nop 0
	global_load_lds_dwordx4 v[192:193], off
	s_add_u32 s100, s53, 0x0
	v_lshl_add_u64 v[192:193], v[190:191], 0, s[100:101]
	s_add_u32 m0, s98, 0x2000
	s_nop 0
	global_load_lds_dwordx4 v[192:193], off
	s_add_u32 s100, s52, 0x0
	v_lshl_add_u64 v[192:193], v[190:191], 0, s[100:101]
	s_add_u32 m0, s98, 0x3000
	s_nop 0
	global_load_lds_dwordx4 v[192:193], off
	s_add_u32 s100, s56, 0x0
	v_lshl_add_u64 v[192:193], v[190:191], 0, s[100:101]
	s_add_u32 m0, s98, 0x4000
	s_nop 0
	global_load_lds_dwordx4 v[192:193], off
	s_add_u32 s100, s57, 0x0
	v_lshl_add_u64 v[192:193], v[190:191], 0, s[100:101]
	s_add_u32 m0, s98, 0x5000
	s_nop 0
	global_load_lds_dwordx4 v[192:193], off
	s_add_u32 s100, s3, 0x0
	v_lshl_add_u64 v[192:193], v[190:191], 0, s[100:101]
	s_add_u32 m0, s98, 0x6000
	s_nop 0
	global_load_lds_dwordx4 v[192:193], off
	s_add_u32 s100, s19, 0x0
	v_lshl_add_u64 v[192:193], v[190:191], 0, s[100:101]
	s_add_u32 m0, s98, 0x7000
	s_nop 0
	global_load_lds_dwordx4 v[192:193], off
	s_waitcnt vmcnt(15) lgkmcnt(1)
; #define MFMA16(a, b, c) __builtin_amdgcn_mfma_f32_16x16x32_bf16((a), (b), (c), 0, 0, 0)
; template <class Epi>
; DEVI void gemm_tile256b(const bf16_t* __restrict__ A, int lda, const bf16_t* __restrict__ Bt, int K,
;                         int m0, int n0, char* smem, Epi epi) {
;     ...
;   for (int kt = 0; kt < nk; ++kt) {
;     const char* base = smem + (kt & 1) * 32768;
;     const bool more = kt + 1 < nk;
;     if (more) {
; #pragma unroll
;       for (int i = 0; i < 8; ++i) ra[i] = *(const u32x4*)(ag + (size_t)(i * 32) * lda + (kt + 1) * 64);
;     }
; #pragma unroll
;     for (int i = 0; i < 4; ++i) b1[i] = *(const bf16x8*)(bp + ((size_t)i * kb32 + kt * 2 + 1) * 512);
;     {
;       bf16x8 af[8];
; #pragma unroll
;       for (int i = 0; i < 8; ++i) af[i] = *(const bf16x8*)(base + a_rd + i * 2048);
; #pragma unroll
;       for (int mi = 0; mi < 8; ++mi)
; #pragma unroll
;         for (int ni = 0; ni < 4; ++ni) acc[mi][ni] = MFMA16(b0[ni], af[mi], acc[mi][ni]);
;     }
;     if (more) {
; #pragma unroll
;       for (int i = 0; i < 4; ++i) b0[i] = *(const bf16x8*)(bp + ((size_t)i * kb32 + kt * 2 + 2) * 512);
;     }
;     {
;       bf16x8 af[8];
; #pragma unroll
;       for (int i = 0; i < 8; ++i) af[i] = *(const bf16x8*)(base + ((a_rd + i * 2048) ^ 64));
; #pragma unroll
;       for (int mi = 0; mi < 8; ++mi)
; #pragma unroll
;         for (int ni = 0; ni < 4; ++ni) acc[mi][ni] = MFMA16(b1[ni], af[mi], acc[mi][ni]);
;     }
;     if (more) {
;       char* nb = smem + ((kt + 1) & 1) * 32768 + lds_w;
; #pragma unroll
;       for (int i = 0; i < 8; ++i) *(u32x4*)(nb + i * 4096) = ra[i];
;     }
;     __syncthreads();
;   }
	v_mfma_f32_16x16x32_bf16 v[134:137], v[146:149], v[174:177], v[134:137]
	s_waitcnt vmcnt(13)
	v_mfma_f32_16x16x32_bf16 v[130:133], v[150:153], v[174:177], v[130:133]
	s_waitcnt vmcnt(11)
	v_mfma_f32_16x16x32_bf16 v[126:129], v[154:157], v[174:177], v[126:129]
	s_waitcnt vmcnt(9)
	v_mfma_f32_16x16x32_bf16 v[122:125], v[158:161], v[174:177], v[122:125]
	s_waitcnt lgkmcnt(0)
	v_mfma_f32_16x16x32_bf16 v[114:117], v[146:149], v[178:181], v[114:117]
	v_mfma_f32_16x16x32_bf16 v[110:113], v[150:153], v[178:181], v[110:113]
	v_mfma_f32_16x16x32_bf16 v[106:109], v[154:157], v[178:181], v[106:109]
	v_mfma_f32_16x16x32_bf16 v[102:105], v[158:161], v[178:181], v[102:105]
	ds_read_b128 v[174:177], v0 offset:4096
	ds_read_b128 v[178:181], v0 offset:6144
	s_waitcnt lgkmcnt(1)
	v_mfma_f32_16x16x32_bf16 v[98:101], v[146:149], v[174:177], v[98:101]
	v_mfma_f32_16x16x32_bf16 v[94:97], v[150:153], v[174:177], v[94:97]
	v_mfma_f32_16x16x32_bf16 v[86:89], v[154:157], v[174:177], v[86:89]
	v_mfma_f32_16x16x32_bf16 v[82:85], v[158:161], v[174:177], v[82:85]
	s_waitcnt lgkmcnt(0)
	v_mfma_f32_16x16x32_bf16 v[74:77], v[146:149], v[178:181], v[74:77]
	v_mfma_f32_16x16x32_bf16 v[70:73], v[150:153], v[178:181], v[70:73]
	v_mfma_f32_16x16x32_bf16 v[62:65], v[154:157], v[178:181], v[62:65]
	v_mfma_f32_16x16x32_bf16 v[66:69], v[158:161], v[178:181], v[66:69]
	ds_read_b128 v[178:181], v0 offset:8192
	ds_read_b128 v[182:185], v0 offset:10240
	s_waitcnt lgkmcnt(1)
	v_mfma_f32_16x16x32_bf16 v[46:49], v[146:149], v[178:181], v[46:49]
	v_mfma_f32_16x16x32_bf16 v[50:53], v[150:153], v[178:181], v[50:53]
	v_mfma_f32_16x16x32_bf16 v[58:61], v[154:157], v[178:181], v[58:61]
	v_mfma_f32_16x16x32_bf16 v[54:57], v[158:161], v[178:181], v[54:57]
	s_waitcnt lgkmcnt(0)
	v_mfma_f32_16x16x32_bf16 v[26:29], v[146:149], v[182:185], v[26:29]
	v_mfma_f32_16x16x32_bf16 v[22:25], v[150:153], v[182:185], v[22:25]
	v_mfma_f32_16x16x32_bf16 v[18:21], v[154:157], v[182:185], v[18:21]
	v_mfma_f32_16x16x32_bf16 v[42:45], v[158:161], v[182:185], v[42:45]
	ds_read_b128 v[178:181], v0 offset:12288
	ds_read_b128 v[182:185], v0 offset:14336
	s_nop 0
	s_nop 0
	s_nop 0
	s_nop 0
	s_nop 0
	s_waitcnt lgkmcnt(1)
	v_mfma_f32_16x16x32_bf16 v[34:37], v[146:149], v[178:181], v[34:37]
	v_mfma_f32_16x16x32_bf16 v[38:41], v[150:153], v[178:181], v[38:41]
	v_mfma_f32_16x16x32_bf16 v[30:33], v[154:157], v[178:181], v[30:33]
	s_waitcnt vmcnt(0) lgkmcnt(0)
	s_barrier
	s_add_i32 s98, s1, 0xffff8000
	s_and_b32 s98, s98, 0x8000
	s_add_i32 s98, s98, 32
	v_add_u32_e32 v226, s98, v173
	ds_read_b128 v[196:199], v226
	ds_read_b128 v[200:203], v226 offset:2048
	v_mfma_f32_16x16x32_bf16 v[142:145], v[158:161], v[178:181], v[142:145]
	v_mfma_f32_16x16x32_bf16 v[138:141], v[146:149], v[182:185], v[138:141]
	v_mfma_f32_16x16x32_bf16 v[118:121], v[150:153], v[182:185], v[118:121]
	v_mfma_f32_16x16x32_bf16 v[90:93], v[154:157], v[182:185], v[90:93]
	v_mfma_f32_16x16x32_bf16 v[78:81], v[158:161], v[182:185], v[78:81]
	s_cmp_eq_u32 s1, 0x80000
	s_cbranch_scc0 .LBB0_1873
	v_and_b32_e32 v236, 16, v206
	v_lshrrev_b32_e32 v237, 1, v236
	v_add_u32_e32 v236, v236, v237
	v_mov_b32_e32 v237, 0
	v_add_u32_e32 v0, 32, v173
	ds_read_b128 v[146:149], v0 offset:32768
	s_movk_i32 s1, 0x7000
	s_waitcnt lgkmcnt(0)
	v_mfma_f32_16x16x32_bf16 v[134:137], v[10:13], v[146:149], v[134:137]
	v_mfma_f32_16x16x32_bf16 v[130:133], v[14:17], v[146:149], v[130:133]
	v_mfma_f32_16x16x32_bf16 v[150:153], v[6:9], v[146:149], v[126:129]
	v_mfma_f32_16x16x32_bf16 v[146:149], v[2:5], v[146:149], v[122:125]
	s_nop 2
	ds_read_b128 v[122:125], v0 offset:34816
	s_waitcnt lgkmcnt(0)
	v_mfma_f32_16x16x32_bf16 v[164:167], v[2:5], v[122:125], v[102:105]
	s_nop 2
	ds_read_b128 v[102:105], v0 offset:36864
	s_waitcnt lgkmcnt(0)
	v_mfma_f32_16x16x32_bf16 v[176:179], v[14:17], v[102:105], v[94:97]
	s_nop 2
	ds_read_b128 v[94:97], v0 offset:38912
	s_waitcnt lgkmcnt(0)
	v_mfma_f32_16x16x32_bf16 v[74:77], v[10:13], v[94:97], v[74:77]
	v_mfma_f32_16x16x32_bf16 v[70:73], v[14:17], v[94:97], v[70:73]
	v_mfma_f32_16x16x32_bf16 v[62:65], v[6:9], v[94:97], v[62:65]
	v_mfma_f32_16x16x32_bf16 v[66:69], v[2:5], v[94:97], v[66:69]
	ds_read_b128 v[94:97], v0 offset:40960
	s_waitcnt lgkmcnt(0)
	v_mfma_f32_16x16x32_bf16 v[190:193], v[2:5], v[94:97], v[54:57]
	s_nop 2
	ds_read_b128 v[54:57], v0 offset:43008
	s_waitcnt lgkmcnt(0)
	v_mfma_f32_16x16x32_bf16 v[194:197], v[2:5], v[54:57], v[42:45]
	s_nop 2
	ds_read_b128 v[42:45], v0 offset:45056
	s_waitcnt lgkmcnt(0)
	v_mfma_f32_16x16x32_bf16 v[226:229], v[6:9], v[42:45], v[30:33]
	s_nop 2
	ds_read_b128 v[30:33], v0 offset:47104
	v_add_u32_e32 v0, 32, v171
	v_mfma_f32_16x16x32_bf16 v[114:117], v[10:13], v[122:125], v[114:117]
	v_mfma_f32_16x16x32_bf16 v[154:157], v[14:17], v[122:125], v[110:113]
	v_mfma_f32_16x16x32_bf16 v[172:175], v[10:13], v[102:105], v[98:101]
	v_mfma_f32_16x16x32_bf16 v[46:49], v[10:13], v[94:97], v[46:49]
	v_mfma_f32_16x16x32_bf16 v[50:53], v[14:17], v[94:97], v[50:53]
	v_mfma_f32_16x16x32_bf16 v[26:29], v[10:13], v[54:57], v[26:29]
	v_mfma_f32_16x16x32_bf16 v[22:25], v[14:17], v[54:57], v[22:25]
	v_mfma_f32_16x16x32_bf16 v[198:201], v[10:13], v[42:45], v[34:37]
	v_mfma_f32_16x16x32_bf16 v[202:205], v[14:17], v[42:45], v[38:41]
	s_waitcnt lgkmcnt(0)
; #define MFMA16(a, b, c) __builtin_amdgcn_mfma_f32_16x16x32_bf16((a), (b), (c), 0, 0, 0)
; template <class Epi>
; DEVI void gemm_tile256b(const bf16_t* __restrict__ A, int lda, const bf16_t* __restrict__ Bt, int K,
;                         int m0, int n0, char* smem, Epi epi) {
;     ...
;     {
;       bf16x8 af[8];
; #pragma unroll
;       for (int i = 0; i < 8; ++i) af[i] = *(const bf16x8*)(base + ((a_rd + i * 2048) ^ 64));
; #pragma unroll
;       for (int mi = 0; mi < 8; ++mi)
; #pragma unroll
;         for (int ni = 0; ni < 4; ++ni) acc[mi][ni] = MFMA16(b1[ni], af[mi], acc[mi][ni]);
;     }
;     if (more) {
;       char* nb = smem + ((kt + 1) & 1) * 32768 + lds_w;
; #pragma unroll
;       for (int i = 0; i < 8; ++i) *(u32x4*)(nb + i * 4096) = ra[i];
;     }
;     __syncthreads();
;   }
; #pragma unroll
;   for (int mi = 0; mi < 8; ++mi)
; #pragma unroll
;     for (int ni = 0; ni < 4; ++ni)
;       epi(m0 + wm * 128 + mi * 16 + l15, n0 + wn * 64 + ni * 16 + quad * 4, acc[mi][ni]);
;   DEVI void operator()(int m, int n, f32x4 v) const {
;     if (m >= L) return;
;     float a = fmaxf(v[0], 0.f), b = fmaxf(v[1], 0.f), c = fmaxf(v[2], 0.f), d = fmaxf(v[3], 0.f);
;     *(u32x2*)(hid + (size_t)m * 4096 + n) = u32x2{pack2(a * a, b * b), pack2(c * c, d * d)};
;   }
	v_mfma_f32_16x16x32_bf16 v[10:13], v[10:13], v[30:33], v[138:141]
	v_mfma_f32_16x16x32_bf16 v[138:141], v[14:17], v[30:33], v[118:121]
	v_add_co_u32_e32 v14, vcc, s1, v162
	s_mov_b32 s1, 0xf000
	s_nop 0
	v_addc_co_u32_e32 v15, vcc, 0, v163, vcc
	global_load_dwordx4 v[14:17], v[14:15], off offset:3072
	v_mfma_f32_16x16x32_bf16 v[158:161], v[6:9], v[122:125], v[106:109]
	v_add_co_u32_e32 v34, vcc, s1, v162
	s_mov_b32 s1, 0x17000
	v_mfma_f32_16x16x32_bf16 v[86:89], v[6:9], v[102:105], v[86:89]
	v_addc_co_u32_e32 v35, vcc, 0, v163, vcc
	global_load_dwordx4 v[230:233], v[34:35], off offset:3072
	v_mfma_f32_16x16x32_bf16 v[82:85], v[2:5], v[102:105], v[82:85]
	v_add_co_u32_e32 v34, vcc, s1, v162
	s_mov_b32 s1, 0x1f000
	v_mfma_f32_16x16x32_bf16 v[180:183], v[6:9], v[94:97], v[58:61]
	v_addc_co_u32_e32 v35, vcc, 0, v163, vcc
	v_mfma_f32_16x16x32_bf16 v[18:21], v[6:9], v[54:57], v[18:21]
	v_mfma_f32_16x16x32_bf16 v[142:145], v[2:5], v[42:45], v[142:145]
	v_mfma_f32_16x16x32_bf16 v[6:9], v[6:9], v[30:33], v[90:93]
	v_mfma_f32_16x16x32_bf16 v[2:5], v[2:5], v[30:33], v[78:81]
	ds_read_b128 v[30:33], v0 offset:32768
	s_waitcnt vmcnt(1) lgkmcnt(0)
	v_mfma_f32_16x16x32_bf16 v[126:129], v[14:17], v[30:33], v[134:137]
	s_nop 2
	global_load_dwordx4 v[134:137], v[34:35], off offset:3072
	v_add_co_u32_e32 v34, vcc, s1, v162
	s_waitcnt vmcnt(1)
	v_mfma_f32_16x16x32_bf16 v[122:125], v[230:233], v[30:33], v[130:133]
	v_addc_co_u32_e32 v35, vcc, 0, v163, vcc
	s_nop 1
	v_lshl_or_b32 v130, v169, 2, v170
	s_waitcnt vmcnt(0)
	v_mfma_f32_16x16x32_bf16 v[118:121], v[134:137], v[30:33], v[150:153]
	s_nop 2
	global_load_dwordx4 v[150:153], v[34:35], off offset:3072
	v_ashrrev_i32_e32 v131, 31, v130
	s_waitcnt vmcnt(0)
	v_mfma_f32_16x16x32_bf16 v[110:113], v[150:153], v[30:33], v[146:149]
	ds_read_b128 v[30:33], v0 offset:34816
	s_waitcnt lgkmcnt(0)
	v_mfma_f32_16x16x32_bf16 v[114:117], v[14:17], v[30:33], v[114:117]
	v_mfma_f32_16x16x32_bf16 v[106:109], v[230:233], v[30:33], v[154:157]
	v_mfma_f32_16x16x32_bf16 v[102:105], v[134:137], v[30:33], v[158:161]
	v_mfma_f32_16x16x32_bf16 v[98:101], v[150:153], v[30:33], v[164:167]
	ds_read_b128 v[30:33], v0 offset:36864
	s_waitcnt lgkmcnt(0)
	v_mfma_f32_16x16x32_bf16 v[94:97], v[14:17], v[30:33], v[172:175]
	v_mfma_f32_16x16x32_bf16 v[90:93], v[230:233], v[30:33], v[176:179]
	v_mfma_f32_16x16x32_bf16 v[86:89], v[134:137], v[30:33], v[86:89]
	v_mfma_f32_16x16x32_bf16 v[82:85], v[150:153], v[30:33], v[82:85]
	ds_read_b128 v[30:33], v0 offset:38912
	s_waitcnt lgkmcnt(0)
	v_mfma_f32_16x16x32_bf16 v[78:81], v[14:17], v[30:33], v[74:77]
	v_mfma_f32_16x16x32_bf16 v[74:77], v[230:233], v[30:33], v[70:73]
	v_mfma_f32_16x16x32_bf16 v[70:73], v[134:137], v[30:33], v[62:65]
	v_mfma_f32_16x16x32_bf16 v[66:69], v[150:153], v[30:33], v[66:69]
	ds_read_b128 v[30:33], v0 offset:40960
	s_waitcnt lgkmcnt(0)
	v_mfma_f32_16x16x32_bf16 v[62:65], v[14:17], v[30:33], v[46:49]
	v_mfma_f32_16x16x32_bf16 v[58:61], v[230:233], v[30:33], v[50:53]
	v_mfma_f32_16x16x32_bf16 v[54:57], v[134:137], v[30:33], v[180:183]
	v_mfma_f32_16x16x32_bf16 v[50:53], v[150:153], v[30:33], v[190:193]
	ds_read_b128 v[30:33], v0 offset:43008
	s_waitcnt lgkmcnt(0)
	v_mfma_f32_16x16x32_bf16 v[38:41], v[134:137], v[30:33], v[18:21]
	s_nop 2
	ds_read_b128 v[18:21], v0 offset:45056
	v_mfma_f32_16x16x32_bf16 v[46:49], v[14:17], v[30:33], v[26:29]
	v_mfma_f32_16x16x32_bf16 v[42:45], v[230:233], v[30:33], v[22:25]
	v_mfma_f32_16x16x32_bf16 v[34:37], v[150:153], v[30:33], v[194:197]
	s_waitcnt lgkmcnt(0)
	v_mfma_f32_16x16x32_bf16 v[30:33], v[14:17], v[18:21], v[198:201]
	v_mfma_f32_16x16x32_bf16 v[26:29], v[230:233], v[18:21], v[202:205]
	v_mfma_f32_16x16x32_bf16 v[22:25], v[134:137], v[18:21], v[226:229]
	v_mfma_f32_16x16x32_bf16 v[18:21], v[150:153], v[18:21], v[142:145]
	s_nop 2
	ds_read_b128 v[142:145], v0 offset:47104
	s_waitcnt lgkmcnt(0)
	v_mfma_f32_16x16x32_bf16 v[14:17], v[14:17], v[142:145], v[10:13]
	v_and_b32_e32 v0, 0xffffff80, v168
	v_add_u32_e32 v0, s0, v0
	v_and_or_b32 v132, v168, 15, v0
	v_mfma_f32_16x16x32_bf16 v[10:13], v[230:233], v[142:145], v[138:141]
	s_movk_i32 s0, 0x4010
	v_cmp_gt_i32_e32 vcc, s0, v132
	v_mfma_f32_16x16x32_bf16 v[6:9], v[134:137], v[142:145], v[6:9]
	s_barrier
	v_mfma_f32_16x16x32_bf16 v[2:5], v[150:153], v[142:145], v[2:5]
	s_and_saveexec_b64 s[0:1], vcc
	s_cbranch_execz .LBB0_1876
	v_max_f32_e32 v0, v126, v126
	v_max_f32_e32 v126, 0, v0
	v_max_f32_e32 v0, v127, v127
	v_max_f32_e32 v127, 0, v0
	v_max_f32_e32 v0, v128, v128
	v_max_f32_e32 v128, 0, v0
	v_max_f32_e32 v0, v129, v129
	v_max_f32_e32 v129, 0, v0
	v_max_f32_e32 v0, v122, v122
	v_max_f32_e32 v122, 0, v0
	v_max_f32_e32 v0, v123, v123
	v_max_f32_e32 v123, 0, v0
	v_max_f32_e32 v0, v124, v124
	v_max_f32_e32 v124, 0, v0
	v_max_f32_e32 v0, v125, v125
	v_max_f32_e32 v125, 0, v0
	v_max_f32_e32 v0, v118, v118
	v_max_f32_e32 v118, 0, v0
	v_max_f32_e32 v0, v119, v119
	v_max_f32_e32 v119, 0, v0
	v_max_f32_e32 v0, v120, v120
	v_max_f32_e32 v120, 0, v0
	v_max_f32_e32 v0, v121, v121
	v_max_f32_e32 v121, 0, v0
	v_max_f32_e32 v0, v110, v110
	v_max_f32_e32 v110, 0, v0
	v_max_f32_e32 v0, v111, v111
	v_max_f32_e32 v111, 0, v0
	v_max_f32_e32 v0, v112, v112
	v_ashrrev_i32_e32 v133, 31, v132
	v_max_f32_e32 v112, 0, v0
	v_max_f32_e32 v0, v113, v113
	v_lshlrev_b64 v[134:135], 13, v[132:133]
	v_max_f32_e32 v113, 0, v0
	v_lshl_add_u64 v[134:135], s[30:31], 0, v[134:135]
	v_pk_mul_f32 v[126:127], v[126:127], v[126:127]
	v_pk_mul_f32 v[128:129], v[128:129], v[128:129]
	v_pk_mul_f32 v[122:123], v[122:123], v[122:123]
	v_pk_mul_f32 v[124:125], v[124:125], v[124:125]
	v_pk_mul_f32 v[118:119], v[118:119], v[118:119]
	v_pk_mul_f32 v[120:121], v[120:121], v[120:121]
	v_pk_mul_f32 v[110:111], v[110:111], v[110:111]
	v_pk_mul_f32 v[112:113], v[112:113], v[112:113]
	v_cvt_pk_bf16_f32 v126, v126, v127
	v_cvt_pk_bf16_f32 v127, v128, v129
	v_lshl_add_u64 v[234:235], v[130:131], 1, v[134:135]
	v_lshl_add_u64 v[234:235], v[234:235], 0, v[236:237]
	v_cvt_pk_bf16_f32 v128, v122, v123
	v_cvt_pk_bf16_f32 v129, v124, v125
	v_cvt_pk_bf16_f32 v118, v118, v119
	v_cvt_pk_bf16_f32 v119, v120, v121
	v_cvt_pk_bf16_f32 v120, v110, v111
	v_cvt_pk_bf16_f32 v121, v112, v113
	s_nop 1
	v_permlane16_swap_b32_e32 v126, v128
	v_permlane16_swap_b32_e32 v127, v129
	v_permlane16_swap_b32_e32 v118, v120
	v_permlane16_swap_b32_e32 v119, v121
	global_store_dwordx4 v[234:235], v[126:129], off
	global_store_dwordx4 v[234:235], v[118:121], off offset:64
	s_nop 1
